# static s_setprio 1 for wave half 1 across each GEMM K-loop instead of a raise around every MFMA block
# speedup vs baseline: 1.0027x; 1.0027x over previous
;     __host__ __device__ bool next(int i, Unit& u) const { const long L = (long)i * G + c; if (L >= nwg) return false; return unit_of((int)L, u); }
;     __host__ __device__ bool next(int i, Unit& u) const { const int L = i == 0 ? l0 : (i == 1 ? l1 : (i == 2 ? l2 : -1)); if (L < 0 || L >= s.nwg) return false; return s.unit_of(L, u); }
;     __host__ __device__ bool next(int i, Unit& u) const { const bool ok = s.next(i >> 1, u); u.kh = i & 1; return ok; }
; #define PG8_STAGE(bufoff, gbase, voff) do { _Pragma("unroll") for (int _i = 0; _i < 2; ++_i) \
;         __builtin_amdgcn_global_load_lds((const unsigned*)((const char*)(gbase) + (voff)[_i]), (PG8_LAS unsigned*)(lds + (bufoff) + ldsw + _i * 8192), 16, 0, 0); } while (0)
; #define PG8_WAIT_V(n) asm volatile("s_waitcnt vmcnt(" #n ")" ::: "memory")
; #define PG8_BAR __builtin_amdgcn_s_barrier()
; template <class Epi, class Sched, bool ALIGN_EPI = false, bool SP2 = false>
; __device__ __forceinline__ void gemm_phase(PG8_LAS unsigned char* lds, const Gemm g, const Sched& S, const Epi& E) {
;     ...
;         const bool has_next = S.next(ui + 1, nxt);
;         const char* nA = has_next ? (const char*)g.A + (size_t)nxt.pm * tstep + nxt.kh * khb : cA; const char* nB = has_next ? (const char*)g.Bt + (size_t)nxt.pn * tstep + nxt.kh * khb : cB;
;         for (int t = 0; t < nt; t += 2) {
;             const bool last = (t == nt - 2);
;             const char* a1 = cA + (size_t)(t + 1) * kstep;
;             const char* a2 = last ? nA : cA + (size_t)(t + 2) * kstep; const char* b2 = last ? nB : cB + (size_t)(t + 2) * kstep;
;             const char* a3 = a2 + kstep; const char* b3 = b2 + kstep;
;             if (last && has_next) S.a_ready(nxt);
;             if constexpr (SP2) {
;             PG8_LDB(B0, 0, 0); PG8_LDB(B1, 0, 1); PG8_SCHED; PG8_LDA(At, 0, 0); PG8_STAGE(PG8_SA(1, 1), a1 + hstep, voffA);
;             PG8_WAIT_V(8); PG8_WAIT_L(0); PG8_BAR; PG8_MMA(0, 0, At, B0); PG8_MMA(0, 1, At, B1); PG8_BAR; PG8_SCHED;
;     ...
;         if (!(Epi::KSPLIT && cur.kh == 0))
; #pragma unroll
;         for (int a = 0; a < 2; ++a)
; #pragma unroll
;             for (int b = 0; b < 2; ++b)
; #pragma unroll
;                 for (int m = 0; m < 4; ++m)
; #pragma unroll
;                     for (int n = 0; n < 2; ++n) acc[a][b][m][n] = (f32x4){0.f, 0.f, 0.f, 0.f};
;         cur = nxt; cA = nA; cB = nB; ++ui;
.LBB0_95:
	s_waitcnt lgkmcnt(0)
	s_ashr_i32 s55, s54, 31
	s_lshl_b64 s[34:35], s[54:55], 19
	s_add_u32 s76, s50, s34
	s_addc_u32 s77, s51, s35
	s_and_b64 s[34:35], s[2:3], exec
	s_cselect_b32 s8, s77, s81
	s_cselect_b32 s55, s76, s80
	s_ashr_i32 s49, s48, 31
	s_lshl_b64 s[34:35], s[48:49], 19
	s_add_u32 s78, s88, s34
	s_addc_u32 s79, s89, s35
	s_and_b64 s[34:35], s[2:3], exec
	s_cselect_b32 s49, s79, s83
	s_cselect_b32 vcc_lo, s78, s82
	s_add_u32 s80, s80, 0x40080
	s_addc_u32 s81, s81, 0
	s_add_u32 vcc_hi, s82, 0x100
	v_mov_b32_e32 v0, 0
	s_addc_u32 s34, s83, 0
	s_mov_b32 s35, -2
	v_mov_b32_e32 v1, v0
	v_mov_b32_e32 v2, v0
	v_mov_b32_e32 v3, v0
	v_mov_b32_e32 v4, v0
	v_mov_b32_e32 v5, v0
	v_mov_b32_e32 v6, v0
	v_mov_b32_e32 v7, v0
	v_mov_b32_e32 v16, v0
	v_mov_b32_e32 v17, v0
	v_mov_b32_e32 v18, v0
	v_mov_b32_e32 v19, v0
	v_mov_b32_e32 v20, v0
	v_mov_b32_e32 v21, v0
	v_mov_b32_e32 v22, v0
	v_mov_b32_e32 v23, v0
	v_mov_b32_e32 v32, v0
	v_mov_b32_e32 v33, v0
	v_mov_b32_e32 v34, v0
	v_mov_b32_e32 v35, v0
	v_mov_b32_e32 v36, v0
	v_mov_b32_e32 v37, v0
	v_mov_b32_e32 v38, v0
	v_mov_b32_e32 v39, v0
	v_mov_b32_e32 v48, v0
	v_mov_b32_e32 v49, v0
	v_mov_b32_e32 v50, v0
	v_mov_b32_e32 v51, v0
	v_mov_b32_e32 v52, v0
	v_mov_b32_e32 v53, v0
	v_mov_b32_e32 v54, v0
	v_mov_b32_e32 v55, v0
	v_mov_b32_e32 v8, v0
	v_mov_b32_e32 v9, v0
	v_mov_b32_e32 v10, v0
	v_mov_b32_e32 v11, v0
	v_mov_b32_e32 v12, v0
	v_mov_b32_e32 v13, v0
	v_mov_b32_e32 v14, v0
	v_mov_b32_e32 v15, v0
	v_mov_b32_e32 v24, v0
	v_mov_b32_e32 v25, v0
	v_mov_b32_e32 v26, v0
	v_mov_b32_e32 v27, v0
	v_mov_b32_e32 v28, v0
	v_mov_b32_e32 v29, v0
	v_mov_b32_e32 v30, v0
	v_mov_b32_e32 v31, v0
	v_mov_b32_e32 v40, v0
	v_mov_b32_e32 v41, v0
	v_mov_b32_e32 v42, v0
	v_mov_b32_e32 v43, v0
	v_mov_b32_e32 v44, v0
	v_mov_b32_e32 v45, v0
	v_mov_b32_e32 v46, v0
	v_mov_b32_e32 v47, v0
	v_mov_b32_e32 v56, v0
	v_mov_b32_e32 v57, v0
	v_mov_b32_e32 v58, v0
	v_mov_b32_e32 v59, v0
	v_mov_b32_e32 v60, v0
	v_mov_b32_e32 v61, v0
	v_mov_b32_e32 v62, v0
	v_mov_b32_e32 v63, v0
	v_mov_b32_e32 v64, v0
	v_mov_b32_e32 v65, v0
	v_mov_b32_e32 v66, v0
	v_mov_b32_e32 v67, v0
	v_mov_b32_e32 v68, v0
	v_mov_b32_e32 v69, v0
	v_mov_b32_e32 v70, v0
	v_mov_b32_e32 v71, v0
	v_mov_b32_e32 v80, v0
	v_mov_b32_e32 v81, v0
	v_mov_b32_e32 v82, v0
	v_mov_b32_e32 v83, v0
	v_mov_b32_e32 v84, v0
	v_mov_b32_e32 v85, v0
	v_mov_b32_e32 v86, v0
	v_mov_b32_e32 v87, v0
	v_mov_b32_e32 v96, v0
	v_mov_b32_e32 v97, v0
	v_mov_b32_e32 v98, v0
	v_mov_b32_e32 v99, v0
	v_mov_b32_e32 v100, v0
	v_mov_b32_e32 v101, v0
	v_mov_b32_e32 v102, v0
	v_mov_b32_e32 v103, v0
	v_mov_b32_e32 v112, v0
	v_mov_b32_e32 v113, v0
	v_mov_b32_e32 v114, v0
	v_mov_b32_e32 v115, v0
	v_mov_b32_e32 v116, v0
	v_mov_b32_e32 v117, v0
	v_mov_b32_e32 v118, v0
	v_mov_b32_e32 v119, v0
	v_mov_b32_e32 v72, v0
	v_mov_b32_e32 v73, v0
	v_mov_b32_e32 v74, v0
	v_mov_b32_e32 v75, v0
	v_mov_b32_e32 v76, v0
	v_mov_b32_e32 v77, v0
	v_mov_b32_e32 v78, v0
	v_mov_b32_e32 v79, v0
	v_mov_b32_e32 v88, v0
	v_mov_b32_e32 v89, v0
	v_mov_b32_e32 v90, v0
	v_mov_b32_e32 v91, v0
	v_mov_b32_e32 v92, v0
	v_mov_b32_e32 v93, v0
	v_mov_b32_e32 v94, v0
	v_mov_b32_e32 v95, v0
	v_mov_b32_e32 v104, v0
	v_mov_b32_e32 v105, v0
	v_mov_b32_e32 v106, v0
	v_mov_b32_e32 v107, v0
	v_mov_b32_e32 v108, v0
	v_mov_b32_e32 v109, v0
	v_mov_b32_e32 v110, v0
	v_mov_b32_e32 v111, v0
	v_mov_b32_e32 v120, v0
	v_mov_b32_e32 v121, v0
	v_mov_b32_e32 v122, v0
	v_mov_b32_e32 v123, v0
	v_mov_b32_e32 v124, v0
	v_mov_b32_e32 v125, v0
	v_mov_b32_e32 v126, v0
	v_mov_b32_e32 v127, v0
	v_readfirstlane_b32 s100, v188
	s_bitcmp1_b32 s100, 8
	s_cbranch_scc0 .Lmy_sprio_96
	s_setprio 1
.Lmy_sprio_96:
.LBB0_96:
	ds_read_b128 v[128:131], v178
	ds_read_b128 v[132:135], v178 offset:1024
	ds_read_b128 v[136:139], v178 offset:2048
	ds_read_b128 v[140:143], v178 offset:3072
	ds_read_b128 v[166:169], v179
	ds_read_b128 v[170:173], v179 offset:1024
	ds_read_b128 v[190:193], v179 offset:2048
	ds_read_b128 v[194:197], v179 offset:3072
	s_add_u32 s36, s80, 0xfffc0080
	s_addc_u32 s37, s81, -1
	s_cmp_eq_u32 s35, 12
	s_cselect_b32 s87, s8, s37
	s_cselect_b32 s86, s55, s36
	s_cselect_b32 s83, s49, s34
	s_cselect_b32 s82, vcc_lo, vcc_hi
	s_add_i32 m0, s93, 0xc000
	ds_read_b128 v[198:201], v181
	ds_read_b128 v[202:205], v181 offset:1024
	ds_read_b128 v[206:209], v181 offset:2048
	ds_read_b128 v[210:213], v181 offset:3072
	ds_read_b128 v[214:217], v181 offset:4096
	ds_read_b128 v[218:221], v181 offset:5120
	ds_read_b128 v[222:225], v181 offset:6144
	ds_read_b128 v[226:229], v181 offset:7168
	global_load_lds_dwordx4 v158, s[80:81]
	s_add_i32 m0, s93, 0xe000
	s_nop 0
	global_load_lds_dwordx4 v160, s[80:81]
	s_waitcnt vmcnt(8)
	s_waitcnt lgkmcnt(0)
	s_barrier
; #define PG8_STAGE(bufoff, gbase, voff) do { _Pragma("unroll") for (int _i = 0; _i < 2; ++_i) \
;         __builtin_amdgcn_global_load_lds((const unsigned*)((const char*)(gbase) + (voff)[_i]), (PG8_LAS unsigned*)(lds + (bufoff) + ldsw + _i * 8192), 16, 0, 0); } while (0)
; #define PG8_LDA(dst, b, h) do { _Pragma("unroll") for (int m = 0; m < 4; ++m) _Pragma("unroll") for (int k = 0; k < 2; ++k) dst[m][k] = *(const PG8_LAS bf16x8*)(lds + PG8_SA(b, h) + aoff + m * 2048 + k * 1024); } while (0)
; #define PG8_MMA(ai, bj, At, Bt) do { __builtin_amdgcn_s_setprio(1); _Pragma("unroll") for (int m = 0; m < 4; ++m) _Pragma("unroll") for (int n = 0; n < 2; ++n) _Pragma("unroll") for (int k = 0; k < 2; ++k) \
;         acc[ai][bj][m][n] = __builtin_amdgcn_mfma_f32_16x16x32_bf16(Bt[n][k], At[m][k], acc[ai][bj][m][n], 0, 0, 0); __builtin_amdgcn_s_setprio(0); } while (0)
; #define PG8_WAIT_V(n) asm volatile("s_waitcnt vmcnt(" #n ")" ::: "memory")
; #define PG8_WAIT_L(n) asm volatile("s_waitcnt lgkmcnt(" #n ")" ::: "memory")
; #define PG8_BAR __builtin_amdgcn_s_barrier()
; #define PG8_SCHED __builtin_amdgcn_sched_barrier(0)
; template <class Epi, class Sched, bool ALIGN_EPI = false, bool SP2 = false>
; __device__ __forceinline__ void gemm_phase(PG8_LAS unsigned char* lds, const Gemm g, const Sched& S, const Epi& E) {
;     ...
;             PG8_WAIT_V(8); PG8_WAIT_L(0); PG8_BAR; PG8_MMA(0, 0, At, B0); PG8_MMA(0, 1, At, B1); PG8_BAR; PG8_SCHED;
;             PG8_LDA(At, 0, 1); PG8_STAGE(PG8_SB(0, 0), b2, voffB); PG8_STAGE(PG8_SB(0, 1), b2 + hstep, voffB); PG8_STAGE(PG8_SA(0, 0), a2, voffA);
;             PG8_WAIT_V(8); PG8_WAIT_L(0); PG8_BAR; PG8_MMA(1, 0, At, B0); PG8_MMA(1, 1, At, B1); PG8_BAR; PG8_SCHED;
	v_mfma_f32_16x16x32_bf16 v[124:127], v[128:131], v[198:201], v[124:127]
	v_mfma_f32_16x16x32_bf16 v[120:123], v[136:139], v[198:201], v[120:123]
	v_mfma_f32_16x16x32_bf16 v[108:111], v[128:131], v[206:209], v[108:111]
	v_mfma_f32_16x16x32_bf16 v[104:107], v[136:139], v[206:209], v[104:107]
	v_mfma_f32_16x16x32_bf16 v[92:95], v[128:131], v[214:217], v[92:95]
	v_mfma_f32_16x16x32_bf16 v[88:91], v[136:139], v[214:217], v[88:91]
	v_mfma_f32_16x16x32_bf16 v[76:79], v[128:131], v[222:225], v[76:79]
	v_mfma_f32_16x16x32_bf16 v[72:75], v[136:139], v[222:225], v[72:75]
	v_mfma_f32_16x16x32_bf16 v[124:127], v[132:135], v[202:205], v[124:127]
	v_mfma_f32_16x16x32_bf16 v[120:123], v[140:143], v[202:205], v[120:123]
	v_mfma_f32_16x16x32_bf16 v[108:111], v[132:135], v[210:213], v[108:111]
	v_mfma_f32_16x16x32_bf16 v[104:107], v[140:143], v[210:213], v[104:107]
	v_mfma_f32_16x16x32_bf16 v[92:95], v[132:135], v[218:221], v[92:95]
	v_mfma_f32_16x16x32_bf16 v[88:91], v[140:143], v[218:221], v[88:91]
	v_mfma_f32_16x16x32_bf16 v[76:79], v[132:135], v[226:229], v[76:79]
	v_mfma_f32_16x16x32_bf16 v[72:75], v[140:143], v[226:229], v[72:75]
	v_mfma_f32_16x16x32_bf16 v[116:119], v[166:169], v[198:201], v[116:119]
	v_mfma_f32_16x16x32_bf16 v[112:115], v[190:193], v[198:201], v[112:115]
	v_mfma_f32_16x16x32_bf16 v[100:103], v[166:169], v[206:209], v[100:103]
	v_mfma_f32_16x16x32_bf16 v[96:99], v[190:193], v[206:209], v[96:99]
	v_mfma_f32_16x16x32_bf16 v[84:87], v[166:169], v[214:217], v[84:87]
	v_mfma_f32_16x16x32_bf16 v[80:83], v[190:193], v[214:217], v[80:83]
	v_mfma_f32_16x16x32_bf16 v[68:71], v[166:169], v[222:225], v[68:71]
	v_mfma_f32_16x16x32_bf16 v[64:67], v[190:193], v[222:225], v[64:67]
	v_mfma_f32_16x16x32_bf16 v[116:119], v[170:173], v[202:205], v[116:119]
	v_mfma_f32_16x16x32_bf16 v[112:115], v[194:197], v[202:205], v[112:115]
	v_mfma_f32_16x16x32_bf16 v[100:103], v[170:173], v[210:213], v[100:103]
	v_mfma_f32_16x16x32_bf16 v[96:99], v[194:197], v[210:213], v[96:99]
	v_mfma_f32_16x16x32_bf16 v[84:87], v[170:173], v[218:221], v[84:87]
	v_mfma_f32_16x16x32_bf16 v[80:83], v[194:197], v[218:221], v[80:83]
	v_mfma_f32_16x16x32_bf16 v[68:71], v[170:173], v[226:229], v[68:71]
	v_mfma_f32_16x16x32_bf16 v[64:67], v[194:197], v[226:229], v[64:67]
	s_barrier
	s_add_i32 s36, s23, s90
	v_lshl_add_u64 v[174:175], s[82:83], 0, v[148:149]
	s_mov_b32 m0, s36
	ds_read_b128 v[198:201], v181 offset:16384
	ds_read_b128 v[202:205], v181 offset:17408
	ds_read_b128 v[206:209], v181 offset:18432
	ds_read_b128 v[210:213], v181 offset:19456
	ds_read_b128 v[214:217], v181 offset:20480
	ds_read_b128 v[218:221], v181 offset:21504
	ds_read_b128 v[222:225], v181 offset:22528
	ds_read_b128 v[226:229], v181 offset:23552
	global_load_lds_dwordx4 v[174:175], off
	s_add_i32 m0, s36, 0x2000
	s_add_u32 s36, s82, 0x40000
	v_lshl_add_u64 v[186:187], s[82:83], 0, v[144:145]
	s_addc_u32 s37, s83, 0
	s_add_i32 s20, s41, s90
	global_load_lds_dwordx4 v[186:187], off
	s_mov_b32 m0, s20
	v_lshl_add_u64 v[232:233], s[86:87], 0, v[146:147]
	global_load_lds_dwordx4 v148, s[36:37]
	s_add_i32 m0, s20, 0x2000
	s_nop 0
	global_load_lds_dwordx4 v144, s[36:37]
	v_lshl_add_u64 v[230:231], s[86:87], 0, v[150:151]
	s_mov_b32 m0, s93
	s_nop 0
	global_load_lds_dwordx4 v[230:231], off
	s_mov_b32 m0, s94
	s_nop 0
	global_load_lds_dwordx4 v[232:233], off
	s_waitcnt vmcnt(8)
	s_waitcnt lgkmcnt(0)
	s_barrier
	v_mfma_f32_16x16x32_bf16 v[60:63], v[128:131], v[198:201], v[60:63]
	v_mfma_f32_16x16x32_bf16 v[56:59], v[136:139], v[198:201], v[56:59]
	v_mfma_f32_16x16x32_bf16 v[44:47], v[128:131], v[206:209], v[44:47]
	v_mfma_f32_16x16x32_bf16 v[40:43], v[136:139], v[206:209], v[40:43]
	v_mfma_f32_16x16x32_bf16 v[28:31], v[128:131], v[214:217], v[28:31]
	v_mfma_f32_16x16x32_bf16 v[24:27], v[136:139], v[214:217], v[24:27]
	v_mfma_f32_16x16x32_bf16 v[12:15], v[128:131], v[222:225], v[12:15]
	v_mfma_f32_16x16x32_bf16 v[8:11], v[136:139], v[222:225], v[8:11]
	v_mfma_f32_16x16x32_bf16 v[60:63], v[132:135], v[202:205], v[60:63]
	v_mfma_f32_16x16x32_bf16 v[56:59], v[140:143], v[202:205], v[56:59]
	v_mfma_f32_16x16x32_bf16 v[44:47], v[132:135], v[210:213], v[44:47]
	v_mfma_f32_16x16x32_bf16 v[40:43], v[140:143], v[210:213], v[40:43]
	v_mfma_f32_16x16x32_bf16 v[28:31], v[132:135], v[218:221], v[28:31]
	v_mfma_f32_16x16x32_bf16 v[24:27], v[140:143], v[218:221], v[24:27]
	v_mfma_f32_16x16x32_bf16 v[12:15], v[132:135], v[226:229], v[12:15]
	v_mfma_f32_16x16x32_bf16 v[8:11], v[140:143], v[226:229], v[8:11]
	v_mfma_f32_16x16x32_bf16 v[52:55], v[166:169], v[198:201], v[52:55]
	v_mfma_f32_16x16x32_bf16 v[48:51], v[190:193], v[198:201], v[48:51]
	v_mfma_f32_16x16x32_bf16 v[36:39], v[166:169], v[206:209], v[36:39]
	v_mfma_f32_16x16x32_bf16 v[32:35], v[190:193], v[206:209], v[32:35]
	v_mfma_f32_16x16x32_bf16 v[20:23], v[166:169], v[214:217], v[20:23]
	v_mfma_f32_16x16x32_bf16 v[16:19], v[190:193], v[214:217], v[16:19]
	v_mfma_f32_16x16x32_bf16 v[4:7], v[166:169], v[222:225], v[4:7]
	v_mfma_f32_16x16x32_bf16 v[0:3], v[190:193], v[222:225], v[0:3]
	v_mfma_f32_16x16x32_bf16 v[52:55], v[170:173], v[202:205], v[52:55]
	v_mfma_f32_16x16x32_bf16 v[48:51], v[194:197], v[202:205], v[48:51]
	v_mfma_f32_16x16x32_bf16 v[36:39], v[170:173], v[210:213], v[36:39]
	v_mfma_f32_16x16x32_bf16 v[32:35], v[194:197], v[210:213], v[32:35]
	v_mfma_f32_16x16x32_bf16 v[20:23], v[170:173], v[218:221], v[20:23]
	v_mfma_f32_16x16x32_bf16 v[16:19], v[194:197], v[218:221], v[16:19]
	v_mfma_f32_16x16x32_bf16 v[4:7], v[170:173], v[226:229], v[4:7]
	v_mfma_f32_16x16x32_bf16 v[0:3], v[194:197], v[226:229], v[0:3]
	s_barrier
; #define PG8_STAGE(bufoff, gbase, voff) do { _Pragma("unroll") for (int _i = 0; _i < 2; ++_i) \
;         __builtin_amdgcn_global_load_lds((const unsigned*)((const char*)(gbase) + (voff)[_i]), (PG8_LAS unsigned*)(lds + (bufoff) + ldsw + _i * 8192), 16, 0, 0); } while (0)
; #define PG8_LDA(dst, b, h) do { _Pragma("unroll") for (int m = 0; m < 4; ++m) _Pragma("unroll") for (int k = 0; k < 2; ++k) dst[m][k] = *(const PG8_LAS bf16x8*)(lds + PG8_SA(b, h) + aoff + m * 2048 + k * 1024); } while (0)
; #define PG8_LDB(dst, b, h) do { _Pragma("unroll") for (int n = 0; n < 2; ++n) _Pragma("unroll") for (int k = 0; k < 2; ++k) dst[n][k] = *(const PG8_LAS bf16x8*)(lds + PG8_SB(b, h) + boff + n * 2048 + k * 1024); } while (0)
; #define PG8_MMA(ai, bj, At, Bt) do { __builtin_amdgcn_s_setprio(1); _Pragma("unroll") for (int m = 0; m < 4; ++m) _Pragma("unroll") for (int n = 0; n < 2; ++n) _Pragma("unroll") for (int k = 0; k < 2; ++k) \
;         acc[ai][bj][m][n] = __builtin_amdgcn_mfma_f32_16x16x32_bf16(Bt[n][k], At[m][k], acc[ai][bj][m][n], 0, 0, 0); __builtin_amdgcn_s_setprio(0); } while (0)
; #define PG8_WAIT_V(n) asm volatile("s_waitcnt vmcnt(" #n ")" ::: "memory")
; #define PG8_WAIT_L(n) asm volatile("s_waitcnt lgkmcnt(" #n ")" ::: "memory")
; #define PG8_BAR __builtin_amdgcn_s_barrier()
; #define PG8_SCHED __builtin_amdgcn_sched_barrier(0)
; template <class Epi, class Sched, bool ALIGN_EPI = false, bool SP2 = false>
; __device__ __forceinline__ void gemm_phase(PG8_LAS unsigned char* lds, const Gemm g, const Sched& S, const Epi& E) {
;     ...
;             PG8_LDB(B0, 1, 0); PG8_LDB(B1, 1, 1); PG8_SCHED; PG8_LDA(At, 1, 0); PG8_STAGE(PG8_SA(0, 1), a2 + hstep, voffA);
;             PG8_WAIT_V(8); PG8_WAIT_L(0); PG8_BAR; PG8_MMA(0, 0, At, B0); PG8_MMA(0, 1, At, B1); PG8_BAR; PG8_SCHED;
;             PG8_LDA(At, 1, 1); PG8_STAGE(PG8_SB(1, 0), b3, voffB); PG8_STAGE(PG8_SB(1, 1), b3 + hstep, voffB); PG8_STAGE(PG8_SA(1, 0), a3, voffA);
;             PG8_WAIT_V(8); PG8_WAIT_L(0); PG8_BAR; PG8_MMA(1, 0, At, B0); PG8_MMA(1, 1, At, B1); PG8_BAR; PG8_SCHED;
;     ...
;         if constexpr (ALIGN_EPI) { if (wr == 0) PG8_BAR; }
	s_add_i32 s20, 0, 0x18000
	s_add_i32 s21, 0, 0x1c000
	v_add_u32_e32 v140, s20, v176
	v_add_u32_e32 v152, s21, v176
	ds_read_b128 v[128:131], v140
	ds_read_b128 v[132:135], v140 offset:1024
	ds_read_b128 v[136:139], v140 offset:2048
	ds_read_b128 v[140:143], v140 offset:3072
	ds_read_b128 v[166:169], v152
	ds_read_b128 v[170:173], v152 offset:1024
	ds_read_b128 v[190:193], v152 offset:2048
	ds_read_b128 v[194:197], v152 offset:3072
	s_add_u32 s36, s86, 0x40000
	s_addc_u32 s37, s87, 0
	s_mov_b32 m0, s95
	ds_read_b128 v[198:201], v181 offset:32768
	ds_read_b128 v[202:205], v181 offset:33792
	ds_read_b128 v[206:209], v181 offset:34816
	ds_read_b128 v[210:213], v181 offset:35840
	ds_read_b128 v[214:217], v181 offset:36864
	ds_read_b128 v[218:221], v181 offset:37888
	ds_read_b128 v[222:225], v181 offset:38912
	ds_read_b128 v[226:229], v181 offset:39936
	global_load_lds_dwordx4 v150, s[36:37]
	s_mov_b32 m0, s97
	s_nop 0
	global_load_lds_dwordx4 v146, s[36:37]
	s_waitcnt vmcnt(8)
	s_waitcnt lgkmcnt(0)
	s_barrier
	v_mfma_f32_16x16x32_bf16 v[124:127], v[128:131], v[198:201], v[124:127]
	v_mfma_f32_16x16x32_bf16 v[120:123], v[136:139], v[198:201], v[120:123]
	v_mfma_f32_16x16x32_bf16 v[108:111], v[128:131], v[206:209], v[108:111]
	v_mfma_f32_16x16x32_bf16 v[104:107], v[136:139], v[206:209], v[104:107]
	v_mfma_f32_16x16x32_bf16 v[92:95], v[128:131], v[214:217], v[92:95]
	v_mfma_f32_16x16x32_bf16 v[88:91], v[136:139], v[214:217], v[88:91]
	v_mfma_f32_16x16x32_bf16 v[76:79], v[128:131], v[222:225], v[76:79]
	v_mfma_f32_16x16x32_bf16 v[72:75], v[136:139], v[222:225], v[72:75]
	v_mfma_f32_16x16x32_bf16 v[124:127], v[132:135], v[202:205], v[124:127]
	v_mfma_f32_16x16x32_bf16 v[120:123], v[140:143], v[202:205], v[120:123]
	v_mfma_f32_16x16x32_bf16 v[108:111], v[132:135], v[210:213], v[108:111]
	v_mfma_f32_16x16x32_bf16 v[104:107], v[140:143], v[210:213], v[104:107]
	v_mfma_f32_16x16x32_bf16 v[92:95], v[132:135], v[218:221], v[92:95]
	v_mfma_f32_16x16x32_bf16 v[88:91], v[140:143], v[218:221], v[88:91]
	v_mfma_f32_16x16x32_bf16 v[76:79], v[132:135], v[226:229], v[76:79]
	v_mfma_f32_16x16x32_bf16 v[72:75], v[140:143], v[226:229], v[72:75]
	v_mfma_f32_16x16x32_bf16 v[116:119], v[166:169], v[198:201], v[116:119]
	v_mfma_f32_16x16x32_bf16 v[112:115], v[190:193], v[198:201], v[112:115]
	v_mfma_f32_16x16x32_bf16 v[100:103], v[166:169], v[206:209], v[100:103]
	v_mfma_f32_16x16x32_bf16 v[96:99], v[190:193], v[206:209], v[96:99]
	v_mfma_f32_16x16x32_bf16 v[84:87], v[166:169], v[214:217], v[84:87]
	v_mfma_f32_16x16x32_bf16 v[80:83], v[190:193], v[214:217], v[80:83]
	v_mfma_f32_16x16x32_bf16 v[68:71], v[166:169], v[222:225], v[68:71]
	v_mfma_f32_16x16x32_bf16 v[64:67], v[190:193], v[222:225], v[64:67]
	v_mfma_f32_16x16x32_bf16 v[116:119], v[170:173], v[202:205], v[116:119]
	v_mfma_f32_16x16x32_bf16 v[112:115], v[194:197], v[202:205], v[112:115]
	v_mfma_f32_16x16x32_bf16 v[100:103], v[170:173], v[210:213], v[100:103]
	v_mfma_f32_16x16x32_bf16 v[96:99], v[194:197], v[210:213], v[96:99]
	v_mfma_f32_16x16x32_bf16 v[84:87], v[170:173], v[218:221], v[84:87]
	v_mfma_f32_16x16x32_bf16 v[80:83], v[194:197], v[218:221], v[80:83]
	v_mfma_f32_16x16x32_bf16 v[68:71], v[170:173], v[226:229], v[68:71]
	v_mfma_f32_16x16x32_bf16 v[64:67], v[194:197], v[226:229], v[64:67]
	s_barrier
	s_add_i32 s20, s20, s90
	v_lshl_add_u64 v[174:175], v[174:175], 0, s[26:27]
	s_mov_b32 m0, s20
	ds_read_b128 v[198:201], v181 offset:49152
	ds_read_b128 v[202:205], v181 offset:50176
	ds_read_b128 v[206:209], v181 offset:51200
	ds_read_b128 v[210:213], v181 offset:52224
	ds_read_b128 v[214:217], v181 offset:53248
	ds_read_b128 v[218:221], v181 offset:54272
	ds_read_b128 v[222:225], v181 offset:55296
	ds_read_b128 v[226:229], v181 offset:56320
	global_load_lds_dwordx4 v[174:175], off
	s_add_i32 m0, s20, 0x2000
	s_add_u32 s36, s82, 0x40080
	v_lshl_add_u64 v[174:175], v[186:187], 0, s[26:27]
	s_addc_u32 s37, s83, 0
	s_add_i32 s20, s21, s90
	global_load_lds_dwordx4 v[174:175], off
	s_mov_b32 m0, s20
	s_nop 0
	global_load_lds_dwordx4 v148, s[36:37]
	s_add_i32 m0, s20, 0x2000
	s_nop 0
	global_load_lds_dwordx4 v144, s[36:37]
	v_lshl_add_u64 v[174:175], v[230:231], 0, s[26:27]
	s_mov_b32 m0, s42
	s_nop 0
	global_load_lds_dwordx4 v[174:175], off
	v_lshl_add_u64 v[174:175], v[232:233], 0, s[26:27]
	s_mov_b32 m0, s43
	s_nop 0
	global_load_lds_dwordx4 v[174:175], off
	s_waitcnt vmcnt(8)
	s_waitcnt lgkmcnt(0)
	s_barrier
	v_mfma_f32_16x16x32_bf16 v[60:63], v[128:131], v[198:201], v[60:63]
	v_mfma_f32_16x16x32_bf16 v[56:59], v[136:139], v[198:201], v[56:59]
	v_mfma_f32_16x16x32_bf16 v[44:47], v[128:131], v[206:209], v[44:47]
	v_mfma_f32_16x16x32_bf16 v[40:43], v[136:139], v[206:209], v[40:43]
	v_mfma_f32_16x16x32_bf16 v[28:31], v[128:131], v[214:217], v[28:31]
	v_mfma_f32_16x16x32_bf16 v[24:27], v[136:139], v[214:217], v[24:27]
	v_mfma_f32_16x16x32_bf16 v[12:15], v[128:131], v[222:225], v[12:15]
	v_mfma_f32_16x16x32_bf16 v[8:11], v[136:139], v[222:225], v[8:11]
	v_mfma_f32_16x16x32_bf16 v[60:63], v[132:135], v[202:205], v[60:63]
	v_mfma_f32_16x16x32_bf16 v[56:59], v[140:143], v[202:205], v[56:59]
	v_mfma_f32_16x16x32_bf16 v[44:47], v[132:135], v[210:213], v[44:47]
	v_mfma_f32_16x16x32_bf16 v[40:43], v[140:143], v[210:213], v[40:43]
	v_mfma_f32_16x16x32_bf16 v[28:31], v[132:135], v[218:221], v[28:31]
	v_mfma_f32_16x16x32_bf16 v[24:27], v[140:143], v[218:221], v[24:27]
	v_mfma_f32_16x16x32_bf16 v[12:15], v[132:135], v[226:229], v[12:15]
	v_mfma_f32_16x16x32_bf16 v[8:11], v[140:143], v[226:229], v[8:11]
	v_mfma_f32_16x16x32_bf16 v[52:55], v[166:169], v[198:201], v[52:55]
	v_mfma_f32_16x16x32_bf16 v[48:51], v[190:193], v[198:201], v[48:51]
	v_mfma_f32_16x16x32_bf16 v[36:39], v[166:169], v[206:209], v[36:39]
	v_mfma_f32_16x16x32_bf16 v[32:35], v[190:193], v[206:209], v[32:35]
	v_mfma_f32_16x16x32_bf16 v[20:23], v[166:169], v[214:217], v[20:23]
	v_mfma_f32_16x16x32_bf16 v[16:19], v[190:193], v[214:217], v[16:19]
	v_mfma_f32_16x16x32_bf16 v[4:7], v[166:169], v[222:225], v[4:7]
	v_mfma_f32_16x16x32_bf16 v[0:3], v[190:193], v[222:225], v[0:3]
	v_mfma_f32_16x16x32_bf16 v[52:55], v[170:173], v[202:205], v[52:55]
	v_mfma_f32_16x16x32_bf16 v[48:51], v[194:197], v[202:205], v[48:51]
	v_mfma_f32_16x16x32_bf16 v[36:39], v[170:173], v[210:213], v[36:39]
	v_mfma_f32_16x16x32_bf16 v[32:35], v[194:197], v[210:213], v[32:35]
	v_mfma_f32_16x16x32_bf16 v[20:23], v[170:173], v[218:221], v[20:23]
	v_mfma_f32_16x16x32_bf16 v[16:19], v[194:197], v[218:221], v[16:19]
	v_mfma_f32_16x16x32_bf16 v[4:7], v[170:173], v[226:229], v[4:7]
	v_mfma_f32_16x16x32_bf16 v[0:3], v[194:197], v[226:229], v[0:3]
	s_barrier
	s_add_i32 s35, s35, 2
	s_add_u32 s80, s80, 0x100
	s_addc_u32 s81, s81, 0
	s_add_u32 vcc_hi, vcc_hi, 0x100
	s_addc_u32 s34, s34, 0
	s_cmp_gt_u32 s35, 13
	s_cbranch_scc0 .LBB0_96
	s_setprio 0
	s_and_b64 vcc, exec, s[28:29]
	s_cbranch_vccz .LBB0_99
	s_barrier

;     __host__ __device__ bool next(int i, Unit& u) const { const long L = (long)i * G + c; if (L >= nwg) return false; return unit_of((int)L, u); }
;     __host__ __device__ bool next(int i, Unit& u) const { const int L = i == 0 ? l0 : (i == 1 ? l1 : (i == 2 ? l2 : -1)); if (L < 0 || L >= s.nwg) return false; return s.unit_of(L, u); }
;     __host__ __device__ bool next(int i, Unit& u) const { const bool ok = s.next(i >> 1, u); u.kh = i & 1; return ok; }
; #define PG8_STAGE(bufoff, gbase, voff) do { _Pragma("unroll") for (int _i = 0; _i < 2; ++_i) \
;         __builtin_amdgcn_global_load_lds((const unsigned*)((const char*)(gbase) + (voff)[_i]), (PG8_LAS unsigned*)(lds + (bufoff) + ldsw + _i * 8192), 16, 0, 0); } while (0)
; #define PG8_WAIT_V(n) asm volatile("s_waitcnt vmcnt(" #n ")" ::: "memory")
; #define PG8_BAR __builtin_amdgcn_s_barrier()
; template <class Epi, class Sched, bool ALIGN_EPI = false, bool SP2 = false>
; __device__ __forceinline__ void gemm_phase(PG8_LAS unsigned char* lds, const Gemm g, const Sched& S, const Epi& E) {
;     ...
;         const bool has_next = S.next(ui + 1, nxt);
;         const char* nA = has_next ? (const char*)g.A + (size_t)nxt.pm * tstep + nxt.kh * khb : cA; const char* nB = has_next ? (const char*)g.Bt + (size_t)nxt.pn * tstep + nxt.kh * khb : cB;
;         for (int t = 0; t < nt; t += 2) {
;             const bool last = (t == nt - 2);
;             const char* a1 = cA + (size_t)(t + 1) * kstep;
;             const char* a2 = last ? nA : cA + (size_t)(t + 2) * kstep; const char* b2 = last ? nB : cB + (size_t)(t + 2) * kstep;
;             const char* a3 = a2 + kstep; const char* b3 = b2 + kstep;
;             if (last && has_next) S.a_ready(nxt);
;             if constexpr (SP2) {
;             PG8_LDB(B0, 0, 0); PG8_LDB(B1, 0, 1); PG8_SCHED; PG8_LDA(At, 0, 0); PG8_STAGE(PG8_SA(1, 1), a1 + hstep, voffA);
;             PG8_WAIT_V(8); PG8_WAIT_L(0); PG8_BAR; PG8_MMA(0, 0, At, B0); PG8_MMA(0, 1, At, B1); PG8_BAR; PG8_SCHED;
;     ...
;         if (!(Epi::KSPLIT && cur.kh == 0))
; #pragma unroll
;         for (int a = 0; a < 2; ++a)
; #pragma unroll
;             for (int b = 0; b < 2; ++b)
; #pragma unroll
;                 for (int m = 0; m < 4; ++m)
; #pragma unroll
;                     for (int n = 0; n < 2; ++n) acc[a][b][m][n] = (f32x4){0.f, 0.f, 0.f, 0.f};
;         cur = nxt; cA = nA; cB = nB; ++ui;
.LBB0_149:
	s_ashr_i32 s17, s16, 31
	s_lshl_b64 s[18:19], s[16:17], 19
	s_add_u32 s18, s29, s18
	s_addc_u32 s19, s30, s19
	s_and_b64 s[20:21], s[2:3], exec
	s_cselect_b32 s17, s19, s23
	s_cselect_b32 s45, s18, s22
	s_ashr_i32 s15, s14, 31
	s_lshl_b64 s[20:21], s[14:15], 19
	s_add_u32 s20, s50, s20
	s_addc_u32 s21, s51, s21
	s_and_b64 s[26:27], s[2:3], exec
	s_cselect_b32 s15, s21, s25
	s_cselect_b32 s46, s20, s24
	s_add_u32 s22, s22, 0x40080
	s_addc_u32 s23, s23, 0
	s_add_u32 s47, s24, 0x100
	v_mov_b32_e32 v0, 0
	s_addc_u32 s48, s25, 0
	s_mov_b32 s49, -2
	v_mov_b32_e32 v1, v0
	v_mov_b32_e32 v2, v0
	v_mov_b32_e32 v3, v0
	v_mov_b32_e32 v4, v0
	v_mov_b32_e32 v5, v0
	v_mov_b32_e32 v6, v0
	v_mov_b32_e32 v7, v0
	v_mov_b32_e32 v8, v0
	v_mov_b32_e32 v9, v0
	v_mov_b32_e32 v10, v0
	v_mov_b32_e32 v11, v0
	v_mov_b32_e32 v12, v0
	v_mov_b32_e32 v13, v0
	v_mov_b32_e32 v14, v0
	v_mov_b32_e32 v15, v0
	v_mov_b32_e32 v24, v0
	v_mov_b32_e32 v25, v0
	v_mov_b32_e32 v26, v0
	v_mov_b32_e32 v27, v0
	v_mov_b32_e32 v28, v0
	v_mov_b32_e32 v29, v0
	v_mov_b32_e32 v30, v0
	v_mov_b32_e32 v31, v0
	v_mov_b32_e32 v40, v0
	v_mov_b32_e32 v41, v0
	v_mov_b32_e32 v42, v0
	v_mov_b32_e32 v43, v0
	v_mov_b32_e32 v44, v0
	v_mov_b32_e32 v45, v0
	v_mov_b32_e32 v46, v0
	v_mov_b32_e32 v47, v0
	v_mov_b32_e32 v16, v0
	v_mov_b32_e32 v17, v0
	v_mov_b32_e32 v18, v0
	v_mov_b32_e32 v19, v0
	v_mov_b32_e32 v20, v0
	v_mov_b32_e32 v21, v0
	v_mov_b32_e32 v22, v0
	v_mov_b32_e32 v23, v0
	v_mov_b32_e32 v32, v0
	v_mov_b32_e32 v33, v0
	v_mov_b32_e32 v34, v0
	v_mov_b32_e32 v35, v0
	v_mov_b32_e32 v36, v0
	v_mov_b32_e32 v37, v0
	v_mov_b32_e32 v38, v0
	v_mov_b32_e32 v39, v0
	v_mov_b32_e32 v48, v0
	v_mov_b32_e32 v49, v0
	v_mov_b32_e32 v50, v0
	v_mov_b32_e32 v51, v0
	v_mov_b32_e32 v52, v0
	v_mov_b32_e32 v53, v0
	v_mov_b32_e32 v54, v0
	v_mov_b32_e32 v55, v0
	v_mov_b32_e32 v56, v0
	v_mov_b32_e32 v57, v0
	v_mov_b32_e32 v58, v0
	v_mov_b32_e32 v59, v0
	v_mov_b32_e32 v60, v0
	v_mov_b32_e32 v61, v0
	v_mov_b32_e32 v62, v0
	v_mov_b32_e32 v63, v0
	v_mov_b32_e32 v64, v0
	v_mov_b32_e32 v65, v0
	v_mov_b32_e32 v66, v0
	v_mov_b32_e32 v67, v0
	v_mov_b32_e32 v68, v0
	v_mov_b32_e32 v69, v0
	v_mov_b32_e32 v70, v0
	v_mov_b32_e32 v71, v0
	v_mov_b32_e32 v72, v0
	v_mov_b32_e32 v73, v0
	v_mov_b32_e32 v74, v0
	v_mov_b32_e32 v75, v0
	v_mov_b32_e32 v76, v0
	v_mov_b32_e32 v77, v0
	v_mov_b32_e32 v78, v0
	v_mov_b32_e32 v79, v0
	v_mov_b32_e32 v88, v0
	v_mov_b32_e32 v89, v0
	v_mov_b32_e32 v90, v0
	v_mov_b32_e32 v91, v0
	v_mov_b32_e32 v92, v0
	v_mov_b32_e32 v93, v0
	v_mov_b32_e32 v94, v0
	v_mov_b32_e32 v95, v0
	v_mov_b32_e32 v104, v0
	v_mov_b32_e32 v105, v0
	v_mov_b32_e32 v106, v0
	v_mov_b32_e32 v107, v0
	v_mov_b32_e32 v108, v0
	v_mov_b32_e32 v109, v0
	v_mov_b32_e32 v110, v0
	v_mov_b32_e32 v111, v0
	v_mov_b32_e32 v80, v0
	v_mov_b32_e32 v81, v0
	v_mov_b32_e32 v82, v0
	v_mov_b32_e32 v83, v0
	v_mov_b32_e32 v84, v0
	v_mov_b32_e32 v85, v0
	v_mov_b32_e32 v86, v0
	v_mov_b32_e32 v87, v0
	v_mov_b32_e32 v96, v0
	v_mov_b32_e32 v97, v0
	v_mov_b32_e32 v98, v0
	v_mov_b32_e32 v99, v0
	v_mov_b32_e32 v100, v0
	v_mov_b32_e32 v101, v0
	v_mov_b32_e32 v102, v0
	v_mov_b32_e32 v103, v0
	v_mov_b32_e32 v112, v0
	v_mov_b32_e32 v113, v0
	v_mov_b32_e32 v114, v0
	v_mov_b32_e32 v115, v0
	v_mov_b32_e32 v116, v0
	v_mov_b32_e32 v117, v0
	v_mov_b32_e32 v118, v0
	v_mov_b32_e32 v119, v0
	v_mov_b32_e32 v120, v0
	v_mov_b32_e32 v121, v0
	v_mov_b32_e32 v122, v0
	v_mov_b32_e32 v123, v0
	v_mov_b32_e32 v124, v0
	v_mov_b32_e32 v125, v0
	v_mov_b32_e32 v126, v0
	v_mov_b32_e32 v127, v0
	v_readfirstlane_b32 s100, v188
	s_bitcmp1_b32 s100, 8
	s_cbranch_scc0 .Lmy_sprio_150
	s_setprio 1
.Lmy_sprio_150:
.LBB0_150:
	s_add_u32 s24, s22, 0xfffc0080
	s_addc_u32 s25, s23, -1
	s_waitcnt lgkmcnt(0)
	s_add_i32 s54, 0, 0x10000
	v_add_u32_e32 v147, s54, v152
	ds_read_b128 v[156:159], v147
	ds_read_b128 v[160:163], v147 offset:1024
	ds_read_b128 v[164:167], v147 offset:2048
	ds_read_b128 v[168:171], v147 offset:3072
	ds_read_b128 v[172:175], v154
	ds_read_b128 v[176:179], v154 offset:1024
	ds_read_b128 v[182:185], v154 offset:2048
	ds_read_b128 v[190:193], v154 offset:3072
	s_cmp_eq_u32 s49, 12
	s_cselect_b32 s27, s17, s25
	s_cselect_b32 s26, s45, s24
	s_cselect_b32 s25, s15, s48
	s_cselect_b32 s24, s46, s47
	s_add_i32 m0, s13, 0xc000
	ds_read_b128 v[194:197], v155
	ds_read_b128 v[198:201], v155 offset:1024
	ds_read_b128 v[202:205], v155 offset:2048
	ds_read_b128 v[206:209], v155 offset:3072
	ds_read_b128 v[210:213], v155 offset:4096
	ds_read_b128 v[214:217], v155 offset:5120
	ds_read_b128 v[218:221], v155 offset:6144
	ds_read_b128 v[222:225], v155 offset:7168
	global_load_lds_dwordx4 v138, s[22:23]
	s_add_i32 m0, s13, 0xe000
	s_nop 0
	global_load_lds_dwordx4 v140, s[22:23]
	s_waitcnt vmcnt(8)
	s_waitcnt lgkmcnt(0)
	s_barrier
; #define PG8_STAGE(bufoff, gbase, voff) do { _Pragma("unroll") for (int _i = 0; _i < 2; ++_i) \
;         __builtin_amdgcn_global_load_lds((const unsigned*)((const char*)(gbase) + (voff)[_i]), (PG8_LAS unsigned*)(lds + (bufoff) + ldsw + _i * 8192), 16, 0, 0); } while (0)
; #define PG8_LDA(dst, b, h) do { _Pragma("unroll") for (int m = 0; m < 4; ++m) _Pragma("unroll") for (int k = 0; k < 2; ++k) dst[m][k] = *(const PG8_LAS bf16x8*)(lds + PG8_SA(b, h) + aoff + m * 2048 + k * 1024); } while (0)
; #define PG8_MMA(ai, bj, At, Bt) do { __builtin_amdgcn_s_setprio(1); _Pragma("unroll") for (int m = 0; m < 4; ++m) _Pragma("unroll") for (int n = 0; n < 2; ++n) _Pragma("unroll") for (int k = 0; k < 2; ++k) \
;         acc[ai][bj][m][n] = __builtin_amdgcn_mfma_f32_16x16x32_bf16(Bt[n][k], At[m][k], acc[ai][bj][m][n], 0, 0, 0); __builtin_amdgcn_s_setprio(0); } while (0)
; #define PG8_WAIT_V(n) asm volatile("s_waitcnt vmcnt(" #n ")" ::: "memory")
; #define PG8_WAIT_L(n) asm volatile("s_waitcnt lgkmcnt(" #n ")" ::: "memory")
; #define PG8_BAR __builtin_amdgcn_s_barrier()
; #define PG8_SCHED __builtin_amdgcn_sched_barrier(0)
; template <class Epi, class Sched, bool ALIGN_EPI = false, bool SP2 = false>
; __device__ __forceinline__ void gemm_phase(PG8_LAS unsigned char* lds, const Gemm g, const Sched& S, const Epi& E) {
;     ...
;             PG8_WAIT_V(8); PG8_WAIT_L(0); PG8_BAR; PG8_MMA(0, 0, At, B0); PG8_MMA(0, 1, At, B1); PG8_BAR; PG8_SCHED;
;             PG8_LDA(At, 0, 1); PG8_STAGE(PG8_SB(0, 0), b2, voffB); PG8_STAGE(PG8_SB(0, 1), b2 + hstep, voffB); PG8_STAGE(PG8_SA(0, 0), a2, voffA);
;             PG8_WAIT_V(8); PG8_WAIT_L(0); PG8_BAR; PG8_MMA(1, 0, At, B0); PG8_MMA(1, 1, At, B1); PG8_BAR; PG8_SCHED;
	v_mfma_f32_16x16x32_bf16 v[124:127], v[156:159], v[194:197], v[124:127]
	v_mfma_f32_16x16x32_bf16 v[120:123], v[164:167], v[194:197], v[120:123]
	v_mfma_f32_16x16x32_bf16 v[116:119], v[156:159], v[202:205], v[116:119]
	v_mfma_f32_16x16x32_bf16 v[112:115], v[164:167], v[202:205], v[112:115]
	v_mfma_f32_16x16x32_bf16 v[100:103], v[156:159], v[210:213], v[100:103]
	v_mfma_f32_16x16x32_bf16 v[96:99], v[164:167], v[210:213], v[96:99]
	v_mfma_f32_16x16x32_bf16 v[84:87], v[156:159], v[218:221], v[84:87]
	v_mfma_f32_16x16x32_bf16 v[80:83], v[164:167], v[218:221], v[80:83]
	v_mfma_f32_16x16x32_bf16 v[124:127], v[160:163], v[198:201], v[124:127]
	v_mfma_f32_16x16x32_bf16 v[120:123], v[168:171], v[198:201], v[120:123]
	v_mfma_f32_16x16x32_bf16 v[116:119], v[160:163], v[206:209], v[116:119]
	v_mfma_f32_16x16x32_bf16 v[112:115], v[168:171], v[206:209], v[112:115]
	v_mfma_f32_16x16x32_bf16 v[100:103], v[160:163], v[214:217], v[100:103]
	v_mfma_f32_16x16x32_bf16 v[96:99], v[168:171], v[214:217], v[96:99]
	v_mfma_f32_16x16x32_bf16 v[84:87], v[160:163], v[222:225], v[84:87]
	v_mfma_f32_16x16x32_bf16 v[80:83], v[168:171], v[222:225], v[80:83]
	v_mfma_f32_16x16x32_bf16 v[108:111], v[172:175], v[194:197], v[108:111]
	v_mfma_f32_16x16x32_bf16 v[104:107], v[182:185], v[194:197], v[104:107]
	v_mfma_f32_16x16x32_bf16 v[92:95], v[172:175], v[202:205], v[92:95]
	v_mfma_f32_16x16x32_bf16 v[88:91], v[182:185], v[202:205], v[88:91]
	v_mfma_f32_16x16x32_bf16 v[76:79], v[172:175], v[210:213], v[76:79]
	v_mfma_f32_16x16x32_bf16 v[72:75], v[182:185], v[210:213], v[72:75]
	v_mfma_f32_16x16x32_bf16 v[68:71], v[172:175], v[218:221], v[68:71]
	v_mfma_f32_16x16x32_bf16 v[64:67], v[182:185], v[218:221], v[64:67]
	v_mfma_f32_16x16x32_bf16 v[108:111], v[176:179], v[198:201], v[108:111]
	v_mfma_f32_16x16x32_bf16 v[104:107], v[190:193], v[198:201], v[104:107]
	v_mfma_f32_16x16x32_bf16 v[92:95], v[176:179], v[206:209], v[92:95]
	v_mfma_f32_16x16x32_bf16 v[88:91], v[190:193], v[206:209], v[88:91]
	v_mfma_f32_16x16x32_bf16 v[76:79], v[176:179], v[214:217], v[76:79]
	v_mfma_f32_16x16x32_bf16 v[72:75], v[190:193], v[214:217], v[72:75]
	v_mfma_f32_16x16x32_bf16 v[68:71], v[176:179], v[222:225], v[68:71]
	v_mfma_f32_16x16x32_bf16 v[64:67], v[190:193], v[222:225], v[64:67]
	s_barrier
	s_add_i32 s54, s54, s31
	v_lshl_add_u64 v[186:187], s[24:25], 0, v[130:131]
	s_mov_b32 m0, s54
	ds_read_b128 v[194:197], v155 offset:16384
	ds_read_b128 v[198:201], v155 offset:17408
	ds_read_b128 v[202:205], v155 offset:18432
	ds_read_b128 v[206:209], v155 offset:19456
	ds_read_b128 v[210:213], v155 offset:20480
	ds_read_b128 v[214:217], v155 offset:21504
	ds_read_b128 v[218:221], v155 offset:22528
	ds_read_b128 v[222:225], v155 offset:23552
	global_load_lds_dwordx4 v[186:187], off
	s_add_i32 m0, s54, 0x2000
	s_add_u32 s54, s24, 0x40000
	v_lshl_add_u64 v[226:227], s[24:25], 0, v[134:135]
	s_addc_u32 s55, s25, 0
	s_add_i32 s76, s43, s31
	global_load_lds_dwordx4 v[226:227], off
	s_mov_b32 m0, s76
	v_lshl_add_u64 v[230:231], s[26:27], 0, v[132:133]
	global_load_lds_dwordx4 v130, s[54:55]
	s_add_i32 m0, s76, 0x2000
	s_nop 0
	global_load_lds_dwordx4 v134, s[54:55]
	v_lshl_add_u64 v[228:229], s[26:27], 0, v[128:129]
	s_mov_b32 m0, s13
	s_nop 0
	global_load_lds_dwordx4 v[228:229], off
	s_mov_b32 m0, s34
	s_nop 0
	global_load_lds_dwordx4 v[230:231], off
	s_waitcnt vmcnt(8)
	s_waitcnt lgkmcnt(0)
	s_barrier
	v_mfma_f32_16x16x32_bf16 v[60:63], v[156:159], v[194:197], v[60:63]
	v_mfma_f32_16x16x32_bf16 v[56:59], v[164:167], v[194:197], v[56:59]
	v_mfma_f32_16x16x32_bf16 v[52:55], v[156:159], v[202:205], v[52:55]
	v_mfma_f32_16x16x32_bf16 v[48:51], v[164:167], v[202:205], v[48:51]
	v_mfma_f32_16x16x32_bf16 v[36:39], v[156:159], v[210:213], v[36:39]
	v_mfma_f32_16x16x32_bf16 v[32:35], v[164:167], v[210:213], v[32:35]
	v_mfma_f32_16x16x32_bf16 v[20:23], v[156:159], v[218:221], v[20:23]
	v_mfma_f32_16x16x32_bf16 v[16:19], v[164:167], v[218:221], v[16:19]
	v_mfma_f32_16x16x32_bf16 v[60:63], v[160:163], v[198:201], v[60:63]
	v_mfma_f32_16x16x32_bf16 v[56:59], v[168:171], v[198:201], v[56:59]
	v_mfma_f32_16x16x32_bf16 v[52:55], v[160:163], v[206:209], v[52:55]
	v_mfma_f32_16x16x32_bf16 v[48:51], v[168:171], v[206:209], v[48:51]
	v_mfma_f32_16x16x32_bf16 v[36:39], v[160:163], v[214:217], v[36:39]
	v_mfma_f32_16x16x32_bf16 v[32:35], v[168:171], v[214:217], v[32:35]
	v_mfma_f32_16x16x32_bf16 v[20:23], v[160:163], v[222:225], v[20:23]
	v_mfma_f32_16x16x32_bf16 v[16:19], v[168:171], v[222:225], v[16:19]
	v_mfma_f32_16x16x32_bf16 v[44:47], v[172:175], v[194:197], v[44:47]
	v_mfma_f32_16x16x32_bf16 v[40:43], v[182:185], v[194:197], v[40:43]
	v_mfma_f32_16x16x32_bf16 v[28:31], v[172:175], v[202:205], v[28:31]
	v_mfma_f32_16x16x32_bf16 v[24:27], v[182:185], v[202:205], v[24:27]
	v_mfma_f32_16x16x32_bf16 v[12:15], v[172:175], v[210:213], v[12:15]
	v_mfma_f32_16x16x32_bf16 v[8:11], v[182:185], v[210:213], v[8:11]
	v_mfma_f32_16x16x32_bf16 v[4:7], v[172:175], v[218:221], v[4:7]
	v_mfma_f32_16x16x32_bf16 v[0:3], v[182:185], v[218:221], v[0:3]
	v_mfma_f32_16x16x32_bf16 v[44:47], v[176:179], v[198:201], v[44:47]
	v_mfma_f32_16x16x32_bf16 v[40:43], v[190:193], v[198:201], v[40:43]
	v_mfma_f32_16x16x32_bf16 v[28:31], v[176:179], v[206:209], v[28:31]
	v_mfma_f32_16x16x32_bf16 v[24:27], v[190:193], v[206:209], v[24:27]
	v_mfma_f32_16x16x32_bf16 v[12:15], v[176:179], v[214:217], v[12:15]
	v_mfma_f32_16x16x32_bf16 v[8:11], v[190:193], v[214:217], v[8:11]
	v_mfma_f32_16x16x32_bf16 v[4:7], v[176:179], v[222:225], v[4:7]
	v_mfma_f32_16x16x32_bf16 v[0:3], v[190:193], v[222:225], v[0:3]
	s_barrier
; #define PG8_STAGE(bufoff, gbase, voff) do { _Pragma("unroll") for (int _i = 0; _i < 2; ++_i) \
;         __builtin_amdgcn_global_load_lds((const unsigned*)((const char*)(gbase) + (voff)[_i]), (PG8_LAS unsigned*)(lds + (bufoff) + ldsw + _i * 8192), 16, 0, 0); } while (0)
; #define PG8_LDA(dst, b, h) do { _Pragma("unroll") for (int m = 0; m < 4; ++m) _Pragma("unroll") for (int k = 0; k < 2; ++k) dst[m][k] = *(const PG8_LAS bf16x8*)(lds + PG8_SA(b, h) + aoff + m * 2048 + k * 1024); } while (0)
; #define PG8_LDB(dst, b, h) do { _Pragma("unroll") for (int n = 0; n < 2; ++n) _Pragma("unroll") for (int k = 0; k < 2; ++k) dst[n][k] = *(const PG8_LAS bf16x8*)(lds + PG8_SB(b, h) + boff + n * 2048 + k * 1024); } while (0)
; #define PG8_MMA(ai, bj, At, Bt) do { __builtin_amdgcn_s_setprio(1); _Pragma("unroll") for (int m = 0; m < 4; ++m) _Pragma("unroll") for (int n = 0; n < 2; ++n) _Pragma("unroll") for (int k = 0; k < 2; ++k) \
;         acc[ai][bj][m][n] = __builtin_amdgcn_mfma_f32_16x16x32_bf16(Bt[n][k], At[m][k], acc[ai][bj][m][n], 0, 0, 0); __builtin_amdgcn_s_setprio(0); } while (0)
; #define PG8_WAIT_V(n) asm volatile("s_waitcnt vmcnt(" #n ")" ::: "memory")
; #define PG8_WAIT_L(n) asm volatile("s_waitcnt lgkmcnt(" #n ")" ::: "memory")
; #define PG8_BAR __builtin_amdgcn_s_barrier()
; #define PG8_SCHED __builtin_amdgcn_sched_barrier(0)
; template <class Epi, class Sched, bool ALIGN_EPI = false, bool SP2 = false>
; __device__ __forceinline__ void gemm_phase(PG8_LAS unsigned char* lds, const Gemm g, const Sched& S, const Epi& E) {
;     ...
;             PG8_LDB(B0, 1, 0); PG8_LDB(B1, 1, 1); PG8_SCHED; PG8_LDA(At, 1, 0); PG8_STAGE(PG8_SA(0, 1), a2 + hstep, voffA);
;             PG8_WAIT_V(8); PG8_WAIT_L(0); PG8_BAR; PG8_MMA(0, 0, At, B0); PG8_MMA(0, 1, At, B1); PG8_BAR; PG8_SCHED;
;             PG8_LDA(At, 1, 1); PG8_STAGE(PG8_SB(1, 0), b3, voffB); PG8_STAGE(PG8_SB(1, 1), b3 + hstep, voffB); PG8_STAGE(PG8_SA(1, 0), a3, voffA);
;             PG8_WAIT_V(8); PG8_WAIT_L(0); PG8_BAR; PG8_MMA(1, 0, At, B0); PG8_MMA(1, 1, At, B1); PG8_BAR; PG8_SCHED;
;     ...
;         if constexpr (ALIGN_EPI) { if (wr == 0) PG8_BAR; }
	s_add_i32 s54, 0, 0x18000
	v_add_u32_e32 v147, s54, v152
	s_add_i32 s55, 0, 0x1c000
	ds_read_b128 v[156:159], v147
	ds_read_b128 v[160:163], v147 offset:1024
	ds_read_b128 v[164:167], v147 offset:2048
	ds_read_b128 v[168:171], v147 offset:3072
	v_add_u32_e32 v147, s55, v152
	ds_read_b128 v[172:175], v147
	ds_read_b128 v[176:179], v147 offset:1024
	ds_read_b128 v[182:185], v147 offset:2048
	ds_read_b128 v[190:193], v147 offset:3072
	s_add_u32 s26, s26, 0x40000
	s_addc_u32 s27, s27, 0
	s_mov_b32 m0, s35
	ds_read_b128 v[194:197], v155 offset:32768
	ds_read_b128 v[198:201], v155 offset:33792
	ds_read_b128 v[202:205], v155 offset:34816
	ds_read_b128 v[206:209], v155 offset:35840
	ds_read_b128 v[210:213], v155 offset:36864
	ds_read_b128 v[214:217], v155 offset:37888
	ds_read_b128 v[218:221], v155 offset:38912
	ds_read_b128 v[222:225], v155 offset:39936
	global_load_lds_dwordx4 v128, s[26:27]
	s_mov_b32 m0, s36
	s_nop 0
	global_load_lds_dwordx4 v132, s[26:27]
	s_waitcnt vmcnt(8)
	s_waitcnt lgkmcnt(0)
	s_barrier
	v_mfma_f32_16x16x32_bf16 v[124:127], v[156:159], v[194:197], v[124:127]
	v_mfma_f32_16x16x32_bf16 v[120:123], v[164:167], v[194:197], v[120:123]
	v_mfma_f32_16x16x32_bf16 v[116:119], v[156:159], v[202:205], v[116:119]
	v_mfma_f32_16x16x32_bf16 v[112:115], v[164:167], v[202:205], v[112:115]
	v_mfma_f32_16x16x32_bf16 v[100:103], v[156:159], v[210:213], v[100:103]
	v_mfma_f32_16x16x32_bf16 v[96:99], v[164:167], v[210:213], v[96:99]
	v_mfma_f32_16x16x32_bf16 v[84:87], v[156:159], v[218:221], v[84:87]
	v_mfma_f32_16x16x32_bf16 v[80:83], v[164:167], v[218:221], v[80:83]
	v_mfma_f32_16x16x32_bf16 v[124:127], v[160:163], v[198:201], v[124:127]
	v_mfma_f32_16x16x32_bf16 v[120:123], v[168:171], v[198:201], v[120:123]
	v_mfma_f32_16x16x32_bf16 v[116:119], v[160:163], v[206:209], v[116:119]
	v_mfma_f32_16x16x32_bf16 v[112:115], v[168:171], v[206:209], v[112:115]
	v_mfma_f32_16x16x32_bf16 v[100:103], v[160:163], v[214:217], v[100:103]
	v_mfma_f32_16x16x32_bf16 v[96:99], v[168:171], v[214:217], v[96:99]
	v_mfma_f32_16x16x32_bf16 v[84:87], v[160:163], v[222:225], v[84:87]
	v_mfma_f32_16x16x32_bf16 v[80:83], v[168:171], v[222:225], v[80:83]
	v_mfma_f32_16x16x32_bf16 v[108:111], v[172:175], v[194:197], v[108:111]
	v_mfma_f32_16x16x32_bf16 v[104:107], v[182:185], v[194:197], v[104:107]
	v_mfma_f32_16x16x32_bf16 v[92:95], v[172:175], v[202:205], v[92:95]
	v_mfma_f32_16x16x32_bf16 v[88:91], v[182:185], v[202:205], v[88:91]
	v_mfma_f32_16x16x32_bf16 v[76:79], v[172:175], v[210:213], v[76:79]
	v_mfma_f32_16x16x32_bf16 v[72:75], v[182:185], v[210:213], v[72:75]
	v_mfma_f32_16x16x32_bf16 v[68:71], v[172:175], v[218:221], v[68:71]
	v_mfma_f32_16x16x32_bf16 v[64:67], v[182:185], v[218:221], v[64:67]
	v_mfma_f32_16x16x32_bf16 v[108:111], v[176:179], v[198:201], v[108:111]
	v_mfma_f32_16x16x32_bf16 v[104:107], v[190:193], v[198:201], v[104:107]
	v_mfma_f32_16x16x32_bf16 v[92:95], v[176:179], v[206:209], v[92:95]
	v_mfma_f32_16x16x32_bf16 v[88:91], v[190:193], v[206:209], v[88:91]
	v_mfma_f32_16x16x32_bf16 v[76:79], v[176:179], v[214:217], v[76:79]
	v_mfma_f32_16x16x32_bf16 v[72:75], v[190:193], v[214:217], v[72:75]
	v_mfma_f32_16x16x32_bf16 v[68:71], v[176:179], v[222:225], v[68:71]
	v_mfma_f32_16x16x32_bf16 v[64:67], v[190:193], v[222:225], v[64:67]
	s_barrier
	s_add_i32 s26, s54, s31
	v_lshl_add_u64 v[186:187], v[186:187], 0, s[8:9]
	s_mov_b32 m0, s26
	ds_read_b128 v[194:197], v155 offset:49152
	ds_read_b128 v[198:201], v155 offset:50176
	ds_read_b128 v[202:205], v155 offset:51200
	ds_read_b128 v[206:209], v155 offset:52224
	ds_read_b128 v[210:213], v155 offset:53248
	ds_read_b128 v[214:217], v155 offset:54272
	ds_read_b128 v[218:221], v155 offset:55296
	ds_read_b128 v[222:225], v155 offset:56320
	global_load_lds_dwordx4 v[186:187], off
	s_add_i32 m0, s26, 0x2000
	s_add_u32 s24, s24, 0x40080
	v_lshl_add_u64 v[186:187], v[226:227], 0, s[8:9]
	s_addc_u32 s25, s25, 0
	s_add_i32 s26, s55, s31
	global_load_lds_dwordx4 v[186:187], off
	s_mov_b32 m0, s26
	s_nop 0
	global_load_lds_dwordx4 v130, s[24:25]
	s_add_i32 m0, s26, 0x2000
	s_nop 0
	global_load_lds_dwordx4 v134, s[24:25]
	v_lshl_add_u64 v[186:187], v[228:229], 0, s[8:9]
	s_mov_b32 m0, s39
	s_nop 0
	global_load_lds_dwordx4 v[186:187], off
	v_lshl_add_u64 v[186:187], v[230:231], 0, s[8:9]
	s_mov_b32 m0, s40
	s_nop 0
	global_load_lds_dwordx4 v[186:187], off
	s_waitcnt vmcnt(8)
	s_waitcnt lgkmcnt(0)
	s_barrier
	v_mfma_f32_16x16x32_bf16 v[60:63], v[156:159], v[194:197], v[60:63]
	v_mfma_f32_16x16x32_bf16 v[56:59], v[164:167], v[194:197], v[56:59]
	v_mfma_f32_16x16x32_bf16 v[52:55], v[156:159], v[202:205], v[52:55]
	v_mfma_f32_16x16x32_bf16 v[48:51], v[164:167], v[202:205], v[48:51]
	v_mfma_f32_16x16x32_bf16 v[36:39], v[156:159], v[210:213], v[36:39]
	v_mfma_f32_16x16x32_bf16 v[32:35], v[164:167], v[210:213], v[32:35]
	v_mfma_f32_16x16x32_bf16 v[20:23], v[156:159], v[218:221], v[20:23]
	v_mfma_f32_16x16x32_bf16 v[16:19], v[164:167], v[218:221], v[16:19]
	v_mfma_f32_16x16x32_bf16 v[60:63], v[160:163], v[198:201], v[60:63]
	v_mfma_f32_16x16x32_bf16 v[56:59], v[168:171], v[198:201], v[56:59]
	v_mfma_f32_16x16x32_bf16 v[52:55], v[160:163], v[206:209], v[52:55]
	v_mfma_f32_16x16x32_bf16 v[48:51], v[168:171], v[206:209], v[48:51]
	v_mfma_f32_16x16x32_bf16 v[36:39], v[160:163], v[214:217], v[36:39]
	v_mfma_f32_16x16x32_bf16 v[32:35], v[168:171], v[214:217], v[32:35]
	v_mfma_f32_16x16x32_bf16 v[20:23], v[160:163], v[222:225], v[20:23]
	v_mfma_f32_16x16x32_bf16 v[16:19], v[168:171], v[222:225], v[16:19]
	v_mfma_f32_16x16x32_bf16 v[44:47], v[172:175], v[194:197], v[44:47]
	v_mfma_f32_16x16x32_bf16 v[40:43], v[182:185], v[194:197], v[40:43]
	v_mfma_f32_16x16x32_bf16 v[28:31], v[172:175], v[202:205], v[28:31]
	v_mfma_f32_16x16x32_bf16 v[24:27], v[182:185], v[202:205], v[24:27]
	v_mfma_f32_16x16x32_bf16 v[12:15], v[172:175], v[210:213], v[12:15]
	v_mfma_f32_16x16x32_bf16 v[8:11], v[182:185], v[210:213], v[8:11]
	v_mfma_f32_16x16x32_bf16 v[4:7], v[172:175], v[218:221], v[4:7]
	v_mfma_f32_16x16x32_bf16 v[0:3], v[182:185], v[218:221], v[0:3]
	v_mfma_f32_16x16x32_bf16 v[44:47], v[176:179], v[198:201], v[44:47]
	v_mfma_f32_16x16x32_bf16 v[40:43], v[190:193], v[198:201], v[40:43]
	v_mfma_f32_16x16x32_bf16 v[28:31], v[176:179], v[206:209], v[28:31]
	v_mfma_f32_16x16x32_bf16 v[24:27], v[190:193], v[206:209], v[24:27]
	v_mfma_f32_16x16x32_bf16 v[12:15], v[176:179], v[214:217], v[12:15]
	v_mfma_f32_16x16x32_bf16 v[8:11], v[190:193], v[214:217], v[8:11]
	v_mfma_f32_16x16x32_bf16 v[4:7], v[176:179], v[222:225], v[4:7]
	v_mfma_f32_16x16x32_bf16 v[0:3], v[190:193], v[222:225], v[0:3]
	s_barrier
	s_add_i32 s49, s49, 2
	s_add_u32 s22, s22, 0x100
	s_addc_u32 s23, s23, 0
	s_add_u32 s47, s47, 0x100
	s_addc_u32 s48, s48, 0
	s_cmp_gt_u32 s49, 13
	s_cbranch_scc0 .LBB0_150
	s_setprio 0
	s_and_b64 vcc, exec, s[10:11]
	s_cbranch_vccz .LBB0_153
	s_barrier

;     __host__ __device__ bool next(int i, Unit& u) const { const long L = (long)i * G + c; if (L >= nwg) return false; return unit_of((int)L, u); }
;     __host__ __device__ bool next(int i, Unit& u) const { const int L = i == 0 ? l0 : (i == 1 ? l1 : (i == 2 ? l2 : -1)); if (L < 0 || L >= s.nwg) return false; return s.unit_of(L, u); }
;     __host__ __device__ bool next(int i, Unit& u) const { const bool ok = s.next(i >> 1, u); u.kh = i & 1; return ok; }
; #define PG8_STAGE(bufoff, gbase, voff) do { _Pragma("unroll") for (int _i = 0; _i < 2; ++_i) \
;         __builtin_amdgcn_global_load_lds((const unsigned*)((const char*)(gbase) + (voff)[_i]), (PG8_LAS unsigned*)(lds + (bufoff) + ldsw + _i * 8192), 16, 0, 0); } while (0)
; #define PG8_WAIT_V(n) asm volatile("s_waitcnt vmcnt(" #n ")" ::: "memory")
; #define PG8_BAR __builtin_amdgcn_s_barrier()
; template <class Epi, class Sched, bool ALIGN_EPI = false, bool SP2 = false>
; __device__ __forceinline__ void gemm_phase(PG8_LAS unsigned char* lds, const Gemm g, const Sched& S, const Epi& E) {
;     ...
;         const bool has_next = S.next(ui + 1, nxt);
;         const char* nA = has_next ? (const char*)g.A + (size_t)nxt.pm * tstep + nxt.kh * khb : cA; const char* nB = has_next ? (const char*)g.Bt + (size_t)nxt.pn * tstep + nxt.kh * khb : cB;
;         for (int t = 0; t < nt; t += 2) {
;             const bool last = (t == nt - 2);
;             const char* a1 = cA + (size_t)(t + 1) * kstep;
;             const char* a2 = last ? nA : cA + (size_t)(t + 2) * kstep; const char* b2 = last ? nB : cB + (size_t)(t + 2) * kstep;
;             const char* a3 = a2 + kstep; const char* b3 = b2 + kstep;
;             if (last && has_next) S.a_ready(nxt);
;             if constexpr (SP2) {
;             PG8_LDB(B0, 0, 0); PG8_LDB(B1, 0, 1); PG8_SCHED; PG8_LDA(At, 0, 0); PG8_STAGE(PG8_SA(1, 1), a1 + hstep, voffA);
;             PG8_WAIT_V(8); PG8_WAIT_L(0); PG8_BAR; PG8_MMA(0, 0, At, B0); PG8_MMA(0, 1, At, B1); PG8_BAR; PG8_SCHED;
;     ...
;         if (!(Epi::KSPLIT && cur.kh == 0))
; #pragma unroll
;         for (int a = 0; a < 2; ++a)
; #pragma unroll
;             for (int b = 0; b < 2; ++b)
; #pragma unroll
;                 for (int m = 0; m < 4; ++m)
; #pragma unroll
;                     for (int n = 0; n < 2; ++n) acc[a][b][m][n] = (f32x4){0.f, 0.f, 0.f, 0.f};
;         cur = nxt; cA = nA; cB = nB; ++ui;
.LBB0_683:
	s_ashr_i32 s3, s2, 31
	s_lshl_b64 s[12:13], s[2:3], 19
	v_readlane_b32 s3, v254, 13
	s_add_u32 s16, s3, s12
	v_readlane_b32 s3, v254, 17
	s_addc_u32 s17, s3, s13
	s_and_b64 s[12:13], s[38:39], exec
	s_cselect_b32 s3, s17, s1
	s_cselect_b32 s94, s16, s0
	s_ashr_i32 s5, s4, 31
	s_lshl_b64 s[12:13], s[4:5], 19
	v_readlane_b32 s5, v254, 15
	s_add_u32 s12, s5, s12
	s_addc_u32 s13, s50, s13
	s_and_b64 s[42:43], s[38:39], exec
	s_cselect_b32 s5, s13, s41
	s_cselect_b32 s95, s12, s40
	s_add_u32 s0, s0, 0x40080
	s_addc_u32 s1, s1, 0
	s_add_u32 s96, s40, 0x100
	v_mov_b32_e32 v0, 0
	s_addc_u32 s97, s41, 0
	s_mov_b32 vcc_lo, -2
	v_mov_b32_e32 v1, v0
	v_mov_b32_e32 v2, v0
	v_mov_b32_e32 v3, v0
	v_mov_b32_e32 v4, v0
	v_mov_b32_e32 v5, v0
	v_mov_b32_e32 v6, v0
	v_mov_b32_e32 v7, v0
	v_mov_b32_e32 v16, v0
	v_mov_b32_e32 v17, v0
	v_mov_b32_e32 v18, v0
	v_mov_b32_e32 v19, v0
	v_mov_b32_e32 v20, v0
	v_mov_b32_e32 v21, v0
	v_mov_b32_e32 v22, v0
	v_mov_b32_e32 v23, v0
	v_mov_b32_e32 v32, v0
	v_mov_b32_e32 v33, v0
	v_mov_b32_e32 v34, v0
	v_mov_b32_e32 v35, v0
	v_mov_b32_e32 v36, v0
	v_mov_b32_e32 v37, v0
	v_mov_b32_e32 v38, v0
	v_mov_b32_e32 v39, v0
	v_mov_b32_e32 v48, v0
	v_mov_b32_e32 v49, v0
	v_mov_b32_e32 v50, v0
	v_mov_b32_e32 v51, v0
	v_mov_b32_e32 v52, v0
	v_mov_b32_e32 v53, v0
	v_mov_b32_e32 v54, v0
	v_mov_b32_e32 v55, v0
	v_mov_b32_e32 v8, v0
	v_mov_b32_e32 v9, v0
	v_mov_b32_e32 v10, v0
	v_mov_b32_e32 v11, v0
	v_mov_b32_e32 v12, v0
	v_mov_b32_e32 v13, v0
	v_mov_b32_e32 v14, v0
	v_mov_b32_e32 v15, v0
	v_mov_b32_e32 v24, v0
	v_mov_b32_e32 v25, v0
	v_mov_b32_e32 v26, v0
	v_mov_b32_e32 v27, v0
	v_mov_b32_e32 v28, v0
	v_mov_b32_e32 v29, v0
	v_mov_b32_e32 v30, v0
	v_mov_b32_e32 v31, v0
	v_mov_b32_e32 v40, v0
	v_mov_b32_e32 v41, v0
	v_mov_b32_e32 v42, v0
	v_mov_b32_e32 v43, v0
	v_mov_b32_e32 v44, v0
	v_mov_b32_e32 v45, v0
	v_mov_b32_e32 v46, v0
	v_mov_b32_e32 v47, v0
	v_mov_b32_e32 v56, v0
	v_mov_b32_e32 v57, v0
	v_mov_b32_e32 v58, v0
	v_mov_b32_e32 v59, v0
	v_mov_b32_e32 v60, v0
	v_mov_b32_e32 v61, v0
	v_mov_b32_e32 v62, v0
	v_mov_b32_e32 v63, v0
	v_mov_b32_e32 v64, v0
	v_mov_b32_e32 v65, v0
	v_mov_b32_e32 v66, v0
	v_mov_b32_e32 v67, v0
	v_mov_b32_e32 v68, v0
	v_mov_b32_e32 v69, v0
	v_mov_b32_e32 v70, v0
	v_mov_b32_e32 v71, v0
	v_mov_b32_e32 v80, v0
	v_mov_b32_e32 v81, v0
	v_mov_b32_e32 v82, v0
	v_mov_b32_e32 v83, v0
	v_mov_b32_e32 v84, v0
	v_mov_b32_e32 v85, v0
	v_mov_b32_e32 v86, v0
	v_mov_b32_e32 v87, v0
	v_mov_b32_e32 v96, v0
	v_mov_b32_e32 v97, v0
	v_mov_b32_e32 v98, v0
	v_mov_b32_e32 v99, v0
	v_mov_b32_e32 v100, v0
	v_mov_b32_e32 v101, v0
	v_mov_b32_e32 v102, v0
	v_mov_b32_e32 v103, v0
	v_mov_b32_e32 v112, v0
	v_mov_b32_e32 v113, v0
	v_mov_b32_e32 v114, v0
	v_mov_b32_e32 v115, v0
	v_mov_b32_e32 v116, v0
	v_mov_b32_e32 v117, v0
	v_mov_b32_e32 v118, v0
	v_mov_b32_e32 v119, v0
	v_mov_b32_e32 v72, v0
	v_mov_b32_e32 v73, v0
	v_mov_b32_e32 v74, v0
	v_mov_b32_e32 v75, v0
	v_mov_b32_e32 v76, v0
	v_mov_b32_e32 v77, v0
	v_mov_b32_e32 v78, v0
	v_mov_b32_e32 v79, v0
	v_mov_b32_e32 v88, v0
	v_mov_b32_e32 v89, v0
	v_mov_b32_e32 v90, v0
	v_mov_b32_e32 v91, v0
	v_mov_b32_e32 v92, v0
	v_mov_b32_e32 v93, v0
	v_mov_b32_e32 v94, v0
	v_mov_b32_e32 v95, v0
	v_mov_b32_e32 v104, v0
	v_mov_b32_e32 v105, v0
	v_mov_b32_e32 v106, v0
	v_mov_b32_e32 v107, v0
	v_mov_b32_e32 v108, v0
	v_mov_b32_e32 v109, v0
	v_mov_b32_e32 v110, v0
	v_mov_b32_e32 v111, v0
	v_mov_b32_e32 v120, v0
	v_mov_b32_e32 v121, v0
	v_mov_b32_e32 v122, v0
	v_mov_b32_e32 v123, v0
	v_mov_b32_e32 v124, v0
	v_mov_b32_e32 v125, v0
	v_mov_b32_e32 v126, v0
	v_mov_b32_e32 v127, v0
	v_readfirstlane_b32 s100, v188
	s_bitcmp1_b32 s100, 8
	s_cbranch_scc0 .Lmy_sprio_684
	s_setprio 1
.Lmy_sprio_684:
.LBB0_684:
	ds_read_b128 v[128:131], v174
	ds_read_b128 v[132:135], v174 offset:1024
	ds_read_b128 v[136:139], v174 offset:2048
	ds_read_b128 v[140:143], v174 offset:3072
	ds_read_b128 v[162:165], v175
	ds_read_b128 v[166:169], v175 offset:1024
	ds_read_b128 v[180:183], v175 offset:2048
	ds_read_b128 v[184:187], v175 offset:3072
	s_add_u32 s8, s0, 0xfffc0080
	s_addc_u32 s9, s1, -1
	s_cmp_eq_u32 vcc_lo, 12
	s_cselect_b32 s43, s3, s9
	s_cselect_b32 s42, s94, s8
	s_cselect_b32 s41, s5, s97
	s_cselect_b32 s40, s95, s96
	s_add_i32 m0, s47, 0xc000
	ds_read_b128 v[190:193], v176
	ds_read_b128 v[194:197], v176 offset:1024
	ds_read_b128 v[198:201], v176 offset:2048
	ds_read_b128 v[202:205], v176 offset:3072
	ds_read_b128 v[206:209], v176 offset:4096
	ds_read_b128 v[210:213], v176 offset:5120
	ds_read_b128 v[214:217], v176 offset:6144
	ds_read_b128 v[218:221], v176 offset:7168
	global_load_lds_dwordx4 v158, s[0:1]
	s_add_i32 m0, s47, 0xe000
	s_nop 0
	global_load_lds_dwordx4 v160, s[0:1]
	s_waitcnt vmcnt(8)
	s_waitcnt lgkmcnt(0)
	s_barrier
; #define PG8_STAGE(bufoff, gbase, voff) do { _Pragma("unroll") for (int _i = 0; _i < 2; ++_i) \
;         __builtin_amdgcn_global_load_lds((const unsigned*)((const char*)(gbase) + (voff)[_i]), (PG8_LAS unsigned*)(lds + (bufoff) + ldsw + _i * 8192), 16, 0, 0); } while (0)
; #define PG8_LDA(dst, b, h) do { _Pragma("unroll") for (int m = 0; m < 4; ++m) _Pragma("unroll") for (int k = 0; k < 2; ++k) dst[m][k] = *(const PG8_LAS bf16x8*)(lds + PG8_SA(b, h) + aoff + m * 2048 + k * 1024); } while (0)
; #define PG8_MMA(ai, bj, At, Bt) do { __builtin_amdgcn_s_setprio(1); _Pragma("unroll") for (int m = 0; m < 4; ++m) _Pragma("unroll") for (int n = 0; n < 2; ++n) _Pragma("unroll") for (int k = 0; k < 2; ++k) \
;         acc[ai][bj][m][n] = __builtin_amdgcn_mfma_f32_16x16x32_bf16(Bt[n][k], At[m][k], acc[ai][bj][m][n], 0, 0, 0); __builtin_amdgcn_s_setprio(0); } while (0)
; #define PG8_WAIT_V(n) asm volatile("s_waitcnt vmcnt(" #n ")" ::: "memory")
; #define PG8_WAIT_L(n) asm volatile("s_waitcnt lgkmcnt(" #n ")" ::: "memory")
; #define PG8_BAR __builtin_amdgcn_s_barrier()
; #define PG8_SCHED __builtin_amdgcn_sched_barrier(0)
; template <class Epi, class Sched, bool ALIGN_EPI = false, bool SP2 = false>
; __device__ __forceinline__ void gemm_phase(PG8_LAS unsigned char* lds, const Gemm g, const Sched& S, const Epi& E) {
;     ...
;             PG8_WAIT_V(8); PG8_WAIT_L(0); PG8_BAR; PG8_MMA(0, 0, At, B0); PG8_MMA(0, 1, At, B1); PG8_BAR; PG8_SCHED;
;             PG8_LDA(At, 0, 1); PG8_STAGE(PG8_SB(0, 0), b2, voffB); PG8_STAGE(PG8_SB(0, 1), b2 + hstep, voffB); PG8_STAGE(PG8_SA(0, 0), a2, voffA);
;             PG8_WAIT_V(8); PG8_WAIT_L(0); PG8_BAR; PG8_MMA(1, 0, At, B0); PG8_MMA(1, 1, At, B1); PG8_BAR; PG8_SCHED;
	v_mfma_f32_16x16x32_bf16 v[124:127], v[128:131], v[190:193], v[124:127]
	v_mfma_f32_16x16x32_bf16 v[120:123], v[136:139], v[190:193], v[120:123]
	v_mfma_f32_16x16x32_bf16 v[108:111], v[128:131], v[198:201], v[108:111]
	v_mfma_f32_16x16x32_bf16 v[104:107], v[136:139], v[198:201], v[104:107]
	v_mfma_f32_16x16x32_bf16 v[92:95], v[128:131], v[206:209], v[92:95]
	v_mfma_f32_16x16x32_bf16 v[88:91], v[136:139], v[206:209], v[88:91]
	v_mfma_f32_16x16x32_bf16 v[76:79], v[128:131], v[214:217], v[76:79]
	v_mfma_f32_16x16x32_bf16 v[72:75], v[136:139], v[214:217], v[72:75]
	v_mfma_f32_16x16x32_bf16 v[124:127], v[132:135], v[194:197], v[124:127]
	v_mfma_f32_16x16x32_bf16 v[120:123], v[140:143], v[194:197], v[120:123]
	v_mfma_f32_16x16x32_bf16 v[108:111], v[132:135], v[202:205], v[108:111]
	v_mfma_f32_16x16x32_bf16 v[104:107], v[140:143], v[202:205], v[104:107]
	v_mfma_f32_16x16x32_bf16 v[92:95], v[132:135], v[210:213], v[92:95]
	v_mfma_f32_16x16x32_bf16 v[88:91], v[140:143], v[210:213], v[88:91]
	v_mfma_f32_16x16x32_bf16 v[76:79], v[132:135], v[218:221], v[76:79]
	v_mfma_f32_16x16x32_bf16 v[72:75], v[140:143], v[218:221], v[72:75]
	v_mfma_f32_16x16x32_bf16 v[116:119], v[162:165], v[190:193], v[116:119]
	v_mfma_f32_16x16x32_bf16 v[112:115], v[180:183], v[190:193], v[112:115]
	v_mfma_f32_16x16x32_bf16 v[100:103], v[162:165], v[198:201], v[100:103]
	v_mfma_f32_16x16x32_bf16 v[96:99], v[180:183], v[198:201], v[96:99]
	v_mfma_f32_16x16x32_bf16 v[84:87], v[162:165], v[206:209], v[84:87]
	v_mfma_f32_16x16x32_bf16 v[80:83], v[180:183], v[206:209], v[80:83]
	v_mfma_f32_16x16x32_bf16 v[68:71], v[162:165], v[214:217], v[68:71]
	v_mfma_f32_16x16x32_bf16 v[64:67], v[180:183], v[214:217], v[64:67]
	v_mfma_f32_16x16x32_bf16 v[116:119], v[166:169], v[194:197], v[116:119]
	v_mfma_f32_16x16x32_bf16 v[112:115], v[184:187], v[194:197], v[112:115]
	v_mfma_f32_16x16x32_bf16 v[100:103], v[166:169], v[202:205], v[100:103]
	v_mfma_f32_16x16x32_bf16 v[96:99], v[184:187], v[202:205], v[96:99]
	v_mfma_f32_16x16x32_bf16 v[84:87], v[166:169], v[210:213], v[84:87]
	v_mfma_f32_16x16x32_bf16 v[80:83], v[184:187], v[210:213], v[80:83]
	v_mfma_f32_16x16x32_bf16 v[68:71], v[166:169], v[218:221], v[68:71]
	v_mfma_f32_16x16x32_bf16 v[64:67], v[184:187], v[218:221], v[64:67]
	s_barrier
	s_add_i32 s8, s76, s46
	v_lshl_add_u64 v[170:171], s[40:41], 0, v[146:147]
	s_mov_b32 m0, s8
	ds_read_b128 v[190:193], v176 offset:16384
	ds_read_b128 v[194:197], v176 offset:17408
	ds_read_b128 v[198:201], v176 offset:18432
	ds_read_b128 v[202:205], v176 offset:19456
	ds_read_b128 v[206:209], v176 offset:20480
	ds_read_b128 v[210:213], v176 offset:21504
	ds_read_b128 v[214:217], v176 offset:22528
	ds_read_b128 v[218:221], v176 offset:23552
	global_load_lds_dwordx4 v[170:171], off
	s_add_i32 m0, s8, 0x2000
	s_add_u32 s8, s40, 0x40000
	v_lshl_add_u64 v[222:223], s[40:41], 0, v[150:151]
	s_addc_u32 s9, s41, 0
	s_add_i32 s54, s77, s46
	global_load_lds_dwordx4 v[222:223], off
	s_mov_b32 m0, s54
	v_lshl_add_u64 v[226:227], s[42:43], 0, v[148:149]
	global_load_lds_dwordx4 v146, s[8:9]
	s_add_i32 m0, s54, 0x2000
	s_nop 0
	global_load_lds_dwordx4 v150, s[8:9]
	v_lshl_add_u64 v[224:225], s[42:43], 0, v[144:145]
	s_mov_b32 m0, s47
	s_nop 0
	global_load_lds_dwordx4 v[224:225], off
	s_mov_b32 m0, s48
	s_nop 0
	global_load_lds_dwordx4 v[226:227], off
	s_waitcnt vmcnt(8)
	s_waitcnt lgkmcnt(0)
	s_barrier
	v_mfma_f32_16x16x32_bf16 v[60:63], v[128:131], v[190:193], v[60:63]
	v_mfma_f32_16x16x32_bf16 v[56:59], v[136:139], v[190:193], v[56:59]
	v_mfma_f32_16x16x32_bf16 v[44:47], v[128:131], v[198:201], v[44:47]
	v_mfma_f32_16x16x32_bf16 v[40:43], v[136:139], v[198:201], v[40:43]
	v_mfma_f32_16x16x32_bf16 v[28:31], v[128:131], v[206:209], v[28:31]
	v_mfma_f32_16x16x32_bf16 v[24:27], v[136:139], v[206:209], v[24:27]
	v_mfma_f32_16x16x32_bf16 v[12:15], v[128:131], v[214:217], v[12:15]
	v_mfma_f32_16x16x32_bf16 v[8:11], v[136:139], v[214:217], v[8:11]
	v_mfma_f32_16x16x32_bf16 v[60:63], v[132:135], v[194:197], v[60:63]
	v_mfma_f32_16x16x32_bf16 v[56:59], v[140:143], v[194:197], v[56:59]
	v_mfma_f32_16x16x32_bf16 v[44:47], v[132:135], v[202:205], v[44:47]
	v_mfma_f32_16x16x32_bf16 v[40:43], v[140:143], v[202:205], v[40:43]
	v_mfma_f32_16x16x32_bf16 v[28:31], v[132:135], v[210:213], v[28:31]
	v_mfma_f32_16x16x32_bf16 v[24:27], v[140:143], v[210:213], v[24:27]
	v_mfma_f32_16x16x32_bf16 v[12:15], v[132:135], v[218:221], v[12:15]
	v_mfma_f32_16x16x32_bf16 v[8:11], v[140:143], v[218:221], v[8:11]
	v_mfma_f32_16x16x32_bf16 v[52:55], v[162:165], v[190:193], v[52:55]
	v_mfma_f32_16x16x32_bf16 v[48:51], v[180:183], v[190:193], v[48:51]
	v_mfma_f32_16x16x32_bf16 v[36:39], v[162:165], v[198:201], v[36:39]
	v_mfma_f32_16x16x32_bf16 v[32:35], v[180:183], v[198:201], v[32:35]
	v_mfma_f32_16x16x32_bf16 v[20:23], v[162:165], v[206:209], v[20:23]
	v_mfma_f32_16x16x32_bf16 v[16:19], v[180:183], v[206:209], v[16:19]
	v_mfma_f32_16x16x32_bf16 v[4:7], v[162:165], v[214:217], v[4:7]
	v_mfma_f32_16x16x32_bf16 v[0:3], v[180:183], v[214:217], v[0:3]
	v_mfma_f32_16x16x32_bf16 v[52:55], v[166:169], v[194:197], v[52:55]
	v_mfma_f32_16x16x32_bf16 v[48:51], v[184:187], v[194:197], v[48:51]
	v_mfma_f32_16x16x32_bf16 v[36:39], v[166:169], v[202:205], v[36:39]
	v_mfma_f32_16x16x32_bf16 v[32:35], v[184:187], v[202:205], v[32:35]
	v_mfma_f32_16x16x32_bf16 v[20:23], v[166:169], v[210:213], v[20:23]
	v_mfma_f32_16x16x32_bf16 v[16:19], v[184:187], v[210:213], v[16:19]
	v_mfma_f32_16x16x32_bf16 v[4:7], v[166:169], v[218:221], v[4:7]
	v_mfma_f32_16x16x32_bf16 v[0:3], v[184:187], v[218:221], v[0:3]
	s_barrier
; #define PG8_STAGE(bufoff, gbase, voff) do { _Pragma("unroll") for (int _i = 0; _i < 2; ++_i) \
;         __builtin_amdgcn_global_load_lds((const unsigned*)((const char*)(gbase) + (voff)[_i]), (PG8_LAS unsigned*)(lds + (bufoff) + ldsw + _i * 8192), 16, 0, 0); } while (0)
; #define PG8_LDA(dst, b, h) do { _Pragma("unroll") for (int m = 0; m < 4; ++m) _Pragma("unroll") for (int k = 0; k < 2; ++k) dst[m][k] = *(const PG8_LAS bf16x8*)(lds + PG8_SA(b, h) + aoff + m * 2048 + k * 1024); } while (0)
; #define PG8_LDB(dst, b, h) do { _Pragma("unroll") for (int n = 0; n < 2; ++n) _Pragma("unroll") for (int k = 0; k < 2; ++k) dst[n][k] = *(const PG8_LAS bf16x8*)(lds + PG8_SB(b, h) + boff + n * 2048 + k * 1024); } while (0)
; #define PG8_MMA(ai, bj, At, Bt) do { __builtin_amdgcn_s_setprio(1); _Pragma("unroll") for (int m = 0; m < 4; ++m) _Pragma("unroll") for (int n = 0; n < 2; ++n) _Pragma("unroll") for (int k = 0; k < 2; ++k) \
;         acc[ai][bj][m][n] = __builtin_amdgcn_mfma_f32_16x16x32_bf16(Bt[n][k], At[m][k], acc[ai][bj][m][n], 0, 0, 0); __builtin_amdgcn_s_setprio(0); } while (0)
; #define PG8_WAIT_V(n) asm volatile("s_waitcnt vmcnt(" #n ")" ::: "memory")
; #define PG8_WAIT_L(n) asm volatile("s_waitcnt lgkmcnt(" #n ")" ::: "memory")
; #define PG8_BAR __builtin_amdgcn_s_barrier()
; #define PG8_SCHED __builtin_amdgcn_sched_barrier(0)
; template <class Epi, class Sched, bool ALIGN_EPI = false, bool SP2 = false>
; __device__ __forceinline__ void gemm_phase(PG8_LAS unsigned char* lds, const Gemm g, const Sched& S, const Epi& E) {
;     ...
;             PG8_LDB(B0, 1, 0); PG8_LDB(B1, 1, 1); PG8_SCHED; PG8_LDA(At, 1, 0); PG8_STAGE(PG8_SA(0, 1), a2 + hstep, voffA);
;             PG8_WAIT_V(8); PG8_WAIT_L(0); PG8_BAR; PG8_MMA(0, 0, At, B0); PG8_MMA(0, 1, At, B1); PG8_BAR; PG8_SCHED;
;             PG8_LDA(At, 1, 1); PG8_STAGE(PG8_SB(1, 0), b3, voffB); PG8_STAGE(PG8_SB(1, 1), b3 + hstep, voffB); PG8_STAGE(PG8_SA(1, 0), a3, voffA);
;             PG8_WAIT_V(8); PG8_WAIT_L(0); PG8_BAR; PG8_MMA(1, 0, At, B0); PG8_MMA(1, 1, At, B1); PG8_BAR; PG8_SCHED;
;     ...
;         if constexpr (ALIGN_EPI) { if (wr == 0) PG8_BAR; }
	s_add_i32 s54, 0, 0x18000
	s_add_i32 s55, 0, 0x1c000
	v_add_u32_e32 v140, s54, v172
	v_add_u32_e32 v152, s55, v172
	ds_read_b128 v[128:131], v140
	ds_read_b128 v[132:135], v140 offset:1024
	ds_read_b128 v[136:139], v140 offset:2048
	ds_read_b128 v[140:143], v140 offset:3072
	ds_read_b128 v[162:165], v152
	ds_read_b128 v[166:169], v152 offset:1024
	ds_read_b128 v[180:183], v152 offset:2048
	ds_read_b128 v[184:187], v152 offset:3072
	s_add_u32 s8, s42, 0x40000
	s_addc_u32 s9, s43, 0
	s_mov_b32 m0, s49
	ds_read_b128 v[190:193], v176 offset:32768
	ds_read_b128 v[194:197], v176 offset:33792
	ds_read_b128 v[198:201], v176 offset:34816
	ds_read_b128 v[202:205], v176 offset:35840
	ds_read_b128 v[206:209], v176 offset:36864
	ds_read_b128 v[210:213], v176 offset:37888
	ds_read_b128 v[214:217], v176 offset:38912
	ds_read_b128 v[218:221], v176 offset:39936
	global_load_lds_dwordx4 v144, s[8:9]
	s_mov_b32 m0, s51
	s_nop 0
	global_load_lds_dwordx4 v148, s[8:9]
	s_waitcnt vmcnt(8)
	s_waitcnt lgkmcnt(0)
	s_barrier
	v_mfma_f32_16x16x32_bf16 v[124:127], v[128:131], v[190:193], v[124:127]
	v_mfma_f32_16x16x32_bf16 v[120:123], v[136:139], v[190:193], v[120:123]
	v_mfma_f32_16x16x32_bf16 v[108:111], v[128:131], v[198:201], v[108:111]
	v_mfma_f32_16x16x32_bf16 v[104:107], v[136:139], v[198:201], v[104:107]
	v_mfma_f32_16x16x32_bf16 v[92:95], v[128:131], v[206:209], v[92:95]
	v_mfma_f32_16x16x32_bf16 v[88:91], v[136:139], v[206:209], v[88:91]
	v_mfma_f32_16x16x32_bf16 v[76:79], v[128:131], v[214:217], v[76:79]
	v_mfma_f32_16x16x32_bf16 v[72:75], v[136:139], v[214:217], v[72:75]
	v_mfma_f32_16x16x32_bf16 v[124:127], v[132:135], v[194:197], v[124:127]
	v_mfma_f32_16x16x32_bf16 v[120:123], v[140:143], v[194:197], v[120:123]
	v_mfma_f32_16x16x32_bf16 v[108:111], v[132:135], v[202:205], v[108:111]
	v_mfma_f32_16x16x32_bf16 v[104:107], v[140:143], v[202:205], v[104:107]
	v_mfma_f32_16x16x32_bf16 v[92:95], v[132:135], v[210:213], v[92:95]
	v_mfma_f32_16x16x32_bf16 v[88:91], v[140:143], v[210:213], v[88:91]
	v_mfma_f32_16x16x32_bf16 v[76:79], v[132:135], v[218:221], v[76:79]
	v_mfma_f32_16x16x32_bf16 v[72:75], v[140:143], v[218:221], v[72:75]
	v_mfma_f32_16x16x32_bf16 v[116:119], v[162:165], v[190:193], v[116:119]
	v_mfma_f32_16x16x32_bf16 v[112:115], v[180:183], v[190:193], v[112:115]
	v_mfma_f32_16x16x32_bf16 v[100:103], v[162:165], v[198:201], v[100:103]
	v_mfma_f32_16x16x32_bf16 v[96:99], v[180:183], v[198:201], v[96:99]
	v_mfma_f32_16x16x32_bf16 v[84:87], v[162:165], v[206:209], v[84:87]
	v_mfma_f32_16x16x32_bf16 v[80:83], v[180:183], v[206:209], v[80:83]
	v_mfma_f32_16x16x32_bf16 v[68:71], v[162:165], v[214:217], v[68:71]
	v_mfma_f32_16x16x32_bf16 v[64:67], v[180:183], v[214:217], v[64:67]
	v_mfma_f32_16x16x32_bf16 v[116:119], v[166:169], v[194:197], v[116:119]
	v_mfma_f32_16x16x32_bf16 v[112:115], v[184:187], v[194:197], v[112:115]
	v_mfma_f32_16x16x32_bf16 v[100:103], v[166:169], v[202:205], v[100:103]
	v_mfma_f32_16x16x32_bf16 v[96:99], v[184:187], v[202:205], v[96:99]
	v_mfma_f32_16x16x32_bf16 v[84:87], v[166:169], v[210:213], v[84:87]
	v_mfma_f32_16x16x32_bf16 v[80:83], v[184:187], v[210:213], v[80:83]
	v_mfma_f32_16x16x32_bf16 v[68:71], v[166:169], v[218:221], v[68:71]
	v_mfma_f32_16x16x32_bf16 v[64:67], v[184:187], v[218:221], v[64:67]
	s_barrier
	s_add_i32 s8, s54, s46
	v_lshl_add_u64 v[170:171], v[170:171], 0, s[14:15]
	s_mov_b32 m0, s8
	ds_read_b128 v[190:193], v176 offset:49152
	ds_read_b128 v[194:197], v176 offset:50176
	ds_read_b128 v[198:201], v176 offset:51200
	ds_read_b128 v[202:205], v176 offset:52224
	ds_read_b128 v[206:209], v176 offset:53248
	ds_read_b128 v[210:213], v176 offset:54272
	ds_read_b128 v[214:217], v176 offset:55296
	ds_read_b128 v[218:221], v176 offset:56320
	global_load_lds_dwordx4 v[170:171], off
	s_add_i32 m0, s8, 0x2000
	s_add_u32 s8, s40, 0x40080
	v_lshl_add_u64 v[170:171], v[222:223], 0, s[14:15]
	s_addc_u32 s9, s41, 0
	s_add_i32 s40, s55, s46
	global_load_lds_dwordx4 v[170:171], off
	s_mov_b32 m0, s40
	s_nop 0
	global_load_lds_dwordx4 v146, s[8:9]
	s_add_i32 m0, s40, 0x2000
	s_nop 0
	global_load_lds_dwordx4 v150, s[8:9]
	v_lshl_add_u64 v[170:171], v[224:225], 0, s[14:15]
	s_mov_b32 m0, s66
	s_nop 0
	global_load_lds_dwordx4 v[170:171], off
	v_lshl_add_u64 v[170:171], v[226:227], 0, s[14:15]
	s_mov_b32 m0, s67
	s_nop 0
	global_load_lds_dwordx4 v[170:171], off
	s_waitcnt vmcnt(8)
	s_waitcnt lgkmcnt(0)
	s_barrier
	v_mfma_f32_16x16x32_bf16 v[60:63], v[128:131], v[190:193], v[60:63]
	v_mfma_f32_16x16x32_bf16 v[56:59], v[136:139], v[190:193], v[56:59]
	v_mfma_f32_16x16x32_bf16 v[44:47], v[128:131], v[198:201], v[44:47]
	v_mfma_f32_16x16x32_bf16 v[40:43], v[136:139], v[198:201], v[40:43]
	v_mfma_f32_16x16x32_bf16 v[28:31], v[128:131], v[206:209], v[28:31]
	v_mfma_f32_16x16x32_bf16 v[24:27], v[136:139], v[206:209], v[24:27]
	v_mfma_f32_16x16x32_bf16 v[12:15], v[128:131], v[214:217], v[12:15]
	v_mfma_f32_16x16x32_bf16 v[8:11], v[136:139], v[214:217], v[8:11]
	v_mfma_f32_16x16x32_bf16 v[60:63], v[132:135], v[194:197], v[60:63]
	v_mfma_f32_16x16x32_bf16 v[56:59], v[140:143], v[194:197], v[56:59]
	v_mfma_f32_16x16x32_bf16 v[44:47], v[132:135], v[202:205], v[44:47]
	v_mfma_f32_16x16x32_bf16 v[40:43], v[140:143], v[202:205], v[40:43]
	v_mfma_f32_16x16x32_bf16 v[28:31], v[132:135], v[210:213], v[28:31]
	v_mfma_f32_16x16x32_bf16 v[24:27], v[140:143], v[210:213], v[24:27]
	v_mfma_f32_16x16x32_bf16 v[12:15], v[132:135], v[218:221], v[12:15]
	v_mfma_f32_16x16x32_bf16 v[8:11], v[140:143], v[218:221], v[8:11]
	v_mfma_f32_16x16x32_bf16 v[52:55], v[162:165], v[190:193], v[52:55]
	v_mfma_f32_16x16x32_bf16 v[48:51], v[180:183], v[190:193], v[48:51]
	v_mfma_f32_16x16x32_bf16 v[36:39], v[162:165], v[198:201], v[36:39]
	v_mfma_f32_16x16x32_bf16 v[32:35], v[180:183], v[198:201], v[32:35]
	v_mfma_f32_16x16x32_bf16 v[20:23], v[162:165], v[206:209], v[20:23]
	v_mfma_f32_16x16x32_bf16 v[16:19], v[180:183], v[206:209], v[16:19]
	v_mfma_f32_16x16x32_bf16 v[4:7], v[162:165], v[214:217], v[4:7]
	v_mfma_f32_16x16x32_bf16 v[0:3], v[180:183], v[214:217], v[0:3]
	v_mfma_f32_16x16x32_bf16 v[52:55], v[166:169], v[194:197], v[52:55]
	v_mfma_f32_16x16x32_bf16 v[48:51], v[184:187], v[194:197], v[48:51]
	v_mfma_f32_16x16x32_bf16 v[36:39], v[166:169], v[202:205], v[36:39]
	v_mfma_f32_16x16x32_bf16 v[32:35], v[184:187], v[202:205], v[32:35]
	v_mfma_f32_16x16x32_bf16 v[20:23], v[166:169], v[210:213], v[20:23]
	v_mfma_f32_16x16x32_bf16 v[16:19], v[184:187], v[210:213], v[16:19]
	v_mfma_f32_16x16x32_bf16 v[4:7], v[166:169], v[218:221], v[4:7]
	v_mfma_f32_16x16x32_bf16 v[0:3], v[184:187], v[218:221], v[0:3]
	s_barrier
	s_add_i32 vcc_lo, vcc_lo, 2
	s_add_u32 s0, s0, 0x100
	s_addc_u32 s1, s1, 0
	s_add_u32 s96, s96, 0x100
	s_addc_u32 s97, s97, 0
	s_cmp_gt_u32 vcc_lo, 13
	s_cbranch_scc0 .LBB0_684
	s_setprio 0
	s_and_b64 vcc, exec, s[18:19]
	s_cbranch_vccz .LBB0_687
	s_barrier

;     __host__ __device__ bool next(int i, Unit& u) const { const long L = (long)i * G + c; if (L >= nwg) return false; return unit_of((int)L, u); }
;     __host__ __device__ bool next(int i, Unit& u) const { const int L = i == 0 ? l0 : (i == 1 ? l1 : (i == 2 ? l2 : -1)); if (L < 0 || L >= s.nwg) return false; return s.unit_of(L, u); }
;     __host__ __device__ bool next(int i, Unit& u) const { const bool ok = s.next(i >> 1, u); u.kh = i & 1; return ok; }
; #define PG8_STAGE(bufoff, gbase, voff) do { _Pragma("unroll") for (int _i = 0; _i < 2; ++_i) \
;         __builtin_amdgcn_global_load_lds((const unsigned*)((const char*)(gbase) + (voff)[_i]), (PG8_LAS unsigned*)(lds + (bufoff) + ldsw + _i * 8192), 16, 0, 0); } while (0)
; #define PG8_LDA(dst, b, h) do { _Pragma("unroll") for (int m = 0; m < 4; ++m) _Pragma("unroll") for (int k = 0; k < 2; ++k) dst[m][k] = *(const PG8_LAS bf16x8*)(lds + PG8_SA(b, h) + aoff + m * 2048 + k * 1024); } while (0)
; template <class Epi, class Sched, bool ALIGN_EPI = false, bool SP2 = false>
; __device__ __forceinline__ void gemm_phase(PG8_LAS unsigned char* lds, const Gemm g, const Sched& S, const Epi& E) {
;     ...
;         const bool has_next = S.next(ui + 1, nxt);
;         const char* nA = has_next ? (const char*)g.A + (size_t)nxt.pm * tstep + nxt.kh * khb : cA; const char* nB = has_next ? (const char*)g.Bt + (size_t)nxt.pn * tstep + nxt.kh * khb : cB;
;         for (int t = 0; t < nt; t += 2) {
;             const bool last = (t == nt - 2);
;             const char* a1 = cA + (size_t)(t + 1) * kstep;
;             const char* a2 = last ? nA : cA + (size_t)(t + 2) * kstep; const char* b2 = last ? nB : cB + (size_t)(t + 2) * kstep;
;             const char* a3 = a2 + kstep; const char* b3 = b2 + kstep;
;             if (last && has_next) S.a_ready(nxt);
;             if constexpr (SP2) {
;             PG8_LDB(B0, 0, 0); PG8_LDB(B1, 0, 1); PG8_SCHED; PG8_LDA(At, 0, 0); PG8_STAGE(PG8_SA(1, 1), a1 + hstep, voffA);
;             PG8_WAIT_V(8); PG8_WAIT_L(0); PG8_BAR; PG8_MMA(0, 0, At, B0); PG8_MMA(0, 1, At, B1); PG8_BAR; PG8_SCHED;
;             PG8_LDA(At, 0, 1); PG8_STAGE(PG8_SB(0, 0), b2, voffB); PG8_STAGE(PG8_SB(0, 1), b2 + hstep, voffB); PG8_STAGE(PG8_SA(0, 0), a2, voffA);
;             PG8_WAIT_V(8); PG8_WAIT_L(0); PG8_BAR; PG8_MMA(1, 0, At, B0); PG8_MMA(1, 1, At, B1); PG8_BAR; PG8_SCHED;
.LBB0_794:
	s_ashr_i32 s41, s40, 31
	s_and_b32 s76, s69, 1
	s_lshl_b64 s[42:43], s[40:41], 20
	s_add_u32 s39, s50, s42
	s_addc_u32 s41, s51, s43
	s_lshl_b32 s56, s76, 11
	s_add_u32 s42, s39, s56
	s_addc_u32 s43, s41, 0
	s_and_b64 s[44:45], s[2:3], exec
	s_cselect_b32 s41, s43, s47
	s_cselect_b32 s78, s42, s46
	s_ashr_i32 s39, s38, 31
	s_lshl_b64 s[44:45], s[38:39], 20
	s_add_u32 s39, s58, s44
	s_addc_u32 s45, s59, s45
	s_add_u32 s44, s39, s56
	s_addc_u32 s45, s45, 0
	s_and_b64 s[56:57], s[2:3], exec
	s_cselect_b32 s39, s45, s55
	s_cselect_b32 s79, s44, s54
	s_add_u32 s46, s46, 0x80080
	s_addc_u32 s47, s47, 0
	s_add_u32 s80, s54, 0x100
	s_addc_u32 s81, s55, 0
	s_mov_b32 s82, -2
	v_readfirstlane_b32 s100, v188
	s_bitcmp1_b32 s100, 8
	s_cbranch_scc0 .Lmy_sprio_795
	s_setprio 1
.Lmy_sprio_795:
.LBB0_795:
	v_add_u32_e32 v162, s67, v186
	v_add_u32_e32 v178, s68, v186
	ds_read_b128 v[150:153], v162
	ds_read_b128 v[154:157], v162 offset:1024
	ds_read_b128 v[158:161], v162 offset:2048
	ds_read_b128 v[162:165], v162 offset:3072
	ds_read_b128 v[166:169], v178
	ds_read_b128 v[170:173], v178 offset:1024
	ds_read_b128 v[174:177], v178 offset:2048
	ds_read_b128 v[178:181], v178 offset:3072
	s_add_u32 s54, s46, 0xfff80080
	s_addc_u32 s55, s47, -1
	s_cmp_eq_u32 s82, 12
	s_cselect_b32 s57, s41, s55
	s_cselect_b32 s56, s78, s54
	s_cselect_b32 s55, s39, s81
	s_cselect_b32 s54, s79, s80
	s_add_i32 m0, s61, 0xc000
	ds_read_b128 v[182:185], v187
	ds_read_b128 v[190:193], v187 offset:1024
	ds_read_b128 v[194:197], v187 offset:2048
	ds_read_b128 v[198:201], v187 offset:3072
	ds_read_b128 v[202:205], v187 offset:4096
	ds_read_b128 v[206:209], v187 offset:5120
	ds_read_b128 v[210:213], v187 offset:6144
	ds_read_b128 v[214:217], v187 offset:7168
	global_load_lds_dwordx4 v142, s[46:47]
	s_add_i32 m0, s61, 0xe000
	s_nop 0
	global_load_lds_dwordx4 v144, s[46:47]
	s_waitcnt vmcnt(8)
	s_waitcnt lgkmcnt(0)
	s_barrier
	v_mfma_f32_16x16x32_bf16 v[124:127], v[150:153], v[182:185], v[124:127]
	v_mfma_f32_16x16x32_bf16 v[120:123], v[158:161], v[182:185], v[120:123]
	v_mfma_f32_16x16x32_bf16 v[116:119], v[150:153], v[194:197], v[116:119]
	v_mfma_f32_16x16x32_bf16 v[112:115], v[158:161], v[194:197], v[112:115]
	v_mfma_f32_16x16x32_bf16 v[108:111], v[150:153], v[202:205], v[108:111]
	v_mfma_f32_16x16x32_bf16 v[104:107], v[158:161], v[202:205], v[104:107]
	v_mfma_f32_16x16x32_bf16 v[100:103], v[150:153], v[210:213], v[100:103]
	v_mfma_f32_16x16x32_bf16 v[96:99], v[158:161], v[210:213], v[96:99]
	v_mfma_f32_16x16x32_bf16 v[124:127], v[154:157], v[190:193], v[124:127]
	v_mfma_f32_16x16x32_bf16 v[120:123], v[162:165], v[190:193], v[120:123]
	v_mfma_f32_16x16x32_bf16 v[116:119], v[154:157], v[198:201], v[116:119]
	v_mfma_f32_16x16x32_bf16 v[112:115], v[162:165], v[198:201], v[112:115]
	v_mfma_f32_16x16x32_bf16 v[108:111], v[154:157], v[206:209], v[108:111]
	v_mfma_f32_16x16x32_bf16 v[104:107], v[162:165], v[206:209], v[104:107]
	v_mfma_f32_16x16x32_bf16 v[100:103], v[154:157], v[214:217], v[100:103]
	v_mfma_f32_16x16x32_bf16 v[96:99], v[162:165], v[214:217], v[96:99]
	v_mfma_f32_16x16x32_bf16 v[92:95], v[166:169], v[182:185], v[92:95]
	v_mfma_f32_16x16x32_bf16 v[88:91], v[174:177], v[182:185], v[88:91]
	v_mfma_f32_16x16x32_bf16 v[84:87], v[166:169], v[194:197], v[84:87]
	v_mfma_f32_16x16x32_bf16 v[80:83], v[174:177], v[194:197], v[80:83]
	v_mfma_f32_16x16x32_bf16 v[76:79], v[166:169], v[202:205], v[76:79]
	v_mfma_f32_16x16x32_bf16 v[72:75], v[174:177], v[202:205], v[72:75]
	v_mfma_f32_16x16x32_bf16 v[68:71], v[166:169], v[210:213], v[68:71]
	v_mfma_f32_16x16x32_bf16 v[64:67], v[174:177], v[210:213], v[64:67]
	v_mfma_f32_16x16x32_bf16 v[92:95], v[170:173], v[190:193], v[92:95]
	v_mfma_f32_16x16x32_bf16 v[88:91], v[178:181], v[190:193], v[88:91]
	v_mfma_f32_16x16x32_bf16 v[84:87], v[170:173], v[198:201], v[84:87]
	v_mfma_f32_16x16x32_bf16 v[80:83], v[178:181], v[198:201], v[80:83]
	v_mfma_f32_16x16x32_bf16 v[76:79], v[170:173], v[206:209], v[76:79]
	v_mfma_f32_16x16x32_bf16 v[72:75], v[178:181], v[206:209], v[72:75]
	v_mfma_f32_16x16x32_bf16 v[68:71], v[170:173], v[214:217], v[68:71]
	v_mfma_f32_16x16x32_bf16 v[64:67], v[178:181], v[214:217], v[64:67]
	s_barrier
	s_add_i32 s83, s67, s60
	v_lshl_add_u64 v[218:219], s[54:55], 0, v[130:131]
	s_mov_b32 m0, s83
	ds_read_b128 v[182:185], v187 offset:16384
	ds_read_b128 v[190:193], v187 offset:17408
	ds_read_b128 v[194:197], v187 offset:18432
	ds_read_b128 v[198:201], v187 offset:19456
	ds_read_b128 v[202:205], v187 offset:20480
	ds_read_b128 v[206:209], v187 offset:21504
	ds_read_b128 v[210:213], v187 offset:22528
	ds_read_b128 v[214:217], v187 offset:23552
	global_load_lds_dwordx4 v[218:219], off
	s_add_i32 m0, s83, 0x2000
	s_add_u32 s86, s54, 0x80000
	v_lshl_add_u64 v[220:221], s[54:55], 0, v[134:135]
	s_addc_u32 s87, s55, 0
	s_add_i32 s83, s68, s60
	global_load_lds_dwordx4 v[220:221], off
	s_mov_b32 m0, s83
	v_lshl_add_u64 v[224:225], s[56:57], 0, v[132:133]
	global_load_lds_dwordx4 v130, s[86:87]
	s_add_i32 m0, s83, 0x2000
	s_nop 0
	global_load_lds_dwordx4 v134, s[86:87]
	v_lshl_add_u64 v[222:223], s[56:57], 0, v[128:129]
	s_mov_b32 m0, s61
	s_nop 0
	global_load_lds_dwordx4 v[222:223], off
	s_mov_b32 m0, s62
	s_nop 0
	global_load_lds_dwordx4 v[224:225], off
	s_waitcnt vmcnt(8)
	s_waitcnt lgkmcnt(0)
	s_barrier
; #define PG8_STAGE(bufoff, gbase, voff) do { _Pragma("unroll") for (int _i = 0; _i < 2; ++_i) \
;         __builtin_amdgcn_global_load_lds((const unsigned*)((const char*)(gbase) + (voff)[_i]), (PG8_LAS unsigned*)(lds + (bufoff) + ldsw + _i * 8192), 16, 0, 0); } while (0)
; #define PG8_LDA(dst, b, h) do { _Pragma("unroll") for (int m = 0; m < 4; ++m) _Pragma("unroll") for (int k = 0; k < 2; ++k) dst[m][k] = *(const PG8_LAS bf16x8*)(lds + PG8_SA(b, h) + aoff + m * 2048 + k * 1024); } while (0)
; #define PG8_LDB(dst, b, h) do { _Pragma("unroll") for (int n = 0; n < 2; ++n) _Pragma("unroll") for (int k = 0; k < 2; ++k) dst[n][k] = *(const PG8_LAS bf16x8*)(lds + PG8_SB(b, h) + boff + n * 2048 + k * 1024); } while (0)
; #define PG8_MMA(ai, bj, At, Bt) do { __builtin_amdgcn_s_setprio(1); _Pragma("unroll") for (int m = 0; m < 4; ++m) _Pragma("unroll") for (int n = 0; n < 2; ++n) _Pragma("unroll") for (int k = 0; k < 2; ++k) \
;         acc[ai][bj][m][n] = __builtin_amdgcn_mfma_f32_16x16x32_bf16(Bt[n][k], At[m][k], acc[ai][bj][m][n], 0, 0, 0); __builtin_amdgcn_s_setprio(0); } while (0)
; #define PG8_WAIT_V(n) asm volatile("s_waitcnt vmcnt(" #n ")" ::: "memory")
; #define PG8_WAIT_L(n) asm volatile("s_waitcnt lgkmcnt(" #n ")" ::: "memory")
; #define PG8_BAR __builtin_amdgcn_s_barrier()
; #define PG8_SCHED __builtin_amdgcn_sched_barrier(0)
; template <class Epi, class Sched, bool ALIGN_EPI = false, bool SP2 = false>
; __device__ __forceinline__ void gemm_phase(PG8_LAS unsigned char* lds, const Gemm g, const Sched& S, const Epi& E) {
;     ...
;             PG8_WAIT_V(8); PG8_WAIT_L(0); PG8_BAR; PG8_MMA(1, 0, At, B0); PG8_MMA(1, 1, At, B1); PG8_BAR; PG8_SCHED;
;             PG8_LDB(B0, 1, 0); PG8_LDB(B1, 1, 1); PG8_SCHED; PG8_LDA(At, 1, 0); PG8_STAGE(PG8_SA(0, 1), a2 + hstep, voffA);
;             PG8_WAIT_V(8); PG8_WAIT_L(0); PG8_BAR; PG8_MMA(0, 0, At, B0); PG8_MMA(0, 1, At, B1); PG8_BAR; PG8_SCHED;
;             PG8_LDA(At, 1, 1); PG8_STAGE(PG8_SB(1, 0), b3, voffB); PG8_STAGE(PG8_SB(1, 1), b3 + hstep, voffB); PG8_STAGE(PG8_SA(1, 0), a3, voffA);
	v_mfma_f32_16x16x32_bf16 v[60:63], v[150:153], v[182:185], v[60:63]
	v_mfma_f32_16x16x32_bf16 v[56:59], v[158:161], v[182:185], v[56:59]
	v_mfma_f32_16x16x32_bf16 v[52:55], v[150:153], v[194:197], v[52:55]
	v_mfma_f32_16x16x32_bf16 v[48:51], v[158:161], v[194:197], v[48:51]
	v_mfma_f32_16x16x32_bf16 v[44:47], v[150:153], v[202:205], v[44:47]
	v_mfma_f32_16x16x32_bf16 v[40:43], v[158:161], v[202:205], v[40:43]
	v_mfma_f32_16x16x32_bf16 v[36:39], v[150:153], v[210:213], v[36:39]
	v_mfma_f32_16x16x32_bf16 v[32:35], v[158:161], v[210:213], v[32:35]
	v_mfma_f32_16x16x32_bf16 v[60:63], v[154:157], v[190:193], v[60:63]
	v_mfma_f32_16x16x32_bf16 v[56:59], v[162:165], v[190:193], v[56:59]
	v_mfma_f32_16x16x32_bf16 v[52:55], v[154:157], v[198:201], v[52:55]
	v_mfma_f32_16x16x32_bf16 v[48:51], v[162:165], v[198:201], v[48:51]
	v_mfma_f32_16x16x32_bf16 v[44:47], v[154:157], v[206:209], v[44:47]
	v_mfma_f32_16x16x32_bf16 v[40:43], v[162:165], v[206:209], v[40:43]
	v_mfma_f32_16x16x32_bf16 v[36:39], v[154:157], v[214:217], v[36:39]
	v_mfma_f32_16x16x32_bf16 v[32:35], v[162:165], v[214:217], v[32:35]
	v_mfma_f32_16x16x32_bf16 v[28:31], v[166:169], v[182:185], v[28:31]
	v_mfma_f32_16x16x32_bf16 v[24:27], v[174:177], v[182:185], v[24:27]
	v_mfma_f32_16x16x32_bf16 v[20:23], v[166:169], v[194:197], v[20:23]
	v_mfma_f32_16x16x32_bf16 v[16:19], v[174:177], v[194:197], v[16:19]
	v_mfma_f32_16x16x32_bf16 v[12:15], v[166:169], v[202:205], v[12:15]
	v_mfma_f32_16x16x32_bf16 v[8:11], v[174:177], v[202:205], v[8:11]
	v_mfma_f32_16x16x32_bf16 v[4:7], v[166:169], v[210:213], v[4:7]
	v_mfma_f32_16x16x32_bf16 v[0:3], v[174:177], v[210:213], v[0:3]
	v_mfma_f32_16x16x32_bf16 v[28:31], v[170:173], v[190:193], v[28:31]
	v_mfma_f32_16x16x32_bf16 v[24:27], v[178:181], v[190:193], v[24:27]
	v_mfma_f32_16x16x32_bf16 v[20:23], v[170:173], v[198:201], v[20:23]
	v_mfma_f32_16x16x32_bf16 v[16:19], v[178:181], v[198:201], v[16:19]
	v_mfma_f32_16x16x32_bf16 v[12:15], v[170:173], v[206:209], v[12:15]
	v_mfma_f32_16x16x32_bf16 v[8:11], v[178:181], v[206:209], v[8:11]
	v_mfma_f32_16x16x32_bf16 v[4:7], v[170:173], v[214:217], v[4:7]
	v_mfma_f32_16x16x32_bf16 v[0:3], v[178:181], v[214:217], v[0:3]
	s_barrier
	s_add_i32 s83, 0, 0x18000
	s_add_i32 s86, 0, 0x1c000
	v_add_u32_e32 v162, s83, v186
	v_add_u32_e32 v178, s86, v186
	ds_read_b128 v[150:153], v162
	ds_read_b128 v[154:157], v162 offset:1024
	ds_read_b128 v[158:161], v162 offset:2048
	ds_read_b128 v[162:165], v162 offset:3072
	ds_read_b128 v[166:169], v178
	ds_read_b128 v[170:173], v178 offset:1024
	ds_read_b128 v[174:177], v178 offset:2048
	ds_read_b128 v[178:181], v178 offset:3072
	s_add_u32 s56, s56, 0x80000
	s_addc_u32 s57, s57, 0
	s_mov_b32 m0, s63
	ds_read_b128 v[182:185], v187 offset:32768
	ds_read_b128 v[190:193], v187 offset:33792
	ds_read_b128 v[194:197], v187 offset:34816
	ds_read_b128 v[198:201], v187 offset:35840
	ds_read_b128 v[202:205], v187 offset:36864
	ds_read_b128 v[206:209], v187 offset:37888
	ds_read_b128 v[210:213], v187 offset:38912
	ds_read_b128 v[214:217], v187 offset:39936
	global_load_lds_dwordx4 v128, s[56:57]
	s_mov_b32 m0, s64
	s_nop 0
	global_load_lds_dwordx4 v132, s[56:57]
	s_waitcnt vmcnt(8)
	s_waitcnt lgkmcnt(0)
	s_barrier
	v_mfma_f32_16x16x32_bf16 v[124:127], v[150:153], v[182:185], v[124:127]
	v_mfma_f32_16x16x32_bf16 v[120:123], v[158:161], v[182:185], v[120:123]
	v_mfma_f32_16x16x32_bf16 v[116:119], v[150:153], v[194:197], v[116:119]
	v_mfma_f32_16x16x32_bf16 v[112:115], v[158:161], v[194:197], v[112:115]
	v_mfma_f32_16x16x32_bf16 v[108:111], v[150:153], v[202:205], v[108:111]
	v_mfma_f32_16x16x32_bf16 v[104:107], v[158:161], v[202:205], v[104:107]
	v_mfma_f32_16x16x32_bf16 v[100:103], v[150:153], v[210:213], v[100:103]
	v_mfma_f32_16x16x32_bf16 v[96:99], v[158:161], v[210:213], v[96:99]
	v_mfma_f32_16x16x32_bf16 v[124:127], v[154:157], v[190:193], v[124:127]
	v_mfma_f32_16x16x32_bf16 v[120:123], v[162:165], v[190:193], v[120:123]
	v_mfma_f32_16x16x32_bf16 v[116:119], v[154:157], v[198:201], v[116:119]
	v_mfma_f32_16x16x32_bf16 v[112:115], v[162:165], v[198:201], v[112:115]
	v_mfma_f32_16x16x32_bf16 v[108:111], v[154:157], v[206:209], v[108:111]
	v_mfma_f32_16x16x32_bf16 v[104:107], v[162:165], v[206:209], v[104:107]
	v_mfma_f32_16x16x32_bf16 v[100:103], v[154:157], v[214:217], v[100:103]
	v_mfma_f32_16x16x32_bf16 v[96:99], v[162:165], v[214:217], v[96:99]
	v_mfma_f32_16x16x32_bf16 v[92:95], v[166:169], v[182:185], v[92:95]
	v_mfma_f32_16x16x32_bf16 v[88:91], v[174:177], v[182:185], v[88:91]
	v_mfma_f32_16x16x32_bf16 v[84:87], v[166:169], v[194:197], v[84:87]
	v_mfma_f32_16x16x32_bf16 v[80:83], v[174:177], v[194:197], v[80:83]
	v_mfma_f32_16x16x32_bf16 v[76:79], v[166:169], v[202:205], v[76:79]
	v_mfma_f32_16x16x32_bf16 v[72:75], v[174:177], v[202:205], v[72:75]
	v_mfma_f32_16x16x32_bf16 v[68:71], v[166:169], v[210:213], v[68:71]
	v_mfma_f32_16x16x32_bf16 v[64:67], v[174:177], v[210:213], v[64:67]
	v_mfma_f32_16x16x32_bf16 v[92:95], v[170:173], v[190:193], v[92:95]
	v_mfma_f32_16x16x32_bf16 v[88:91], v[178:181], v[190:193], v[88:91]
	v_mfma_f32_16x16x32_bf16 v[84:87], v[170:173], v[198:201], v[84:87]
	v_mfma_f32_16x16x32_bf16 v[80:83], v[178:181], v[198:201], v[80:83]
	v_mfma_f32_16x16x32_bf16 v[76:79], v[170:173], v[206:209], v[76:79]
	v_mfma_f32_16x16x32_bf16 v[72:75], v[178:181], v[206:209], v[72:75]
	v_mfma_f32_16x16x32_bf16 v[68:71], v[170:173], v[214:217], v[68:71]
	v_mfma_f32_16x16x32_bf16 v[64:67], v[178:181], v[214:217], v[64:67]
	s_barrier
; #define PG8_STAGE(bufoff, gbase, voff) do { _Pragma("unroll") for (int _i = 0; _i < 2; ++_i) \
;         __builtin_amdgcn_global_load_lds((const unsigned*)((const char*)(gbase) + (voff)[_i]), (PG8_LAS unsigned*)(lds + (bufoff) + ldsw + _i * 8192), 16, 0, 0); } while (0)
; #define PG8_LDA(dst, b, h) do { _Pragma("unroll") for (int m = 0; m < 4; ++m) _Pragma("unroll") for (int k = 0; k < 2; ++k) dst[m][k] = *(const PG8_LAS bf16x8*)(lds + PG8_SA(b, h) + aoff + m * 2048 + k * 1024); } while (0)
; #define PG8_MMA(ai, bj, At, Bt) do { __builtin_amdgcn_s_setprio(1); _Pragma("unroll") for (int m = 0; m < 4; ++m) _Pragma("unroll") for (int n = 0; n < 2; ++n) _Pragma("unroll") for (int k = 0; k < 2; ++k) \
;         acc[ai][bj][m][n] = __builtin_amdgcn_mfma_f32_16x16x32_bf16(Bt[n][k], At[m][k], acc[ai][bj][m][n], 0, 0, 0); __builtin_amdgcn_s_setprio(0); } while (0)
; #define PG8_WAIT_V(n) asm volatile("s_waitcnt vmcnt(" #n ")" ::: "memory")
; #define PG8_WAIT_L(n) asm volatile("s_waitcnt lgkmcnt(" #n ")" ::: "memory")
; #define PG8_BAR __builtin_amdgcn_s_barrier()
; #define PG8_SCHED __builtin_amdgcn_sched_barrier(0)
; template <class Epi, class Sched, bool ALIGN_EPI = false, bool SP2 = false>
; __device__ __forceinline__ void gemm_phase(PG8_LAS unsigned char* lds, const Gemm g, const Sched& S, const Epi& E) {
;     ...
;             PG8_LDA(At, 1, 1); PG8_STAGE(PG8_SB(1, 0), b3, voffB); PG8_STAGE(PG8_SB(1, 1), b3 + hstep, voffB); PG8_STAGE(PG8_SA(1, 0), a3, voffA);
;             PG8_WAIT_V(8); PG8_WAIT_L(0); PG8_BAR; PG8_MMA(1, 0, At, B0); PG8_MMA(1, 1, At, B1); PG8_BAR; PG8_SCHED;
;     ...
;         if constexpr (ALIGN_EPI) { if (wr == 0) PG8_BAR; }
	s_add_i32 s56, s83, s60
	v_lshl_add_u64 v[218:219], v[218:219], 0, s[14:15]
	s_mov_b32 m0, s56
	ds_read_b128 v[182:185], v187 offset:49152
	ds_read_b128 v[190:193], v187 offset:50176
	ds_read_b128 v[194:197], v187 offset:51200
	ds_read_b128 v[198:201], v187 offset:52224
	ds_read_b128 v[202:205], v187 offset:53248
	ds_read_b128 v[206:209], v187 offset:54272
	ds_read_b128 v[210:213], v187 offset:55296
	ds_read_b128 v[214:217], v187 offset:56320
	global_load_lds_dwordx4 v[218:219], off
	s_add_i32 m0, s56, 0x2000
	s_add_u32 s54, s54, 0x80080
	v_lshl_add_u64 v[218:219], v[220:221], 0, s[14:15]
	s_addc_u32 s55, s55, 0
	s_add_i32 s56, s86, s60
	global_load_lds_dwordx4 v[218:219], off
	s_mov_b32 m0, s56
	s_nop 0
	global_load_lds_dwordx4 v130, s[54:55]
	s_add_i32 m0, s56, 0x2000
	s_nop 0
	global_load_lds_dwordx4 v134, s[54:55]
	v_lshl_add_u64 v[218:219], v[222:223], 0, s[14:15]
	s_mov_b32 m0, s65
	s_nop 0
	global_load_lds_dwordx4 v[218:219], off
	v_lshl_add_u64 v[218:219], v[224:225], 0, s[14:15]
	s_mov_b32 m0, s66
	s_nop 0
	global_load_lds_dwordx4 v[218:219], off
	s_waitcnt vmcnt(8)
	s_waitcnt lgkmcnt(0)
	s_barrier
	v_mfma_f32_16x16x32_bf16 v[60:63], v[150:153], v[182:185], v[60:63]
	v_mfma_f32_16x16x32_bf16 v[56:59], v[158:161], v[182:185], v[56:59]
	v_mfma_f32_16x16x32_bf16 v[52:55], v[150:153], v[194:197], v[52:55]
	v_mfma_f32_16x16x32_bf16 v[48:51], v[158:161], v[194:197], v[48:51]
	v_mfma_f32_16x16x32_bf16 v[44:47], v[150:153], v[202:205], v[44:47]
	v_mfma_f32_16x16x32_bf16 v[40:43], v[158:161], v[202:205], v[40:43]
	v_mfma_f32_16x16x32_bf16 v[36:39], v[150:153], v[210:213], v[36:39]
	v_mfma_f32_16x16x32_bf16 v[32:35], v[158:161], v[210:213], v[32:35]
	v_mfma_f32_16x16x32_bf16 v[60:63], v[154:157], v[190:193], v[60:63]
	v_mfma_f32_16x16x32_bf16 v[56:59], v[162:165], v[190:193], v[56:59]
	v_mfma_f32_16x16x32_bf16 v[52:55], v[154:157], v[198:201], v[52:55]
	v_mfma_f32_16x16x32_bf16 v[48:51], v[162:165], v[198:201], v[48:51]
	v_mfma_f32_16x16x32_bf16 v[44:47], v[154:157], v[206:209], v[44:47]
	v_mfma_f32_16x16x32_bf16 v[40:43], v[162:165], v[206:209], v[40:43]
	v_mfma_f32_16x16x32_bf16 v[36:39], v[154:157], v[214:217], v[36:39]
	v_mfma_f32_16x16x32_bf16 v[32:35], v[162:165], v[214:217], v[32:35]
	v_mfma_f32_16x16x32_bf16 v[28:31], v[166:169], v[182:185], v[28:31]
	v_mfma_f32_16x16x32_bf16 v[24:27], v[174:177], v[182:185], v[24:27]
	v_mfma_f32_16x16x32_bf16 v[20:23], v[166:169], v[194:197], v[20:23]
	v_mfma_f32_16x16x32_bf16 v[16:19], v[174:177], v[194:197], v[16:19]
	v_mfma_f32_16x16x32_bf16 v[12:15], v[166:169], v[202:205], v[12:15]
	v_mfma_f32_16x16x32_bf16 v[8:11], v[174:177], v[202:205], v[8:11]
	v_mfma_f32_16x16x32_bf16 v[4:7], v[166:169], v[210:213], v[4:7]
	v_mfma_f32_16x16x32_bf16 v[0:3], v[174:177], v[210:213], v[0:3]
	v_mfma_f32_16x16x32_bf16 v[28:31], v[170:173], v[190:193], v[28:31]
	v_mfma_f32_16x16x32_bf16 v[24:27], v[178:181], v[190:193], v[24:27]
	v_mfma_f32_16x16x32_bf16 v[20:23], v[170:173], v[198:201], v[20:23]
	v_mfma_f32_16x16x32_bf16 v[16:19], v[178:181], v[198:201], v[16:19]
	v_mfma_f32_16x16x32_bf16 v[12:15], v[170:173], v[206:209], v[12:15]
	v_mfma_f32_16x16x32_bf16 v[8:11], v[178:181], v[206:209], v[8:11]
	v_mfma_f32_16x16x32_bf16 v[4:7], v[170:173], v[214:217], v[4:7]
	v_mfma_f32_16x16x32_bf16 v[0:3], v[178:181], v[214:217], v[0:3]
	s_barrier
	s_add_i32 s82, s82, 2
	s_add_u32 s46, s46, 0x100
	s_addc_u32 s47, s47, 0
	s_add_u32 s80, s80, 0x100
	s_addc_u32 s81, s81, 0
	s_cmp_gt_u32 s82, 13
	s_cbranch_scc0 .LBB0_795
	s_setprio 0
	s_and_b64 vcc, exec, s[16:17]
	s_cbranch_vccz .LBB0_798
	s_barrier

;     __host__ __device__ bool next(int i, Unit& u) const { const long L = (long)i * G + c; if (L >= nwg) return false; return unit_of((int)L, u); }
;     __host__ __device__ bool next(int i, Unit& u) const { const int L = i == 0 ? l0 : (i == 1 ? l1 : (i == 2 ? l2 : -1)); if (L < 0 || L >= s.nwg) return false; return s.unit_of(L, u); }
;     __host__ __device__ bool next(int i, Unit& u) const { const bool ok = s.next(i >> 1, u); u.kh = i & 1; return ok; }
; #define PG8_STAGE(bufoff, gbase, voff) do { _Pragma("unroll") for (int _i = 0; _i < 2; ++_i) \
;         __builtin_amdgcn_global_load_lds((const unsigned*)((const char*)(gbase) + (voff)[_i]), (PG8_LAS unsigned*)(lds + (bufoff) + ldsw + _i * 8192), 16, 0, 0); } while (0)
; #define PG8_WAIT_V(n) asm volatile("s_waitcnt vmcnt(" #n ")" ::: "memory")
; #define PG8_BAR __builtin_amdgcn_s_barrier()
; template <class Epi, class Sched, bool ALIGN_EPI = false, bool SP2 = false>
; __device__ __forceinline__ void gemm_phase(PG8_LAS unsigned char* lds, const Gemm g, const Sched& S, const Epi& E) {
;     ...
;         const bool has_next = S.next(ui + 1, nxt);
;         const char* nA = has_next ? (const char*)g.A + (size_t)nxt.pm * tstep + nxt.kh * khb : cA; const char* nB = has_next ? (const char*)g.Bt + (size_t)nxt.pn * tstep + nxt.kh * khb : cB;
;         for (int t = 0; t < nt; t += 2) {
;             const bool last = (t == nt - 2);
;             const char* a1 = cA + (size_t)(t + 1) * kstep;
;             const char* a2 = last ? nA : cA + (size_t)(t + 2) * kstep; const char* b2 = last ? nB : cB + (size_t)(t + 2) * kstep;
;             const char* a3 = a2 + kstep; const char* b3 = b2 + kstep;
;             if (last && has_next) S.a_ready(nxt);
;             if constexpr (SP2) {
;             PG8_LDB(B0, 0, 0); PG8_LDB(B1, 0, 1); PG8_SCHED; PG8_LDA(At, 0, 0); PG8_STAGE(PG8_SA(1, 1), a1 + hstep, voffA);
;             PG8_WAIT_V(8); PG8_WAIT_L(0); PG8_BAR; PG8_MMA(0, 0, At, B0); PG8_MMA(0, 1, At, B1); PG8_BAR; PG8_SCHED;
;     ...
;         if (!(Epi::KSPLIT && cur.kh == 0))
; #pragma unroll
;         for (int a = 0; a < 2; ++a)
; #pragma unroll
;             for (int b = 0; b < 2; ++b)
; #pragma unroll
;                 for (int m = 0; m < 4; ++m)
; #pragma unroll
;                     for (int n = 0; n < 2; ++n) acc[a][b][m][n] = (f32x4){0.f, 0.f, 0.f, 0.f};
;         cur = nxt; cA = nA; cB = nB; ++ui;
.LBB0_881:
	s_ashr_i32 s23, s22, 31
	s_lshl_b64 s[24:25], s[22:23], 19
	s_add_u32 s24, s38, s24
	s_addc_u32 s25, s39, s25
	s_and_b64 s[26:27], s[4:5], exec
	s_cselect_b32 s23, s25, s31
	s_cselect_b32 s29, s24, s30
	s_ashr_i32 s21, s20, 31
	s_lshl_b64 s[26:27], s[20:21], 19
	s_add_u32 s26, s40, s26
	s_addc_u32 s27, s41, s27
	s_and_b64 s[36:37], s[4:5], exec
	s_cselect_b32 s21, s27, s35
	s_cselect_b32 s58, s26, s34
	s_add_u32 s30, s30, 0x40080
	s_addc_u32 s31, s31, 0
	s_add_u32 s59, s34, 0x100
	v_mov_b32_e32 v0, 0
	s_addc_u32 s60, s35, 0
	s_mov_b32 s61, -2
	s_waitcnt lgkmcnt(0)
	v_mov_b32_e32 v1, v0
	v_mov_b32_e32 v2, v0
	v_mov_b32_e32 v3, v0
	v_mov_b32_e32 v4, v0
	v_mov_b32_e32 v5, v0
	v_mov_b32_e32 v6, v0
	v_mov_b32_e32 v7, v0
	v_mov_b32_e32 v16, v0
	v_mov_b32_e32 v17, v0
	v_mov_b32_e32 v18, v0
	v_mov_b32_e32 v19, v0
	v_mov_b32_e32 v20, v0
	v_mov_b32_e32 v21, v0
	v_mov_b32_e32 v22, v0
	v_mov_b32_e32 v23, v0
	v_mov_b32_e32 v32, v0
	v_mov_b32_e32 v33, v0
	v_mov_b32_e32 v34, v0
	v_mov_b32_e32 v35, v0
	v_mov_b32_e32 v36, v0
	v_mov_b32_e32 v37, v0
	v_mov_b32_e32 v38, v0
	v_mov_b32_e32 v39, v0
	v_mov_b32_e32 v48, v0
	v_mov_b32_e32 v49, v0
	v_mov_b32_e32 v50, v0
	v_mov_b32_e32 v51, v0
	v_mov_b32_e32 v52, v0
	v_mov_b32_e32 v53, v0
	v_mov_b32_e32 v54, v0
	v_mov_b32_e32 v55, v0
	v_mov_b32_e32 v8, v0
	v_mov_b32_e32 v9, v0
	v_mov_b32_e32 v10, v0
	v_mov_b32_e32 v11, v0
	v_mov_b32_e32 v12, v0
	v_mov_b32_e32 v13, v0
	v_mov_b32_e32 v14, v0
	v_mov_b32_e32 v15, v0
	v_mov_b32_e32 v24, v0
	v_mov_b32_e32 v25, v0
	v_mov_b32_e32 v26, v0
	v_mov_b32_e32 v27, v0
	v_mov_b32_e32 v28, v0
	v_mov_b32_e32 v29, v0
	v_mov_b32_e32 v30, v0
	v_mov_b32_e32 v31, v0
	v_mov_b32_e32 v40, v0
	v_mov_b32_e32 v41, v0
	v_mov_b32_e32 v42, v0
	v_mov_b32_e32 v43, v0
	v_mov_b32_e32 v44, v0
	v_mov_b32_e32 v45, v0
	v_mov_b32_e32 v46, v0
	v_mov_b32_e32 v47, v0
	v_mov_b32_e32 v56, v0
	v_mov_b32_e32 v57, v0
	v_mov_b32_e32 v58, v0
	v_mov_b32_e32 v59, v0
	v_mov_b32_e32 v60, v0
	v_mov_b32_e32 v61, v0
	v_mov_b32_e32 v62, v0
	v_mov_b32_e32 v63, v0
	v_mov_b32_e32 v64, v0
	v_mov_b32_e32 v65, v0
	v_mov_b32_e32 v66, v0
	v_mov_b32_e32 v67, v0
	v_mov_b32_e32 v68, v0
	v_mov_b32_e32 v69, v0
	v_mov_b32_e32 v70, v0
	v_mov_b32_e32 v71, v0
	v_mov_b32_e32 v80, v0
	v_mov_b32_e32 v81, v0
	v_mov_b32_e32 v82, v0
	v_mov_b32_e32 v83, v0
	v_mov_b32_e32 v84, v0
	v_mov_b32_e32 v85, v0
	v_mov_b32_e32 v86, v0
	v_mov_b32_e32 v87, v0
	v_mov_b32_e32 v96, v0
	v_mov_b32_e32 v97, v0
	v_mov_b32_e32 v98, v0
	v_mov_b32_e32 v99, v0
	v_mov_b32_e32 v100, v0
	v_mov_b32_e32 v101, v0
	v_mov_b32_e32 v102, v0
	v_mov_b32_e32 v103, v0
	v_mov_b32_e32 v112, v0
	v_mov_b32_e32 v113, v0
	v_mov_b32_e32 v114, v0
	v_mov_b32_e32 v115, v0
	v_mov_b32_e32 v116, v0
	v_mov_b32_e32 v117, v0
	v_mov_b32_e32 v118, v0
	v_mov_b32_e32 v119, v0
	v_mov_b32_e32 v72, v0
	v_mov_b32_e32 v73, v0
	v_mov_b32_e32 v74, v0
	v_mov_b32_e32 v75, v0
	v_mov_b32_e32 v76, v0
	v_mov_b32_e32 v77, v0
	v_mov_b32_e32 v78, v0
	v_mov_b32_e32 v79, v0
	v_mov_b32_e32 v88, v0
	v_mov_b32_e32 v89, v0
	v_mov_b32_e32 v90, v0
	v_mov_b32_e32 v91, v0
	v_mov_b32_e32 v92, v0
	v_mov_b32_e32 v93, v0
	v_mov_b32_e32 v94, v0
	v_mov_b32_e32 v95, v0
	v_mov_b32_e32 v104, v0
	v_mov_b32_e32 v105, v0
	v_mov_b32_e32 v106, v0
	v_mov_b32_e32 v107, v0
	v_mov_b32_e32 v108, v0
	v_mov_b32_e32 v109, v0
	v_mov_b32_e32 v110, v0
	v_mov_b32_e32 v111, v0
	v_mov_b32_e32 v120, v0
	v_mov_b32_e32 v121, v0
	v_mov_b32_e32 v122, v0
	v_mov_b32_e32 v123, v0
	v_mov_b32_e32 v124, v0
	v_mov_b32_e32 v125, v0
	v_mov_b32_e32 v126, v0
	v_mov_b32_e32 v127, v0
	v_readfirstlane_b32 s100, v188
	s_bitcmp1_b32 s100, 8
	s_cbranch_scc0 .Lmy_sprio_882
	s_setprio 1
.Lmy_sprio_882:
.LBB0_882:
	ds_read_b128 v[128:131], v173
	ds_read_b128 v[132:135], v173 offset:1024
	ds_read_b128 v[136:139], v173 offset:2048
	ds_read_b128 v[140:143], v173 offset:3072
	ds_read_b128 v[164:167], v174
	ds_read_b128 v[168:171], v174 offset:1024
	ds_read_b128 v[178:181], v174 offset:2048
	ds_read_b128 v[182:185], v174 offset:3072
	s_add_u32 s34, s30, 0xfffc0080
	s_addc_u32 s35, s31, -1
	s_cmp_eq_u32 s61, 12
	s_cselect_b32 s37, s23, s35
	s_cselect_b32 s36, s29, s34
	s_cselect_b32 s35, s21, s60
	s_cselect_b32 s34, s58, s59
	s_add_i32 m0, s43, 0xc000
	ds_read_b128 v[190:193], v175
	ds_read_b128 v[194:197], v175 offset:1024
	ds_read_b128 v[198:201], v175 offset:2048
	ds_read_b128 v[202:205], v175 offset:3072
	ds_read_b128 v[206:209], v175 offset:4096
	ds_read_b128 v[210:213], v175 offset:5120
	ds_read_b128 v[214:217], v175 offset:6144
	ds_read_b128 v[218:221], v175 offset:7168
	global_load_lds_dwordx4 v156, s[30:31]
	s_add_i32 m0, s43, 0xe000
	s_nop 0
	global_load_lds_dwordx4 v158, s[30:31]
	s_waitcnt vmcnt(8)
	s_waitcnt lgkmcnt(0)
	s_barrier
; #define PG8_STAGE(bufoff, gbase, voff) do { _Pragma("unroll") for (int _i = 0; _i < 2; ++_i) \
;         __builtin_amdgcn_global_load_lds((const unsigned*)((const char*)(gbase) + (voff)[_i]), (PG8_LAS unsigned*)(lds + (bufoff) + ldsw + _i * 8192), 16, 0, 0); } while (0)
; #define PG8_LDA(dst, b, h) do { _Pragma("unroll") for (int m = 0; m < 4; ++m) _Pragma("unroll") for (int k = 0; k < 2; ++k) dst[m][k] = *(const PG8_LAS bf16x8*)(lds + PG8_SA(b, h) + aoff + m * 2048 + k * 1024); } while (0)
; #define PG8_MMA(ai, bj, At, Bt) do { __builtin_amdgcn_s_setprio(1); _Pragma("unroll") for (int m = 0; m < 4; ++m) _Pragma("unroll") for (int n = 0; n < 2; ++n) _Pragma("unroll") for (int k = 0; k < 2; ++k) \
;         acc[ai][bj][m][n] = __builtin_amdgcn_mfma_f32_16x16x32_bf16(Bt[n][k], At[m][k], acc[ai][bj][m][n], 0, 0, 0); __builtin_amdgcn_s_setprio(0); } while (0)
; #define PG8_WAIT_V(n) asm volatile("s_waitcnt vmcnt(" #n ")" ::: "memory")
; #define PG8_WAIT_L(n) asm volatile("s_waitcnt lgkmcnt(" #n ")" ::: "memory")
; #define PG8_BAR __builtin_amdgcn_s_barrier()
; #define PG8_SCHED __builtin_amdgcn_sched_barrier(0)
; template <class Epi, class Sched, bool ALIGN_EPI = false, bool SP2 = false>
; __device__ __forceinline__ void gemm_phase(PG8_LAS unsigned char* lds, const Gemm g, const Sched& S, const Epi& E) {
;     ...
;             PG8_WAIT_V(8); PG8_WAIT_L(0); PG8_BAR; PG8_MMA(0, 0, At, B0); PG8_MMA(0, 1, At, B1); PG8_BAR; PG8_SCHED;
;             PG8_LDA(At, 0, 1); PG8_STAGE(PG8_SB(0, 0), b2, voffB); PG8_STAGE(PG8_SB(0, 1), b2 + hstep, voffB); PG8_STAGE(PG8_SA(0, 0), a2, voffA);
;             PG8_WAIT_V(8); PG8_WAIT_L(0); PG8_BAR; PG8_MMA(1, 0, At, B0); PG8_MMA(1, 1, At, B1); PG8_BAR; PG8_SCHED;
	v_mfma_f32_16x16x32_bf16 v[124:127], v[128:131], v[190:193], v[124:127]
	v_mfma_f32_16x16x32_bf16 v[120:123], v[136:139], v[190:193], v[120:123]
	v_mfma_f32_16x16x32_bf16 v[108:111], v[128:131], v[198:201], v[108:111]
	v_mfma_f32_16x16x32_bf16 v[104:107], v[136:139], v[198:201], v[104:107]
	v_mfma_f32_16x16x32_bf16 v[92:95], v[128:131], v[206:209], v[92:95]
	v_mfma_f32_16x16x32_bf16 v[88:91], v[136:139], v[206:209], v[88:91]
	v_mfma_f32_16x16x32_bf16 v[76:79], v[128:131], v[214:217], v[76:79]
	v_mfma_f32_16x16x32_bf16 v[72:75], v[136:139], v[214:217], v[72:75]
	v_mfma_f32_16x16x32_bf16 v[124:127], v[132:135], v[194:197], v[124:127]
	v_mfma_f32_16x16x32_bf16 v[120:123], v[140:143], v[194:197], v[120:123]
	v_mfma_f32_16x16x32_bf16 v[108:111], v[132:135], v[202:205], v[108:111]
	v_mfma_f32_16x16x32_bf16 v[104:107], v[140:143], v[202:205], v[104:107]
	v_mfma_f32_16x16x32_bf16 v[92:95], v[132:135], v[210:213], v[92:95]
	v_mfma_f32_16x16x32_bf16 v[88:91], v[140:143], v[210:213], v[88:91]
	v_mfma_f32_16x16x32_bf16 v[76:79], v[132:135], v[218:221], v[76:79]
	v_mfma_f32_16x16x32_bf16 v[72:75], v[140:143], v[218:221], v[72:75]
	v_mfma_f32_16x16x32_bf16 v[116:119], v[164:167], v[190:193], v[116:119]
	v_mfma_f32_16x16x32_bf16 v[112:115], v[178:181], v[190:193], v[112:115]
	v_mfma_f32_16x16x32_bf16 v[100:103], v[164:167], v[198:201], v[100:103]
	v_mfma_f32_16x16x32_bf16 v[96:99], v[178:181], v[198:201], v[96:99]
	v_mfma_f32_16x16x32_bf16 v[84:87], v[164:167], v[206:209], v[84:87]
	v_mfma_f32_16x16x32_bf16 v[80:83], v[178:181], v[206:209], v[80:83]
	v_mfma_f32_16x16x32_bf16 v[68:71], v[164:167], v[214:217], v[68:71]
	v_mfma_f32_16x16x32_bf16 v[64:67], v[178:181], v[214:217], v[64:67]
	v_mfma_f32_16x16x32_bf16 v[116:119], v[168:171], v[194:197], v[116:119]
	v_mfma_f32_16x16x32_bf16 v[112:115], v[182:185], v[194:197], v[112:115]
	v_mfma_f32_16x16x32_bf16 v[100:103], v[168:171], v[202:205], v[100:103]
	v_mfma_f32_16x16x32_bf16 v[96:99], v[182:185], v[202:205], v[96:99]
	v_mfma_f32_16x16x32_bf16 v[84:87], v[168:171], v[210:213], v[84:87]
	v_mfma_f32_16x16x32_bf16 v[80:83], v[182:185], v[210:213], v[80:83]
	v_mfma_f32_16x16x32_bf16 v[68:71], v[168:171], v[218:221], v[68:71]
	v_mfma_f32_16x16x32_bf16 v[64:67], v[182:185], v[218:221], v[64:67]
	s_barrier
	s_add_i32 s62, s55, s42
	v_lshl_add_u64 v[186:187], s[34:35], 0, v[146:147]
	s_mov_b32 m0, s62
	ds_read_b128 v[190:193], v175 offset:16384
	ds_read_b128 v[194:197], v175 offset:17408
	ds_read_b128 v[198:201], v175 offset:18432
	ds_read_b128 v[202:205], v175 offset:19456
	ds_read_b128 v[206:209], v175 offset:20480
	ds_read_b128 v[210:213], v175 offset:21504
	ds_read_b128 v[214:217], v175 offset:22528
	ds_read_b128 v[218:221], v175 offset:23552
	global_load_lds_dwordx4 v[186:187], off
	s_add_i32 m0, s62, 0x2000
	s_add_u32 s62, s34, 0x40000
	v_lshl_add_u64 v[222:223], s[34:35], 0, v[150:151]
	s_addc_u32 s63, s35, 0
	s_add_i32 s64, s56, s42
	global_load_lds_dwordx4 v[222:223], off
	s_mov_b32 m0, s64
	v_lshl_add_u64 v[226:227], s[36:37], 0, v[148:149]
	global_load_lds_dwordx4 v146, s[62:63]
	s_add_i32 m0, s64, 0x2000
	s_nop 0
	global_load_lds_dwordx4 v150, s[62:63]
	v_lshl_add_u64 v[224:225], s[36:37], 0, v[144:145]
	s_mov_b32 m0, s43
	s_nop 0
	global_load_lds_dwordx4 v[224:225], off
	s_mov_b32 m0, s44
	s_nop 0
	global_load_lds_dwordx4 v[226:227], off
	s_waitcnt vmcnt(8)
	s_waitcnt lgkmcnt(0)
	s_barrier
	v_mfma_f32_16x16x32_bf16 v[60:63], v[128:131], v[190:193], v[60:63]
	v_mfma_f32_16x16x32_bf16 v[56:59], v[136:139], v[190:193], v[56:59]
	v_mfma_f32_16x16x32_bf16 v[44:47], v[128:131], v[198:201], v[44:47]
	v_mfma_f32_16x16x32_bf16 v[40:43], v[136:139], v[198:201], v[40:43]
	v_mfma_f32_16x16x32_bf16 v[28:31], v[128:131], v[206:209], v[28:31]
	v_mfma_f32_16x16x32_bf16 v[24:27], v[136:139], v[206:209], v[24:27]
	v_mfma_f32_16x16x32_bf16 v[12:15], v[128:131], v[214:217], v[12:15]
	v_mfma_f32_16x16x32_bf16 v[8:11], v[136:139], v[214:217], v[8:11]
	v_mfma_f32_16x16x32_bf16 v[60:63], v[132:135], v[194:197], v[60:63]
	v_mfma_f32_16x16x32_bf16 v[56:59], v[140:143], v[194:197], v[56:59]
	v_mfma_f32_16x16x32_bf16 v[44:47], v[132:135], v[202:205], v[44:47]
	v_mfma_f32_16x16x32_bf16 v[40:43], v[140:143], v[202:205], v[40:43]
	v_mfma_f32_16x16x32_bf16 v[28:31], v[132:135], v[210:213], v[28:31]
	v_mfma_f32_16x16x32_bf16 v[24:27], v[140:143], v[210:213], v[24:27]
	v_mfma_f32_16x16x32_bf16 v[12:15], v[132:135], v[218:221], v[12:15]
	v_mfma_f32_16x16x32_bf16 v[8:11], v[140:143], v[218:221], v[8:11]
	v_mfma_f32_16x16x32_bf16 v[52:55], v[164:167], v[190:193], v[52:55]
	v_mfma_f32_16x16x32_bf16 v[48:51], v[178:181], v[190:193], v[48:51]
	v_mfma_f32_16x16x32_bf16 v[36:39], v[164:167], v[198:201], v[36:39]
	v_mfma_f32_16x16x32_bf16 v[32:35], v[178:181], v[198:201], v[32:35]
	v_mfma_f32_16x16x32_bf16 v[20:23], v[164:167], v[206:209], v[20:23]
	v_mfma_f32_16x16x32_bf16 v[16:19], v[178:181], v[206:209], v[16:19]
	v_mfma_f32_16x16x32_bf16 v[4:7], v[164:167], v[214:217], v[4:7]
	v_mfma_f32_16x16x32_bf16 v[0:3], v[178:181], v[214:217], v[0:3]
	v_mfma_f32_16x16x32_bf16 v[52:55], v[168:171], v[194:197], v[52:55]
	v_mfma_f32_16x16x32_bf16 v[48:51], v[182:185], v[194:197], v[48:51]
	v_mfma_f32_16x16x32_bf16 v[36:39], v[168:171], v[202:205], v[36:39]
	v_mfma_f32_16x16x32_bf16 v[32:35], v[182:185], v[202:205], v[32:35]
	v_mfma_f32_16x16x32_bf16 v[20:23], v[168:171], v[210:213], v[20:23]
	v_mfma_f32_16x16x32_bf16 v[16:19], v[182:185], v[210:213], v[16:19]
	v_mfma_f32_16x16x32_bf16 v[4:7], v[168:171], v[218:221], v[4:7]
	v_mfma_f32_16x16x32_bf16 v[0:3], v[182:185], v[218:221], v[0:3]
	s_barrier
; #define PG8_STAGE(bufoff, gbase, voff) do { _Pragma("unroll") for (int _i = 0; _i < 2; ++_i) \
;         __builtin_amdgcn_global_load_lds((const unsigned*)((const char*)(gbase) + (voff)[_i]), (PG8_LAS unsigned*)(lds + (bufoff) + ldsw + _i * 8192), 16, 0, 0); } while (0)
; #define PG8_LDA(dst, b, h) do { _Pragma("unroll") for (int m = 0; m < 4; ++m) _Pragma("unroll") for (int k = 0; k < 2; ++k) dst[m][k] = *(const PG8_LAS bf16x8*)(lds + PG8_SA(b, h) + aoff + m * 2048 + k * 1024); } while (0)
; #define PG8_LDB(dst, b, h) do { _Pragma("unroll") for (int n = 0; n < 2; ++n) _Pragma("unroll") for (int k = 0; k < 2; ++k) dst[n][k] = *(const PG8_LAS bf16x8*)(lds + PG8_SB(b, h) + boff + n * 2048 + k * 1024); } while (0)
; #define PG8_MMA(ai, bj, At, Bt) do { __builtin_amdgcn_s_setprio(1); _Pragma("unroll") for (int m = 0; m < 4; ++m) _Pragma("unroll") for (int n = 0; n < 2; ++n) _Pragma("unroll") for (int k = 0; k < 2; ++k) \
;         acc[ai][bj][m][n] = __builtin_amdgcn_mfma_f32_16x16x32_bf16(Bt[n][k], At[m][k], acc[ai][bj][m][n], 0, 0, 0); __builtin_amdgcn_s_setprio(0); } while (0)
; #define PG8_WAIT_V(n) asm volatile("s_waitcnt vmcnt(" #n ")" ::: "memory")
; #define PG8_WAIT_L(n) asm volatile("s_waitcnt lgkmcnt(" #n ")" ::: "memory")
; #define PG8_BAR __builtin_amdgcn_s_barrier()
; #define PG8_SCHED __builtin_amdgcn_sched_barrier(0)
; template <class Epi, class Sched, bool ALIGN_EPI = false, bool SP2 = false>
; __device__ __forceinline__ void gemm_phase(PG8_LAS unsigned char* lds, const Gemm g, const Sched& S, const Epi& E) {
;     ...
;             PG8_LDB(B0, 1, 0); PG8_LDB(B1, 1, 1); PG8_SCHED; PG8_LDA(At, 1, 0); PG8_STAGE(PG8_SA(0, 1), a2 + hstep, voffA);
;             PG8_WAIT_V(8); PG8_WAIT_L(0); PG8_BAR; PG8_MMA(0, 0, At, B0); PG8_MMA(0, 1, At, B1); PG8_BAR; PG8_SCHED;
;             PG8_LDA(At, 1, 1); PG8_STAGE(PG8_SB(1, 0), b3, voffB); PG8_STAGE(PG8_SB(1, 1), b3 + hstep, voffB); PG8_STAGE(PG8_SA(1, 0), a3, voffA);
;             PG8_WAIT_V(8); PG8_WAIT_L(0); PG8_BAR; PG8_MMA(1, 0, At, B0); PG8_MMA(1, 1, At, B1); PG8_BAR; PG8_SCHED;
;     ...
;         if constexpr (ALIGN_EPI) { if (wr == 0) PG8_BAR; }
	s_add_i32 s62, 0, 0x18000
	s_add_i32 s63, 0, 0x1c000
	v_add_u32_e32 v140, s62, v172
	v_add_u32_e32 v177, s63, v172
	ds_read_b128 v[128:131], v140
	ds_read_b128 v[132:135], v140 offset:1024
	ds_read_b128 v[136:139], v140 offset:2048
	ds_read_b128 v[140:143], v140 offset:3072
	ds_read_b128 v[164:167], v177
	ds_read_b128 v[168:171], v177 offset:1024
	ds_read_b128 v[178:181], v177 offset:2048
	ds_read_b128 v[182:185], v177 offset:3072
	s_add_u32 s36, s36, 0x40000
	s_addc_u32 s37, s37, 0
	s_mov_b32 m0, s45
	ds_read_b128 v[190:193], v175 offset:32768
	ds_read_b128 v[194:197], v175 offset:33792
	ds_read_b128 v[198:201], v175 offset:34816
	ds_read_b128 v[202:205], v175 offset:35840
	ds_read_b128 v[206:209], v175 offset:36864
	ds_read_b128 v[210:213], v175 offset:37888
	ds_read_b128 v[214:217], v175 offset:38912
	ds_read_b128 v[218:221], v175 offset:39936
	global_load_lds_dwordx4 v144, s[36:37]
	s_mov_b32 m0, s46
	s_nop 0
	global_load_lds_dwordx4 v148, s[36:37]
	s_waitcnt vmcnt(8)
	s_waitcnt lgkmcnt(0)
	s_barrier
	v_mfma_f32_16x16x32_bf16 v[124:127], v[128:131], v[190:193], v[124:127]
	v_mfma_f32_16x16x32_bf16 v[120:123], v[136:139], v[190:193], v[120:123]
	v_mfma_f32_16x16x32_bf16 v[108:111], v[128:131], v[198:201], v[108:111]
	v_mfma_f32_16x16x32_bf16 v[104:107], v[136:139], v[198:201], v[104:107]
	v_mfma_f32_16x16x32_bf16 v[92:95], v[128:131], v[206:209], v[92:95]
	v_mfma_f32_16x16x32_bf16 v[88:91], v[136:139], v[206:209], v[88:91]
	v_mfma_f32_16x16x32_bf16 v[76:79], v[128:131], v[214:217], v[76:79]
	v_mfma_f32_16x16x32_bf16 v[72:75], v[136:139], v[214:217], v[72:75]
	v_mfma_f32_16x16x32_bf16 v[124:127], v[132:135], v[194:197], v[124:127]
	v_mfma_f32_16x16x32_bf16 v[120:123], v[140:143], v[194:197], v[120:123]
	v_mfma_f32_16x16x32_bf16 v[108:111], v[132:135], v[202:205], v[108:111]
	v_mfma_f32_16x16x32_bf16 v[104:107], v[140:143], v[202:205], v[104:107]
	v_mfma_f32_16x16x32_bf16 v[92:95], v[132:135], v[210:213], v[92:95]
	v_mfma_f32_16x16x32_bf16 v[88:91], v[140:143], v[210:213], v[88:91]
	v_mfma_f32_16x16x32_bf16 v[76:79], v[132:135], v[218:221], v[76:79]
	v_mfma_f32_16x16x32_bf16 v[72:75], v[140:143], v[218:221], v[72:75]
	v_mfma_f32_16x16x32_bf16 v[116:119], v[164:167], v[190:193], v[116:119]
	v_mfma_f32_16x16x32_bf16 v[112:115], v[178:181], v[190:193], v[112:115]
	v_mfma_f32_16x16x32_bf16 v[100:103], v[164:167], v[198:201], v[100:103]
	v_mfma_f32_16x16x32_bf16 v[96:99], v[178:181], v[198:201], v[96:99]
	v_mfma_f32_16x16x32_bf16 v[84:87], v[164:167], v[206:209], v[84:87]
	v_mfma_f32_16x16x32_bf16 v[80:83], v[178:181], v[206:209], v[80:83]
	v_mfma_f32_16x16x32_bf16 v[68:71], v[164:167], v[214:217], v[68:71]
	v_mfma_f32_16x16x32_bf16 v[64:67], v[178:181], v[214:217], v[64:67]
	v_mfma_f32_16x16x32_bf16 v[116:119], v[168:171], v[194:197], v[116:119]
	v_mfma_f32_16x16x32_bf16 v[112:115], v[182:185], v[194:197], v[112:115]
	v_mfma_f32_16x16x32_bf16 v[100:103], v[168:171], v[202:205], v[100:103]
	v_mfma_f32_16x16x32_bf16 v[96:99], v[182:185], v[202:205], v[96:99]
	v_mfma_f32_16x16x32_bf16 v[84:87], v[168:171], v[210:213], v[84:87]
	v_mfma_f32_16x16x32_bf16 v[80:83], v[182:185], v[210:213], v[80:83]
	v_mfma_f32_16x16x32_bf16 v[68:71], v[168:171], v[218:221], v[68:71]
	v_mfma_f32_16x16x32_bf16 v[64:67], v[182:185], v[218:221], v[64:67]
	s_barrier
	s_add_i32 s36, s62, s42
	v_lshl_add_u64 v[186:187], v[186:187], 0, s[16:17]
	s_mov_b32 m0, s36
	ds_read_b128 v[190:193], v175 offset:49152
	ds_read_b128 v[194:197], v175 offset:50176
	ds_read_b128 v[198:201], v175 offset:51200
	ds_read_b128 v[202:205], v175 offset:52224
	ds_read_b128 v[206:209], v175 offset:53248
	ds_read_b128 v[210:213], v175 offset:54272
	ds_read_b128 v[214:217], v175 offset:55296
	ds_read_b128 v[218:221], v175 offset:56320
	global_load_lds_dwordx4 v[186:187], off
	s_add_i32 m0, s36, 0x2000
	s_add_u32 s34, s34, 0x40080
	v_lshl_add_u64 v[186:187], v[222:223], 0, s[16:17]
	s_addc_u32 s35, s35, 0
	s_add_i32 s36, s63, s42
	global_load_lds_dwordx4 v[186:187], off
	s_mov_b32 m0, s36
	s_nop 0
	global_load_lds_dwordx4 v146, s[34:35]
	s_add_i32 m0, s36, 0x2000
	s_nop 0
	global_load_lds_dwordx4 v150, s[34:35]
	v_lshl_add_u64 v[186:187], v[224:225], 0, s[16:17]
	s_mov_b32 m0, s48
	s_nop 0
	global_load_lds_dwordx4 v[186:187], off
	v_lshl_add_u64 v[186:187], v[226:227], 0, s[16:17]
	s_mov_b32 m0, s49
	s_nop 0
	global_load_lds_dwordx4 v[186:187], off
	s_waitcnt vmcnt(8)
	s_waitcnt lgkmcnt(0)
	s_barrier
	v_mfma_f32_16x16x32_bf16 v[60:63], v[128:131], v[190:193], v[60:63]
	v_mfma_f32_16x16x32_bf16 v[56:59], v[136:139], v[190:193], v[56:59]
	v_mfma_f32_16x16x32_bf16 v[44:47], v[128:131], v[198:201], v[44:47]
	v_mfma_f32_16x16x32_bf16 v[40:43], v[136:139], v[198:201], v[40:43]
	v_mfma_f32_16x16x32_bf16 v[28:31], v[128:131], v[206:209], v[28:31]
	v_mfma_f32_16x16x32_bf16 v[24:27], v[136:139], v[206:209], v[24:27]
	v_mfma_f32_16x16x32_bf16 v[12:15], v[128:131], v[214:217], v[12:15]
	v_mfma_f32_16x16x32_bf16 v[8:11], v[136:139], v[214:217], v[8:11]
	v_mfma_f32_16x16x32_bf16 v[60:63], v[132:135], v[194:197], v[60:63]
	v_mfma_f32_16x16x32_bf16 v[56:59], v[140:143], v[194:197], v[56:59]
	v_mfma_f32_16x16x32_bf16 v[44:47], v[132:135], v[202:205], v[44:47]
	v_mfma_f32_16x16x32_bf16 v[40:43], v[140:143], v[202:205], v[40:43]
	v_mfma_f32_16x16x32_bf16 v[28:31], v[132:135], v[210:213], v[28:31]
	v_mfma_f32_16x16x32_bf16 v[24:27], v[140:143], v[210:213], v[24:27]
	v_mfma_f32_16x16x32_bf16 v[12:15], v[132:135], v[218:221], v[12:15]
	v_mfma_f32_16x16x32_bf16 v[8:11], v[140:143], v[218:221], v[8:11]
	v_mfma_f32_16x16x32_bf16 v[52:55], v[164:167], v[190:193], v[52:55]
	v_mfma_f32_16x16x32_bf16 v[48:51], v[178:181], v[190:193], v[48:51]
	v_mfma_f32_16x16x32_bf16 v[36:39], v[164:167], v[198:201], v[36:39]
	v_mfma_f32_16x16x32_bf16 v[32:35], v[178:181], v[198:201], v[32:35]
	v_mfma_f32_16x16x32_bf16 v[20:23], v[164:167], v[206:209], v[20:23]
	v_mfma_f32_16x16x32_bf16 v[16:19], v[178:181], v[206:209], v[16:19]
	v_mfma_f32_16x16x32_bf16 v[4:7], v[164:167], v[214:217], v[4:7]
	v_mfma_f32_16x16x32_bf16 v[0:3], v[178:181], v[214:217], v[0:3]
	v_mfma_f32_16x16x32_bf16 v[52:55], v[168:171], v[194:197], v[52:55]
	v_mfma_f32_16x16x32_bf16 v[48:51], v[182:185], v[194:197], v[48:51]
	v_mfma_f32_16x16x32_bf16 v[36:39], v[168:171], v[202:205], v[36:39]
	v_mfma_f32_16x16x32_bf16 v[32:35], v[182:185], v[202:205], v[32:35]
	v_mfma_f32_16x16x32_bf16 v[20:23], v[168:171], v[210:213], v[20:23]
	v_mfma_f32_16x16x32_bf16 v[16:19], v[182:185], v[210:213], v[16:19]
	v_mfma_f32_16x16x32_bf16 v[4:7], v[168:171], v[218:221], v[4:7]
	v_mfma_f32_16x16x32_bf16 v[0:3], v[182:185], v[218:221], v[0:3]
	s_barrier
	s_add_i32 s61, s61, 2
	s_add_u32 s30, s30, 0x100
	s_addc_u32 s31, s31, 0
	s_add_u32 s59, s59, 0x100
	s_addc_u32 s60, s60, 0
	s_cmp_gt_u32 s61, 13
	s_cbranch_scc0 .LBB0_882
	s_setprio 0
	s_and_b64 vcc, exec, s[18:19]
	s_cbranch_vccz .LBB0_885
	s_barrier

;     __host__ __device__ bool next(int i, Unit& u) const { const long L = (long)i * G + c; if (L >= nwg) return false; return unit_of((int)L, u); }
;     __host__ __device__ bool next(int i, Unit& u) const { const int L = i == 0 ? l0 : (i == 1 ? l1 : (i == 2 ? l2 : -1)); if (L < 0 || L >= s.nwg) return false; return s.unit_of(L, u); }
;     __host__ __device__ bool next(int i, Unit& u) const { const bool ok = s.next(i >> 1, u); u.kh = i & 1; return ok; }
; #define PG8_STAGE(bufoff, gbase, voff) do { _Pragma("unroll") for (int _i = 0; _i < 2; ++_i) \
;         __builtin_amdgcn_global_load_lds((const unsigned*)((const char*)(gbase) + (voff)[_i]), (PG8_LAS unsigned*)(lds + (bufoff) + ldsw + _i * 8192), 16, 0, 0); } while (0)
; #define PG8_WAIT_V(n) asm volatile("s_waitcnt vmcnt(" #n ")" ::: "memory")
; #define PG8_WAIT_L(n) asm volatile("s_waitcnt lgkmcnt(" #n ")" ::: "memory")
; #define PG8_BAR __builtin_amdgcn_s_barrier()
; template <class Epi, class Sched, bool ALIGN_EPI = false, bool SP2 = false>
; __device__ __forceinline__ void gemm_phase(PG8_LAS unsigned char* lds, const Gemm g, const Sched& S, const Epi& E) {
;     ...
;         const bool has_next = S.next(ui + 1, nxt);
;         const char* nA = has_next ? (const char*)g.A + (size_t)nxt.pm * tstep + nxt.kh * khb : cA; const char* nB = has_next ? (const char*)g.Bt + (size_t)nxt.pn * tstep + nxt.kh * khb : cB;
;         for (int t = 0; t < nt; t += 2) {
;             const bool last = (t == nt - 2);
;             const char* a1 = cA + (size_t)(t + 1) * kstep;
;             const char* a2 = last ? nA : cA + (size_t)(t + 2) * kstep; const char* b2 = last ? nB : cB + (size_t)(t + 2) * kstep;
;             const char* a3 = a2 + kstep; const char* b3 = b2 + kstep;
;             if (last && has_next) S.a_ready(nxt);
;             if constexpr (SP2) {
;             PG8_LDB(B0, 0, 0); PG8_LDB(B1, 0, 1); PG8_SCHED; PG8_LDA(At, 0, 0); PG8_STAGE(PG8_SA(1, 1), a1 + hstep, voffA);
;             PG8_WAIT_V(8); PG8_WAIT_L(0); PG8_BAR; PG8_MMA(0, 0, At, B0); PG8_MMA(0, 1, At, B1); PG8_BAR; PG8_SCHED;
;     ...
;         for (int a = 0; a < 2; ++a)
; #pragma unroll
;             for (int b = 0; b < 2; ++b)
; #pragma unroll
;                 for (int m = 0; m < 4; ++m)
; #pragma unroll
;                     for (int n = 0; n < 2; ++n) acc[a][b][m][n] = (f32x4){0.f, 0.f, 0.f, 0.f};
;         cur = nxt; cA = nA; cB = nB; ++ui;
.LBB0_968:
	s_ashr_i32 s17, s16, 31
	s_lshl_b64 s[18:19], s[16:17], 19
	s_add_u32 s18, s30, s18
	s_addc_u32 s19, s31, s19
	s_and_b64 s[20:21], s[2:3], exec
	s_cselect_b32 s17, s19, s25
	s_cselect_b32 s51, s18, s24
	s_ashr_i32 s15, s14, 31
	s_lshl_b64 s[20:21], s[14:15], 19
	s_add_u32 s20, s34, s20
	s_addc_u32 s21, s35, s21
	s_and_b64 s[28:29], s[2:3], exec
	s_cselect_b32 s15, s21, s27
	s_cselect_b32 s54, s20, s26
	s_add_u32 s24, s24, 0x40080
	s_addc_u32 s25, s25, 0
	s_add_u32 s55, s26, 0x100
	v_mov_b32_e32 v0, 0
	s_addc_u32 s56, s27, 0
	s_mov_b32 s57, -2
	v_mov_b32_e32 v1, v0
	v_mov_b32_e32 v2, v0
	v_mov_b32_e32 v3, v0
	v_mov_b32_e32 v4, v0
	v_mov_b32_e32 v5, v0
	v_mov_b32_e32 v6, v0
	v_mov_b32_e32 v7, v0
	v_mov_b32_e32 v16, v0
	v_mov_b32_e32 v17, v0
	v_mov_b32_e32 v18, v0
	v_mov_b32_e32 v19, v0
	v_mov_b32_e32 v24, v0
	v_mov_b32_e32 v25, v0
	v_mov_b32_e32 v26, v0
	v_mov_b32_e32 v27, v0
	v_mov_b32_e32 v32, v0
	v_mov_b32_e32 v33, v0
	v_mov_b32_e32 v34, v0
	v_mov_b32_e32 v35, v0
	v_mov_b32_e32 v36, v0
	v_mov_b32_e32 v37, v0
	v_mov_b32_e32 v38, v0
	v_mov_b32_e32 v39, v0
	v_mov_b32_e32 v48, v0
	v_mov_b32_e32 v49, v0
	v_mov_b32_e32 v50, v0
	v_mov_b32_e32 v51, v0
	v_mov_b32_e32 v56, v0
	v_mov_b32_e32 v57, v0
	v_mov_b32_e32 v58, v0
	v_mov_b32_e32 v59, v0
	v_mov_b32_e32 v8, v0
	v_mov_b32_e32 v9, v0
	v_mov_b32_e32 v10, v0
	v_mov_b32_e32 v11, v0
	v_mov_b32_e32 v12, v0
	v_mov_b32_e32 v13, v0
	v_mov_b32_e32 v14, v0
	v_mov_b32_e32 v15, v0
	v_mov_b32_e32 v20, v0
	v_mov_b32_e32 v21, v0
	v_mov_b32_e32 v22, v0
	v_mov_b32_e32 v23, v0
	v_mov_b32_e32 v28, v0
	v_mov_b32_e32 v29, v0
	v_mov_b32_e32 v30, v0
	v_mov_b32_e32 v31, v0
	v_mov_b32_e32 v40, v0
	v_mov_b32_e32 v41, v0
	v_mov_b32_e32 v42, v0
	v_mov_b32_e32 v43, v0
	v_mov_b32_e32 v44, v0
	v_mov_b32_e32 v45, v0
	v_mov_b32_e32 v46, v0
	v_mov_b32_e32 v47, v0
	v_mov_b32_e32 v52, v0
	v_mov_b32_e32 v53, v0
	v_mov_b32_e32 v54, v0
	v_mov_b32_e32 v55, v0
	v_mov_b32_e32 v60, v0
	v_mov_b32_e32 v61, v0
	v_mov_b32_e32 v62, v0
	v_mov_b32_e32 v63, v0
	v_mov_b32_e32 v64, v0
	v_mov_b32_e32 v65, v0
	v_mov_b32_e32 v66, v0
	v_mov_b32_e32 v67, v0
	v_mov_b32_e32 v68, v0
	v_mov_b32_e32 v69, v0
	v_mov_b32_e32 v70, v0
	v_mov_b32_e32 v71, v0
	v_mov_b32_e32 v80, v0
	v_mov_b32_e32 v81, v0
	v_mov_b32_e32 v82, v0
	v_mov_b32_e32 v83, v0
	v_mov_b32_e32 v88, v0
	v_mov_b32_e32 v89, v0
	v_mov_b32_e32 v90, v0
	v_mov_b32_e32 v91, v0
	v_mov_b32_e32 v96, v0
	v_mov_b32_e32 v97, v0
	v_mov_b32_e32 v98, v0
	v_mov_b32_e32 v99, v0
	v_mov_b32_e32 v100, v0
	v_mov_b32_e32 v101, v0
	v_mov_b32_e32 v102, v0
	v_mov_b32_e32 v103, v0
	v_mov_b32_e32 v112, v0
	v_mov_b32_e32 v113, v0
	v_mov_b32_e32 v114, v0
	v_mov_b32_e32 v115, v0
	v_mov_b32_e32 v116, v0
	v_mov_b32_e32 v117, v0
	v_mov_b32_e32 v118, v0
	v_mov_b32_e32 v119, v0
	v_mov_b32_e32 v72, v0
	v_mov_b32_e32 v73, v0
	v_mov_b32_e32 v74, v0
	v_mov_b32_e32 v75, v0
	v_mov_b32_e32 v76, v0
	v_mov_b32_e32 v77, v0
	v_mov_b32_e32 v78, v0
	v_mov_b32_e32 v79, v0
	v_mov_b32_e32 v84, v0
	v_mov_b32_e32 v85, v0
	v_mov_b32_e32 v86, v0
	v_mov_b32_e32 v87, v0
	v_mov_b32_e32 v92, v0
	v_mov_b32_e32 v93, v0
	v_mov_b32_e32 v94, v0
	v_mov_b32_e32 v95, v0
	v_mov_b32_e32 v104, v0
	v_mov_b32_e32 v105, v0
	v_mov_b32_e32 v106, v0
	v_mov_b32_e32 v107, v0
	v_mov_b32_e32 v108, v0
	v_mov_b32_e32 v109, v0
	v_mov_b32_e32 v110, v0
	v_mov_b32_e32 v111, v0
	v_mov_b32_e32 v120, v0
	v_mov_b32_e32 v121, v0
	v_mov_b32_e32 v122, v0
	v_mov_b32_e32 v123, v0
	v_mov_b32_e32 v124, v0
	v_mov_b32_e32 v125, v0
	v_mov_b32_e32 v126, v0
	v_mov_b32_e32 v127, v0
	v_readfirstlane_b32 s100, v188
	s_bitcmp1_b32 s100, 8
	s_cbranch_scc0 .Lmy_sprio_969
	s_setprio 1
.Lmy_sprio_969:
.LBB0_969:
	ds_read_b128 v[128:131], v191
	ds_read_b128 v[132:135], v191 offset:1024
	ds_read_b128 v[136:139], v191 offset:2048
	ds_read_b128 v[140:143], v191 offset:3072
	ds_read_b128 v[144:147], v192
	ds_read_b128 v[148:151], v192 offset:1024
	ds_read_b128 v[172:175], v192 offset:2048
	ds_read_b128 v[176:179], v192 offset:3072
	s_add_u32 s26, s24, 0xfffc0080
	s_addc_u32 s27, s25, -1
	s_cmp_eq_u32 s57, 12
	s_cselect_b32 s29, s17, s27
	s_cselect_b32 s28, s51, s26
	s_cselect_b32 s27, s15, s56
	s_cselect_b32 s26, s54, s55
	s_add_i32 m0, s39, 0xc000
	ds_read_b128 v[180:183], v193
	ds_read_b128 v[184:187], v193 offset:1024
	ds_read_b128 v[196:199], v193 offset:2048
	ds_read_b128 v[200:203], v193 offset:3072
	ds_read_b128 v[204:207], v193 offset:4096
	ds_read_b128 v[208:211], v193 offset:5120
	ds_read_b128 v[212:215], v193 offset:6144
	ds_read_b128 v[216:219], v193 offset:7168
	global_load_lds_dwordx4 v164, s[24:25]
	s_add_i32 m0, s39, 0xe000
	s_nop 0
	global_load_lds_dwordx4 v166, s[24:25]
	s_waitcnt vmcnt(8)
	s_waitcnt lgkmcnt(0)
	s_barrier
; #define PG8_STAGE(bufoff, gbase, voff) do { _Pragma("unroll") for (int _i = 0; _i < 2; ++_i) \
;         __builtin_amdgcn_global_load_lds((const unsigned*)((const char*)(gbase) + (voff)[_i]), (PG8_LAS unsigned*)(lds + (bufoff) + ldsw + _i * 8192), 16, 0, 0); } while (0)
; #define PG8_LDA(dst, b, h) do { _Pragma("unroll") for (int m = 0; m < 4; ++m) _Pragma("unroll") for (int k = 0; k < 2; ++k) dst[m][k] = *(const PG8_LAS bf16x8*)(lds + PG8_SA(b, h) + aoff + m * 2048 + k * 1024); } while (0)
; #define PG8_MMA(ai, bj, At, Bt) do { __builtin_amdgcn_s_setprio(1); _Pragma("unroll") for (int m = 0; m < 4; ++m) _Pragma("unroll") for (int n = 0; n < 2; ++n) _Pragma("unroll") for (int k = 0; k < 2; ++k) \
;         acc[ai][bj][m][n] = __builtin_amdgcn_mfma_f32_16x16x32_bf16(Bt[n][k], At[m][k], acc[ai][bj][m][n], 0, 0, 0); __builtin_amdgcn_s_setprio(0); } while (0)
; #define PG8_WAIT_V(n) asm volatile("s_waitcnt vmcnt(" #n ")" ::: "memory")
; #define PG8_WAIT_L(n) asm volatile("s_waitcnt lgkmcnt(" #n ")" ::: "memory")
; #define PG8_BAR __builtin_amdgcn_s_barrier()
; #define PG8_SCHED __builtin_amdgcn_sched_barrier(0)
; template <class Epi, class Sched, bool ALIGN_EPI = false, bool SP2 = false>
; __device__ __forceinline__ void gemm_phase(PG8_LAS unsigned char* lds, const Gemm g, const Sched& S, const Epi& E) {
;     ...
;             PG8_WAIT_V(8); PG8_WAIT_L(0); PG8_BAR; PG8_MMA(0, 0, At, B0); PG8_MMA(0, 1, At, B1); PG8_BAR; PG8_SCHED;
;             PG8_LDA(At, 0, 1); PG8_STAGE(PG8_SB(0, 0), b2, voffB); PG8_STAGE(PG8_SB(0, 1), b2 + hstep, voffB); PG8_STAGE(PG8_SA(0, 0), a2, voffA);
;             PG8_WAIT_V(8); PG8_WAIT_L(0); PG8_BAR; PG8_MMA(1, 0, At, B0); PG8_MMA(1, 1, At, B1); PG8_BAR; PG8_SCHED;
	v_mfma_f32_16x16x32_bf16 v[124:127], v[128:131], v[180:183], v[124:127]
	v_mfma_f32_16x16x32_bf16 v[120:123], v[136:139], v[180:183], v[120:123]
	v_mfma_f32_16x16x32_bf16 v[108:111], v[128:131], v[196:199], v[108:111]
	v_mfma_f32_16x16x32_bf16 v[104:107], v[136:139], v[196:199], v[104:107]
	v_mfma_f32_16x16x32_bf16 v[92:95], v[128:131], v[204:207], v[92:95]
	v_mfma_f32_16x16x32_bf16 v[84:87], v[136:139], v[204:207], v[84:87]
	v_mfma_f32_16x16x32_bf16 v[76:79], v[128:131], v[212:215], v[76:79]
	v_mfma_f32_16x16x32_bf16 v[72:75], v[136:139], v[212:215], v[72:75]
	v_mfma_f32_16x16x32_bf16 v[124:127], v[132:135], v[184:187], v[124:127]
	v_mfma_f32_16x16x32_bf16 v[120:123], v[140:143], v[184:187], v[120:123]
	v_mfma_f32_16x16x32_bf16 v[108:111], v[132:135], v[200:203], v[108:111]
	v_mfma_f32_16x16x32_bf16 v[104:107], v[140:143], v[200:203], v[104:107]
	v_mfma_f32_16x16x32_bf16 v[92:95], v[132:135], v[208:211], v[92:95]
	v_mfma_f32_16x16x32_bf16 v[84:87], v[140:143], v[208:211], v[84:87]
	v_mfma_f32_16x16x32_bf16 v[76:79], v[132:135], v[216:219], v[76:79]
	v_mfma_f32_16x16x32_bf16 v[72:75], v[140:143], v[216:219], v[72:75]
	v_mfma_f32_16x16x32_bf16 v[116:119], v[144:147], v[180:183], v[116:119]
	v_mfma_f32_16x16x32_bf16 v[112:115], v[172:175], v[180:183], v[112:115]
	v_mfma_f32_16x16x32_bf16 v[100:103], v[144:147], v[196:199], v[100:103]
	v_mfma_f32_16x16x32_bf16 v[96:99], v[172:175], v[196:199], v[96:99]
	v_mfma_f32_16x16x32_bf16 v[88:91], v[144:147], v[204:207], v[88:91]
	v_mfma_f32_16x16x32_bf16 v[80:83], v[172:175], v[204:207], v[80:83]
	v_mfma_f32_16x16x32_bf16 v[68:71], v[144:147], v[212:215], v[68:71]
	v_mfma_f32_16x16x32_bf16 v[64:67], v[172:175], v[212:215], v[64:67]
	v_mfma_f32_16x16x32_bf16 v[116:119], v[148:151], v[184:187], v[116:119]
	v_mfma_f32_16x16x32_bf16 v[112:115], v[176:179], v[184:187], v[112:115]
	v_mfma_f32_16x16x32_bf16 v[100:103], v[148:151], v[200:203], v[100:103]
	v_mfma_f32_16x16x32_bf16 v[96:99], v[176:179], v[200:203], v[96:99]
	v_mfma_f32_16x16x32_bf16 v[88:91], v[148:151], v[208:211], v[88:91]
	v_mfma_f32_16x16x32_bf16 v[80:83], v[176:179], v[208:211], v[80:83]
	v_mfma_f32_16x16x32_bf16 v[68:71], v[148:151], v[216:219], v[68:71]
	v_mfma_f32_16x16x32_bf16 v[64:67], v[176:179], v[216:219], v[64:67]
	s_barrier
	s_add_i32 s58, s47, s36
	v_lshl_add_u64 v[220:221], s[26:27], 0, v[156:157]
	s_mov_b32 m0, s58
	ds_read_b128 v[180:183], v193 offset:16384
	ds_read_b128 v[184:187], v193 offset:17408
	ds_read_b128 v[196:199], v193 offset:18432
	ds_read_b128 v[200:203], v193 offset:19456
	ds_read_b128 v[204:207], v193 offset:20480
	ds_read_b128 v[208:211], v193 offset:21504
	ds_read_b128 v[212:215], v193 offset:22528
	ds_read_b128 v[216:219], v193 offset:23552
	global_load_lds_dwordx4 v[220:221], off
	s_add_i32 m0, s58, 0x2000
	s_add_u32 s58, s26, 0x40000
	v_lshl_add_u64 v[222:223], s[26:27], 0, v[152:153]
	s_addc_u32 s59, s27, 0
	s_add_i32 s60, s48, s36
	global_load_lds_dwordx4 v[222:223], off
	s_mov_b32 m0, s60
	v_lshl_add_u64 v[226:227], s[28:29], 0, v[154:155]
	global_load_lds_dwordx4 v156, s[58:59]
	s_add_i32 m0, s60, 0x2000
	s_nop 0
	global_load_lds_dwordx4 v152, s[58:59]
	v_lshl_add_u64 v[224:225], s[28:29], 0, v[158:159]
	s_mov_b32 m0, s39
	s_nop 0
	global_load_lds_dwordx4 v[224:225], off
	s_mov_b32 m0, s40
	s_nop 0
	global_load_lds_dwordx4 v[226:227], off
	s_waitcnt vmcnt(8)
	s_waitcnt lgkmcnt(0)
	s_barrier
	v_mfma_f32_16x16x32_bf16 v[60:63], v[128:131], v[180:183], v[60:63]
	v_mfma_f32_16x16x32_bf16 v[52:55], v[136:139], v[180:183], v[52:55]
	v_mfma_f32_16x16x32_bf16 v[44:47], v[128:131], v[196:199], v[44:47]
	v_mfma_f32_16x16x32_bf16 v[40:43], v[136:139], v[196:199], v[40:43]
	v_mfma_f32_16x16x32_bf16 v[28:31], v[128:131], v[204:207], v[28:31]
	v_mfma_f32_16x16x32_bf16 v[20:23], v[136:139], v[204:207], v[20:23]
	v_mfma_f32_16x16x32_bf16 v[12:15], v[128:131], v[212:215], v[12:15]
	v_mfma_f32_16x16x32_bf16 v[8:11], v[136:139], v[212:215], v[8:11]
	v_mfma_f32_16x16x32_bf16 v[60:63], v[132:135], v[184:187], v[60:63]
	v_mfma_f32_16x16x32_bf16 v[52:55], v[140:143], v[184:187], v[52:55]
	v_mfma_f32_16x16x32_bf16 v[44:47], v[132:135], v[200:203], v[44:47]
	v_mfma_f32_16x16x32_bf16 v[40:43], v[140:143], v[200:203], v[40:43]
	v_mfma_f32_16x16x32_bf16 v[28:31], v[132:135], v[208:211], v[28:31]
	v_mfma_f32_16x16x32_bf16 v[20:23], v[140:143], v[208:211], v[20:23]
	v_mfma_f32_16x16x32_bf16 v[12:15], v[132:135], v[216:219], v[12:15]
	v_mfma_f32_16x16x32_bf16 v[8:11], v[140:143], v[216:219], v[8:11]
	v_mfma_f32_16x16x32_bf16 v[56:59], v[144:147], v[180:183], v[56:59]
	v_mfma_f32_16x16x32_bf16 v[48:51], v[172:175], v[180:183], v[48:51]
	v_mfma_f32_16x16x32_bf16 v[36:39], v[144:147], v[196:199], v[36:39]
	v_mfma_f32_16x16x32_bf16 v[32:35], v[172:175], v[196:199], v[32:35]
	v_mfma_f32_16x16x32_bf16 v[24:27], v[144:147], v[204:207], v[24:27]
	v_mfma_f32_16x16x32_bf16 v[16:19], v[172:175], v[204:207], v[16:19]
	v_mfma_f32_16x16x32_bf16 v[4:7], v[144:147], v[212:215], v[4:7]
	v_mfma_f32_16x16x32_bf16 v[0:3], v[172:175], v[212:215], v[0:3]
	v_mfma_f32_16x16x32_bf16 v[56:59], v[148:151], v[184:187], v[56:59]
	v_mfma_f32_16x16x32_bf16 v[48:51], v[176:179], v[184:187], v[48:51]
	v_mfma_f32_16x16x32_bf16 v[36:39], v[148:151], v[200:203], v[36:39]
	v_mfma_f32_16x16x32_bf16 v[32:35], v[176:179], v[200:203], v[32:35]
	v_mfma_f32_16x16x32_bf16 v[24:27], v[148:151], v[208:211], v[24:27]
	v_mfma_f32_16x16x32_bf16 v[16:19], v[176:179], v[208:211], v[16:19]
	v_mfma_f32_16x16x32_bf16 v[4:7], v[148:151], v[216:219], v[4:7]
	v_mfma_f32_16x16x32_bf16 v[0:3], v[176:179], v[216:219], v[0:3]
	s_barrier
; #define PG8_STAGE(bufoff, gbase, voff) do { _Pragma("unroll") for (int _i = 0; _i < 2; ++_i) \
;         __builtin_amdgcn_global_load_lds((const unsigned*)((const char*)(gbase) + (voff)[_i]), (PG8_LAS unsigned*)(lds + (bufoff) + ldsw + _i * 8192), 16, 0, 0); } while (0)
; #define PG8_LDA(dst, b, h) do { _Pragma("unroll") for (int m = 0; m < 4; ++m) _Pragma("unroll") for (int k = 0; k < 2; ++k) dst[m][k] = *(const PG8_LAS bf16x8*)(lds + PG8_SA(b, h) + aoff + m * 2048 + k * 1024); } while (0)
; #define PG8_LDB(dst, b, h) do { _Pragma("unroll") for (int n = 0; n < 2; ++n) _Pragma("unroll") for (int k = 0; k < 2; ++k) dst[n][k] = *(const PG8_LAS bf16x8*)(lds + PG8_SB(b, h) + boff + n * 2048 + k * 1024); } while (0)
; #define PG8_MMA(ai, bj, At, Bt) do { __builtin_amdgcn_s_setprio(1); _Pragma("unroll") for (int m = 0; m < 4; ++m) _Pragma("unroll") for (int n = 0; n < 2; ++n) _Pragma("unroll") for (int k = 0; k < 2; ++k) \
;         acc[ai][bj][m][n] = __builtin_amdgcn_mfma_f32_16x16x32_bf16(Bt[n][k], At[m][k], acc[ai][bj][m][n], 0, 0, 0); __builtin_amdgcn_s_setprio(0); } while (0)
; #define PG8_WAIT_V(n) asm volatile("s_waitcnt vmcnt(" #n ")" ::: "memory")
; #define PG8_WAIT_L(n) asm volatile("s_waitcnt lgkmcnt(" #n ")" ::: "memory")
; #define PG8_BAR __builtin_amdgcn_s_barrier()
; #define PG8_SCHED __builtin_amdgcn_sched_barrier(0)
; template <class Epi, class Sched, bool ALIGN_EPI = false, bool SP2 = false>
; __device__ __forceinline__ void gemm_phase(PG8_LAS unsigned char* lds, const Gemm g, const Sched& S, const Epi& E) {
;     ...
;             PG8_LDB(B0, 1, 0); PG8_LDB(B1, 1, 1); PG8_SCHED; PG8_LDA(At, 1, 0); PG8_STAGE(PG8_SA(0, 1), a2 + hstep, voffA);
;             PG8_WAIT_V(8); PG8_WAIT_L(0); PG8_BAR; PG8_MMA(0, 0, At, B0); PG8_MMA(0, 1, At, B1); PG8_BAR; PG8_SCHED;
;             PG8_LDA(At, 1, 1); PG8_STAGE(PG8_SB(1, 0), b3, voffB); PG8_STAGE(PG8_SB(1, 1), b3 + hstep, voffB); PG8_STAGE(PG8_SA(1, 0), a3, voffA);
;             PG8_WAIT_V(8); PG8_WAIT_L(0); PG8_BAR; PG8_MMA(1, 0, At, B0); PG8_MMA(1, 1, At, B1); PG8_BAR; PG8_SCHED;
;     ...
;         if constexpr (ALIGN_EPI) { if (wr == 0) PG8_BAR; }
	s_add_i32 s58, 0, 0x18000
	s_add_i32 s59, 0, 0x1c000
	v_add_u32_e32 v140, s58, v190
	v_add_u32_e32 v176, s59, v190
	ds_read_b128 v[128:131], v140
	ds_read_b128 v[132:135], v140 offset:1024
	ds_read_b128 v[136:139], v140 offset:2048
	ds_read_b128 v[140:143], v140 offset:3072
	ds_read_b128 v[144:147], v176
	ds_read_b128 v[148:151], v176 offset:1024
	ds_read_b128 v[172:175], v176 offset:2048
	ds_read_b128 v[176:179], v176 offset:3072
	s_add_u32 s28, s28, 0x40000
	s_addc_u32 s29, s29, 0
	s_mov_b32 m0, s41
	ds_read_b128 v[180:183], v193 offset:32768
	ds_read_b128 v[184:187], v193 offset:33792
	ds_read_b128 v[196:199], v193 offset:34816
	ds_read_b128 v[200:203], v193 offset:35840
	ds_read_b128 v[204:207], v193 offset:36864
	ds_read_b128 v[208:211], v193 offset:37888
	ds_read_b128 v[212:215], v193 offset:38912
	ds_read_b128 v[216:219], v193 offset:39936
	global_load_lds_dwordx4 v158, s[28:29]
	s_mov_b32 m0, s42
	s_nop 0
	global_load_lds_dwordx4 v154, s[28:29]
	s_waitcnt vmcnt(8)
	s_waitcnt lgkmcnt(0)
	s_barrier
	v_mfma_f32_16x16x32_bf16 v[124:127], v[128:131], v[180:183], v[124:127]
	v_mfma_f32_16x16x32_bf16 v[120:123], v[136:139], v[180:183], v[120:123]
	v_mfma_f32_16x16x32_bf16 v[108:111], v[128:131], v[196:199], v[108:111]
	v_mfma_f32_16x16x32_bf16 v[104:107], v[136:139], v[196:199], v[104:107]
	v_mfma_f32_16x16x32_bf16 v[92:95], v[128:131], v[204:207], v[92:95]
	v_mfma_f32_16x16x32_bf16 v[84:87], v[136:139], v[204:207], v[84:87]
	v_mfma_f32_16x16x32_bf16 v[76:79], v[128:131], v[212:215], v[76:79]
	v_mfma_f32_16x16x32_bf16 v[72:75], v[136:139], v[212:215], v[72:75]
	v_mfma_f32_16x16x32_bf16 v[124:127], v[132:135], v[184:187], v[124:127]
	v_mfma_f32_16x16x32_bf16 v[120:123], v[140:143], v[184:187], v[120:123]
	v_mfma_f32_16x16x32_bf16 v[108:111], v[132:135], v[200:203], v[108:111]
	v_mfma_f32_16x16x32_bf16 v[104:107], v[140:143], v[200:203], v[104:107]
	v_mfma_f32_16x16x32_bf16 v[92:95], v[132:135], v[208:211], v[92:95]
	v_mfma_f32_16x16x32_bf16 v[84:87], v[140:143], v[208:211], v[84:87]
	v_mfma_f32_16x16x32_bf16 v[76:79], v[132:135], v[216:219], v[76:79]
	v_mfma_f32_16x16x32_bf16 v[72:75], v[140:143], v[216:219], v[72:75]
	v_mfma_f32_16x16x32_bf16 v[116:119], v[144:147], v[180:183], v[116:119]
	v_mfma_f32_16x16x32_bf16 v[112:115], v[172:175], v[180:183], v[112:115]
	v_mfma_f32_16x16x32_bf16 v[100:103], v[144:147], v[196:199], v[100:103]
	v_mfma_f32_16x16x32_bf16 v[96:99], v[172:175], v[196:199], v[96:99]
	v_mfma_f32_16x16x32_bf16 v[88:91], v[144:147], v[204:207], v[88:91]
	v_mfma_f32_16x16x32_bf16 v[80:83], v[172:175], v[204:207], v[80:83]
	v_mfma_f32_16x16x32_bf16 v[68:71], v[144:147], v[212:215], v[68:71]
	v_mfma_f32_16x16x32_bf16 v[64:67], v[172:175], v[212:215], v[64:67]
	v_mfma_f32_16x16x32_bf16 v[116:119], v[148:151], v[184:187], v[116:119]
	v_mfma_f32_16x16x32_bf16 v[112:115], v[176:179], v[184:187], v[112:115]
	v_mfma_f32_16x16x32_bf16 v[100:103], v[148:151], v[200:203], v[100:103]
	v_mfma_f32_16x16x32_bf16 v[96:99], v[176:179], v[200:203], v[96:99]
	v_mfma_f32_16x16x32_bf16 v[88:91], v[148:151], v[208:211], v[88:91]
	v_mfma_f32_16x16x32_bf16 v[80:83], v[176:179], v[208:211], v[80:83]
	v_mfma_f32_16x16x32_bf16 v[68:71], v[148:151], v[216:219], v[68:71]
	v_mfma_f32_16x16x32_bf16 v[64:67], v[176:179], v[216:219], v[64:67]
	s_barrier
	s_add_i32 s28, s58, s36
	v_lshl_add_u64 v[220:221], v[220:221], 0, s[10:11]
	s_mov_b32 m0, s28
	ds_read_b128 v[180:183], v193 offset:49152
	ds_read_b128 v[184:187], v193 offset:50176
	ds_read_b128 v[196:199], v193 offset:51200
	ds_read_b128 v[200:203], v193 offset:52224
	ds_read_b128 v[204:207], v193 offset:53248
	ds_read_b128 v[208:211], v193 offset:54272
	ds_read_b128 v[212:215], v193 offset:55296
	ds_read_b128 v[216:219], v193 offset:56320
	global_load_lds_dwordx4 v[220:221], off
	s_add_i32 m0, s28, 0x2000
	s_add_u32 s26, s26, 0x40080
	v_lshl_add_u64 v[220:221], v[222:223], 0, s[10:11]
	s_addc_u32 s27, s27, 0
	s_add_i32 s28, s59, s36
	global_load_lds_dwordx4 v[220:221], off
	s_mov_b32 m0, s28
	s_nop 0
	global_load_lds_dwordx4 v156, s[26:27]
	s_add_i32 m0, s28, 0x2000
	s_nop 0
	global_load_lds_dwordx4 v152, s[26:27]
	v_lshl_add_u64 v[220:221], v[224:225], 0, s[10:11]
	s_mov_b32 m0, s43
	s_nop 0
	global_load_lds_dwordx4 v[220:221], off
	v_lshl_add_u64 v[220:221], v[226:227], 0, s[10:11]
	s_mov_b32 m0, s44
	s_nop 0
	global_load_lds_dwordx4 v[220:221], off
	s_waitcnt vmcnt(8)
	s_waitcnt lgkmcnt(0)
	s_barrier
	v_mfma_f32_16x16x32_bf16 v[60:63], v[128:131], v[180:183], v[60:63]
	v_mfma_f32_16x16x32_bf16 v[52:55], v[136:139], v[180:183], v[52:55]
	v_mfma_f32_16x16x32_bf16 v[44:47], v[128:131], v[196:199], v[44:47]
	v_mfma_f32_16x16x32_bf16 v[40:43], v[136:139], v[196:199], v[40:43]
	v_mfma_f32_16x16x32_bf16 v[28:31], v[128:131], v[204:207], v[28:31]
	v_mfma_f32_16x16x32_bf16 v[20:23], v[136:139], v[204:207], v[20:23]
	v_mfma_f32_16x16x32_bf16 v[12:15], v[128:131], v[212:215], v[12:15]
	v_mfma_f32_16x16x32_bf16 v[8:11], v[136:139], v[212:215], v[8:11]
	v_mfma_f32_16x16x32_bf16 v[60:63], v[132:135], v[184:187], v[60:63]
	v_mfma_f32_16x16x32_bf16 v[52:55], v[140:143], v[184:187], v[52:55]
	v_mfma_f32_16x16x32_bf16 v[44:47], v[132:135], v[200:203], v[44:47]
	v_mfma_f32_16x16x32_bf16 v[40:43], v[140:143], v[200:203], v[40:43]
	v_mfma_f32_16x16x32_bf16 v[28:31], v[132:135], v[208:211], v[28:31]
	v_mfma_f32_16x16x32_bf16 v[20:23], v[140:143], v[208:211], v[20:23]
	v_mfma_f32_16x16x32_bf16 v[12:15], v[132:135], v[216:219], v[12:15]
	v_mfma_f32_16x16x32_bf16 v[8:11], v[140:143], v[216:219], v[8:11]
	v_mfma_f32_16x16x32_bf16 v[56:59], v[144:147], v[180:183], v[56:59]
	v_mfma_f32_16x16x32_bf16 v[48:51], v[172:175], v[180:183], v[48:51]
	v_mfma_f32_16x16x32_bf16 v[36:39], v[144:147], v[196:199], v[36:39]
	v_mfma_f32_16x16x32_bf16 v[32:35], v[172:175], v[196:199], v[32:35]
	v_mfma_f32_16x16x32_bf16 v[24:27], v[144:147], v[204:207], v[24:27]
	v_mfma_f32_16x16x32_bf16 v[16:19], v[172:175], v[204:207], v[16:19]
	v_mfma_f32_16x16x32_bf16 v[4:7], v[144:147], v[212:215], v[4:7]
	v_mfma_f32_16x16x32_bf16 v[0:3], v[172:175], v[212:215], v[0:3]
	v_mfma_f32_16x16x32_bf16 v[56:59], v[148:151], v[184:187], v[56:59]
	v_mfma_f32_16x16x32_bf16 v[48:51], v[176:179], v[184:187], v[48:51]
	v_mfma_f32_16x16x32_bf16 v[36:39], v[148:151], v[200:203], v[36:39]
	v_mfma_f32_16x16x32_bf16 v[32:35], v[176:179], v[200:203], v[32:35]
	v_mfma_f32_16x16x32_bf16 v[24:27], v[148:151], v[208:211], v[24:27]
	v_mfma_f32_16x16x32_bf16 v[16:19], v[176:179], v[208:211], v[16:19]
	v_mfma_f32_16x16x32_bf16 v[4:7], v[148:151], v[216:219], v[4:7]
	v_mfma_f32_16x16x32_bf16 v[0:3], v[176:179], v[216:219], v[0:3]
	s_barrier
	s_add_i32 s57, s57, 2
	s_add_u32 s24, s24, 0x100
	s_addc_u32 s25, s25, 0
	s_add_u32 s55, s55, 0x100
	s_addc_u32 s56, s56, 0
	s_cmp_gt_u32 s57, 13
	s_cbranch_scc0 .LBB0_969
	s_setprio 0
	s_and_b64 vcc, exec, s[12:13]
	s_cbranch_vccz .LBB0_972
	s_barrier

; #define PG8_STAGE(bufoff, gbase, voff) do { _Pragma("unroll") for (int _i = 0; _i < 2; ++_i) \
;         __builtin_amdgcn_global_load_lds((const unsigned*)((const char*)(gbase) + (voff)[_i]), (PG8_LAS unsigned*)(lds + (bufoff) + ldsw + _i * 8192), 16, 0, 0); } while (0)
; #define PG8_LDA(dst, b, h) do { _Pragma("unroll") for (int m = 0; m < 4; ++m) _Pragma("unroll") for (int k = 0; k < 2; ++k) dst[m][k] = *(const PG8_LAS bf16x8*)(lds + PG8_SA(b, h) + aoff + m * 2048 + k * 1024); } while (0)
; #define PG8_LDB(dst, b, h) do { _Pragma("unroll") for (int n = 0; n < 2; ++n) _Pragma("unroll") for (int k = 0; k < 2; ++k) dst[n][k] = *(const PG8_LAS bf16x8*)(lds + PG8_SB(b, h) + boff + n * 2048 + k * 1024); } while (0)
; #define PG8_MMA(ai, bj, At, Bt) do { __builtin_amdgcn_s_setprio(1); _Pragma("unroll") for (int m = 0; m < 4; ++m) _Pragma("unroll") for (int n = 0; n < 2; ++n) _Pragma("unroll") for (int k = 0; k < 2; ++k) \
;         acc[ai][bj][m][n] = __builtin_amdgcn_mfma_f32_16x16x32_bf16(Bt[n][k], At[m][k], acc[ai][bj][m][n], 0, 0, 0); __builtin_amdgcn_s_setprio(0); } while (0)
; #define PG8_WAIT_V(n) asm volatile("s_waitcnt vmcnt(" #n ")" ::: "memory")
; #define PG8_WAIT_L(n) asm volatile("s_waitcnt lgkmcnt(" #n ")" ::: "memory")
; #define PG8_BAR __builtin_amdgcn_s_barrier()
; #define PG8_SCHED __builtin_amdgcn_sched_barrier(0)
; template <class Epi, class Sched, bool ALIGN_EPI = false, bool SP2 = false>
; __device__ __forceinline__ void gemm_phase(PG8_LAS unsigned char* lds, const Gemm g, const Sched& S, const Epi& E) {
;     ...
;             PG8_LDB(B0, 0, 0); PG8_LDB(B1, 0, 1); PG8_SCHED; PG8_LDA(At, 0, 0); PG8_STAGE(PG8_SA(1, 1), a1 + hstep, voffA);
;             PG8_WAIT_V(8); PG8_WAIT_L(0); PG8_BAR; PG8_MMA(0, 0, At, B0); PG8_MMA(0, 1, At, B1); PG8_BAR; PG8_SCHED;
;     ...
;         for (int a = 0; a < 2; ++a)
; #pragma unroll
;             for (int b = 0; b < 2; ++b)
; #pragma unroll
;                 for (int m = 0; m < 4; ++m)
; #pragma unroll
;                     for (int n = 0; n < 2; ++n) acc[a][b][m][n] = (f32x4){0.f, 0.f, 0.f, 0.f};
;         cur = nxt; cA = nA; cB = nB; ++ui;
.LBB0_1051:
	s_add_u32 s54, s24, 0x100
	v_mov_b32_e32 v0, 0
	s_addc_u32 s55, s25, 0
	s_mov_b32 s56, -2
	v_mov_b32_e32 v1, v0
	v_mov_b32_e32 v2, v0
	v_mov_b32_e32 v3, v0
	v_mov_b32_e32 v4, v0
	v_mov_b32_e32 v5, v0
	v_mov_b32_e32 v6, v0
	v_mov_b32_e32 v7, v0
	v_mov_b32_e32 v16, v0
	v_mov_b32_e32 v17, v0
	v_mov_b32_e32 v18, v0
	v_mov_b32_e32 v19, v0
	v_mov_b32_e32 v20, v0
	v_mov_b32_e32 v21, v0
	v_mov_b32_e32 v22, v0
	v_mov_b32_e32 v23, v0
	v_mov_b32_e32 v32, v0
	v_mov_b32_e32 v33, v0
	v_mov_b32_e32 v34, v0
	v_mov_b32_e32 v35, v0
	v_mov_b32_e32 v36, v0
	v_mov_b32_e32 v37, v0
	v_mov_b32_e32 v38, v0
	v_mov_b32_e32 v39, v0
	v_mov_b32_e32 v48, v0
	v_mov_b32_e32 v49, v0
	v_mov_b32_e32 v50, v0
	v_mov_b32_e32 v51, v0
	v_mov_b32_e32 v52, v0
	v_mov_b32_e32 v53, v0
	v_mov_b32_e32 v54, v0
	v_mov_b32_e32 v55, v0
	v_mov_b32_e32 v8, v0
	v_mov_b32_e32 v9, v0
	v_mov_b32_e32 v10, v0
	v_mov_b32_e32 v11, v0
	v_mov_b32_e32 v12, v0
	v_mov_b32_e32 v13, v0
	v_mov_b32_e32 v14, v0
	v_mov_b32_e32 v15, v0
	v_mov_b32_e32 v24, v0
	v_mov_b32_e32 v25, v0
	v_mov_b32_e32 v26, v0
	v_mov_b32_e32 v27, v0
	v_mov_b32_e32 v28, v0
	v_mov_b32_e32 v29, v0
	v_mov_b32_e32 v30, v0
	v_mov_b32_e32 v31, v0
	v_mov_b32_e32 v40, v0
	v_mov_b32_e32 v41, v0
	v_mov_b32_e32 v42, v0
	v_mov_b32_e32 v43, v0
	v_mov_b32_e32 v44, v0
	v_mov_b32_e32 v45, v0
	v_mov_b32_e32 v46, v0
	v_mov_b32_e32 v47, v0
	v_mov_b32_e32 v56, v0
	v_mov_b32_e32 v57, v0
	v_mov_b32_e32 v58, v0
	v_mov_b32_e32 v59, v0
	v_mov_b32_e32 v60, v0
	v_mov_b32_e32 v61, v0
	v_mov_b32_e32 v62, v0
	v_mov_b32_e32 v63, v0
	v_mov_b32_e32 v64, v0
	v_mov_b32_e32 v65, v0
	v_mov_b32_e32 v66, v0
	v_mov_b32_e32 v67, v0
	v_mov_b32_e32 v68, v0
	v_mov_b32_e32 v69, v0
	v_mov_b32_e32 v70, v0
	v_mov_b32_e32 v71, v0
	v_mov_b32_e32 v80, v0
	v_mov_b32_e32 v81, v0
	v_mov_b32_e32 v82, v0
	v_mov_b32_e32 v83, v0
	v_mov_b32_e32 v84, v0
	v_mov_b32_e32 v85, v0
	v_mov_b32_e32 v86, v0
	v_mov_b32_e32 v87, v0
	v_mov_b32_e32 v96, v0
	v_mov_b32_e32 v97, v0
	v_mov_b32_e32 v98, v0
	v_mov_b32_e32 v99, v0
	v_mov_b32_e32 v100, v0
	v_mov_b32_e32 v101, v0
	v_mov_b32_e32 v102, v0
	v_mov_b32_e32 v103, v0
	v_mov_b32_e32 v104, v0
	v_mov_b32_e32 v105, v0
	v_mov_b32_e32 v106, v0
	v_mov_b32_e32 v107, v0
	v_mov_b32_e32 v108, v0
	v_mov_b32_e32 v109, v0
	v_mov_b32_e32 v110, v0
	v_mov_b32_e32 v111, v0
	v_mov_b32_e32 v72, v0
	v_mov_b32_e32 v73, v0
	v_mov_b32_e32 v74, v0
	v_mov_b32_e32 v75, v0
	v_mov_b32_e32 v76, v0
	v_mov_b32_e32 v77, v0
	v_mov_b32_e32 v78, v0
	v_mov_b32_e32 v79, v0
	v_mov_b32_e32 v88, v0
	v_mov_b32_e32 v89, v0
	v_mov_b32_e32 v90, v0
	v_mov_b32_e32 v91, v0
	v_mov_b32_e32 v92, v0
	v_mov_b32_e32 v93, v0
	v_mov_b32_e32 v94, v0
	v_mov_b32_e32 v95, v0
	v_mov_b32_e32 v112, v0
	v_mov_b32_e32 v113, v0
	v_mov_b32_e32 v114, v0
	v_mov_b32_e32 v115, v0
	v_mov_b32_e32 v116, v0
	v_mov_b32_e32 v117, v0
	v_mov_b32_e32 v118, v0
	v_mov_b32_e32 v119, v0
	v_mov_b32_e32 v120, v0
	v_mov_b32_e32 v121, v0
	v_mov_b32_e32 v122, v0
	v_mov_b32_e32 v123, v0
	v_mov_b32_e32 v124, v0
	v_mov_b32_e32 v125, v0
	v_mov_b32_e32 v126, v0
	v_mov_b32_e32 v127, v0
	v_readfirstlane_b32 s100, v188
	s_bitcmp1_b32 s100, 8
	s_cbranch_scc0 .Lmy_sprio_1052
	s_setprio 1
.Lmy_sprio_1052:
.LBB0_1052:
	ds_read_b128 v[146:149], v153
	ds_read_b128 v[156:159], v153 offset:1024
	ds_read_b128 v[160:163], v153 offset:2048
	ds_read_b128 v[164:167], v153 offset:3072
	ds_read_b128 v[168:171], v154
	ds_read_b128 v[172:175], v154 offset:1024
	ds_read_b128 v[176:179], v154 offset:2048
	ds_read_b128 v[180:183], v154 offset:3072
	s_add_u32 s24, s22, 0x100
	s_addc_u32 s25, s23, 0
	s_cmp_eq_u32 s56, 40
	s_cselect_b32 s29, s3, s25
	s_cselect_b32 s28, s2, s24
	s_cselect_b32 s27, s21, s55
	s_cselect_b32 s26, s20, s54
	s_add_i32 m0, s38, 0xc000
	ds_read_b128 v[184:187], v155
	ds_read_b128 v[188:191], v155 offset:1024
	ds_read_b128 v[192:195], v155 offset:2048
	ds_read_b128 v[196:199], v155 offset:3072
	ds_read_b128 v[200:203], v155 offset:4096
	ds_read_b128 v[204:207], v155 offset:5120
	ds_read_b128 v[208:211], v155 offset:6144
	ds_read_b128 v[212:215], v155 offset:7168
	global_load_lds_dwordx4 v138, s[22:23]
	s_add_i32 m0, s38, 0xe000
	s_nop 0
	global_load_lds_dwordx4 v140, s[22:23]
	s_waitcnt vmcnt(8)
	s_waitcnt lgkmcnt(0)
	s_barrier
	v_mfma_f32_16x16x32_bf16 v[124:127], v[146:149], v[184:187], v[124:127]
	v_mfma_f32_16x16x32_bf16 v[120:123], v[160:163], v[184:187], v[120:123]
	v_mfma_f32_16x16x32_bf16 v[116:119], v[146:149], v[192:195], v[116:119]
	v_mfma_f32_16x16x32_bf16 v[112:115], v[160:163], v[192:195], v[112:115]
	v_mfma_f32_16x16x32_bf16 v[92:95], v[146:149], v[200:203], v[92:95]
	v_mfma_f32_16x16x32_bf16 v[88:91], v[160:163], v[200:203], v[88:91]
	v_mfma_f32_16x16x32_bf16 v[76:79], v[146:149], v[208:211], v[76:79]
	v_mfma_f32_16x16x32_bf16 v[72:75], v[160:163], v[208:211], v[72:75]
	v_mfma_f32_16x16x32_bf16 v[124:127], v[156:159], v[188:191], v[124:127]
	v_mfma_f32_16x16x32_bf16 v[120:123], v[164:167], v[188:191], v[120:123]
	v_mfma_f32_16x16x32_bf16 v[116:119], v[156:159], v[196:199], v[116:119]
	v_mfma_f32_16x16x32_bf16 v[112:115], v[164:167], v[196:199], v[112:115]
	v_mfma_f32_16x16x32_bf16 v[92:95], v[156:159], v[204:207], v[92:95]
	v_mfma_f32_16x16x32_bf16 v[88:91], v[164:167], v[204:207], v[88:91]
	v_mfma_f32_16x16x32_bf16 v[76:79], v[156:159], v[212:215], v[76:79]
	v_mfma_f32_16x16x32_bf16 v[72:75], v[164:167], v[212:215], v[72:75]
	v_mfma_f32_16x16x32_bf16 v[108:111], v[168:171], v[184:187], v[108:111]
	v_mfma_f32_16x16x32_bf16 v[104:107], v[176:179], v[184:187], v[104:107]
	v_mfma_f32_16x16x32_bf16 v[100:103], v[168:171], v[192:195], v[100:103]
	v_mfma_f32_16x16x32_bf16 v[96:99], v[176:179], v[192:195], v[96:99]
	v_mfma_f32_16x16x32_bf16 v[84:87], v[168:171], v[200:203], v[84:87]
	v_mfma_f32_16x16x32_bf16 v[80:83], v[176:179], v[200:203], v[80:83]
	v_mfma_f32_16x16x32_bf16 v[68:71], v[168:171], v[208:211], v[68:71]
	v_mfma_f32_16x16x32_bf16 v[64:67], v[176:179], v[208:211], v[64:67]
	v_mfma_f32_16x16x32_bf16 v[108:111], v[172:175], v[188:191], v[108:111]
	v_mfma_f32_16x16x32_bf16 v[104:107], v[180:183], v[188:191], v[104:107]
	v_mfma_f32_16x16x32_bf16 v[100:103], v[172:175], v[196:199], v[100:103]
	v_mfma_f32_16x16x32_bf16 v[96:99], v[180:183], v[196:199], v[96:99]
	v_mfma_f32_16x16x32_bf16 v[84:87], v[172:175], v[204:207], v[84:87]
	v_mfma_f32_16x16x32_bf16 v[80:83], v[180:183], v[204:207], v[80:83]
	v_mfma_f32_16x16x32_bf16 v[68:71], v[172:175], v[212:215], v[68:71]
	v_mfma_f32_16x16x32_bf16 v[64:67], v[180:183], v[212:215], v[64:67]
	s_barrier
; #define PG8_STAGE(bufoff, gbase, voff) do { _Pragma("unroll") for (int _i = 0; _i < 2; ++_i) \
;         __builtin_amdgcn_global_load_lds((const unsigned*)((const char*)(gbase) + (voff)[_i]), (PG8_LAS unsigned*)(lds + (bufoff) + ldsw + _i * 8192), 16, 0, 0); } while (0)
; #define PG8_LDA(dst, b, h) do { _Pragma("unroll") for (int m = 0; m < 4; ++m) _Pragma("unroll") for (int k = 0; k < 2; ++k) dst[m][k] = *(const PG8_LAS bf16x8*)(lds + PG8_SA(b, h) + aoff + m * 2048 + k * 1024); } while (0)
; #define PG8_LDB(dst, b, h) do { _Pragma("unroll") for (int n = 0; n < 2; ++n) _Pragma("unroll") for (int k = 0; k < 2; ++k) dst[n][k] = *(const PG8_LAS bf16x8*)(lds + PG8_SB(b, h) + boff + n * 2048 + k * 1024); } while (0)
; #define PG8_MMA(ai, bj, At, Bt) do { __builtin_amdgcn_s_setprio(1); _Pragma("unroll") for (int m = 0; m < 4; ++m) _Pragma("unroll") for (int n = 0; n < 2; ++n) _Pragma("unroll") for (int k = 0; k < 2; ++k) \
;         acc[ai][bj][m][n] = __builtin_amdgcn_mfma_f32_16x16x32_bf16(Bt[n][k], At[m][k], acc[ai][bj][m][n], 0, 0, 0); __builtin_amdgcn_s_setprio(0); } while (0)
; #define PG8_WAIT_V(n) asm volatile("s_waitcnt vmcnt(" #n ")" ::: "memory")
; #define PG8_WAIT_L(n) asm volatile("s_waitcnt lgkmcnt(" #n ")" ::: "memory")
; #define PG8_BAR __builtin_amdgcn_s_barrier()
; #define PG8_SCHED __builtin_amdgcn_sched_barrier(0)
; template <class Epi, class Sched, bool ALIGN_EPI = false, bool SP2 = false>
; __device__ __forceinline__ void gemm_phase(PG8_LAS unsigned char* lds, const Gemm g, const Sched& S, const Epi& E) {
;     ...
;             PG8_LDA(At, 0, 1); PG8_STAGE(PG8_SB(0, 0), b2, voffB); PG8_STAGE(PG8_SB(0, 1), b2 + hstep, voffB); PG8_STAGE(PG8_SA(0, 0), a2, voffA);
;             PG8_WAIT_V(8); PG8_WAIT_L(0); PG8_BAR; PG8_MMA(1, 0, At, B0); PG8_MMA(1, 1, At, B1); PG8_BAR; PG8_SCHED;
;             PG8_LDB(B0, 1, 0); PG8_LDB(B1, 1, 1); PG8_SCHED; PG8_LDA(At, 1, 0); PG8_STAGE(PG8_SA(0, 1), a2 + hstep, voffA);
;             PG8_WAIT_V(8); PG8_WAIT_L(0); PG8_BAR; PG8_MMA(0, 0, At, B0); PG8_MMA(0, 1, At, B1); PG8_BAR; PG8_SCHED;
	s_add_i32 s22, s46, s37
	v_lshl_add_u64 v[150:151], s[26:27], 0, v[130:131]
	s_mov_b32 m0, s22
	ds_read_b128 v[184:187], v155 offset:16384
	ds_read_b128 v[188:191], v155 offset:17408
	ds_read_b128 v[192:195], v155 offset:18432
	ds_read_b128 v[196:199], v155 offset:19456
	ds_read_b128 v[200:203], v155 offset:20480
	ds_read_b128 v[204:207], v155 offset:21504
	ds_read_b128 v[208:211], v155 offset:22528
	ds_read_b128 v[212:215], v155 offset:23552
	global_load_lds_dwordx4 v[150:151], off
	s_add_i32 m0, s22, 0x2000
	s_add_u32 s22, s26, 0xb0000
	v_lshl_add_u64 v[216:217], s[26:27], 0, v[134:135]
	s_addc_u32 s23, s27, 0
	s_add_i32 s57, s47, s37
	global_load_lds_dwordx4 v[216:217], off
	s_mov_b32 m0, s57
	v_lshl_add_u64 v[220:221], s[28:29], 0, v[132:133]
	global_load_lds_dwordx4 v130, s[22:23]
	s_add_i32 m0, s57, 0x2000
	s_nop 0
	global_load_lds_dwordx4 v134, s[22:23]
	v_lshl_add_u64 v[218:219], s[28:29], 0, v[128:129]
	s_mov_b32 m0, s38
	s_nop 0
	global_load_lds_dwordx4 v[218:219], off
	s_mov_b32 m0, s39
	s_nop 0
	global_load_lds_dwordx4 v[220:221], off
	s_waitcnt vmcnt(8)
	s_waitcnt lgkmcnt(0)
	s_barrier
	v_mfma_f32_16x16x32_bf16 v[60:63], v[146:149], v[184:187], v[60:63]
	v_mfma_f32_16x16x32_bf16 v[56:59], v[160:163], v[184:187], v[56:59]
	v_mfma_f32_16x16x32_bf16 v[44:47], v[146:149], v[192:195], v[44:47]
	v_mfma_f32_16x16x32_bf16 v[40:43], v[160:163], v[192:195], v[40:43]
	v_mfma_f32_16x16x32_bf16 v[28:31], v[146:149], v[200:203], v[28:31]
	v_mfma_f32_16x16x32_bf16 v[24:27], v[160:163], v[200:203], v[24:27]
	v_mfma_f32_16x16x32_bf16 v[12:15], v[146:149], v[208:211], v[12:15]
	v_mfma_f32_16x16x32_bf16 v[8:11], v[160:163], v[208:211], v[8:11]
	v_mfma_f32_16x16x32_bf16 v[60:63], v[156:159], v[188:191], v[60:63]
	v_mfma_f32_16x16x32_bf16 v[56:59], v[164:167], v[188:191], v[56:59]
	v_mfma_f32_16x16x32_bf16 v[44:47], v[156:159], v[196:199], v[44:47]
	v_mfma_f32_16x16x32_bf16 v[40:43], v[164:167], v[196:199], v[40:43]
	v_mfma_f32_16x16x32_bf16 v[28:31], v[156:159], v[204:207], v[28:31]
	v_mfma_f32_16x16x32_bf16 v[24:27], v[164:167], v[204:207], v[24:27]
	v_mfma_f32_16x16x32_bf16 v[12:15], v[156:159], v[212:215], v[12:15]
	v_mfma_f32_16x16x32_bf16 v[8:11], v[164:167], v[212:215], v[8:11]
	v_mfma_f32_16x16x32_bf16 v[52:55], v[168:171], v[184:187], v[52:55]
	v_mfma_f32_16x16x32_bf16 v[48:51], v[176:179], v[184:187], v[48:51]
	v_mfma_f32_16x16x32_bf16 v[36:39], v[168:171], v[192:195], v[36:39]
	v_mfma_f32_16x16x32_bf16 v[32:35], v[176:179], v[192:195], v[32:35]
	v_mfma_f32_16x16x32_bf16 v[20:23], v[168:171], v[200:203], v[20:23]
	v_mfma_f32_16x16x32_bf16 v[16:19], v[176:179], v[200:203], v[16:19]
	v_mfma_f32_16x16x32_bf16 v[4:7], v[168:171], v[208:211], v[4:7]
	v_mfma_f32_16x16x32_bf16 v[0:3], v[176:179], v[208:211], v[0:3]
	v_mfma_f32_16x16x32_bf16 v[52:55], v[172:175], v[188:191], v[52:55]
	v_mfma_f32_16x16x32_bf16 v[48:51], v[180:183], v[188:191], v[48:51]
	v_mfma_f32_16x16x32_bf16 v[36:39], v[172:175], v[196:199], v[36:39]
	v_mfma_f32_16x16x32_bf16 v[32:35], v[180:183], v[196:199], v[32:35]
	v_mfma_f32_16x16x32_bf16 v[20:23], v[172:175], v[204:207], v[20:23]
	v_mfma_f32_16x16x32_bf16 v[16:19], v[180:183], v[204:207], v[16:19]
	v_mfma_f32_16x16x32_bf16 v[4:7], v[172:175], v[212:215], v[4:7]
	v_mfma_f32_16x16x32_bf16 v[0:3], v[180:183], v[212:215], v[0:3]
	s_barrier
	s_add_i32 s57, 0, 0x18000
	s_add_i32 s58, 0, 0x1c000
	v_add_u32_e32 v164, s57, v152
	v_add_u32_e32 v180, s58, v152
	ds_read_b128 v[146:149], v164
	ds_read_b128 v[156:159], v164 offset:1024
	ds_read_b128 v[160:163], v164 offset:2048
	ds_read_b128 v[164:167], v164 offset:3072
	ds_read_b128 v[168:171], v180
	ds_read_b128 v[172:175], v180 offset:1024
	ds_read_b128 v[176:179], v180 offset:2048
	ds_read_b128 v[180:183], v180 offset:3072
	s_add_u32 s22, s28, 0xb0000
	s_addc_u32 s23, s29, 0
	s_mov_b32 m0, s40
	ds_read_b128 v[184:187], v155 offset:32768
	ds_read_b128 v[188:191], v155 offset:33792
	ds_read_b128 v[192:195], v155 offset:34816
	ds_read_b128 v[196:199], v155 offset:35840
	ds_read_b128 v[200:203], v155 offset:36864
	ds_read_b128 v[204:207], v155 offset:37888
	ds_read_b128 v[208:211], v155 offset:38912
	ds_read_b128 v[212:215], v155 offset:39936
	global_load_lds_dwordx4 v128, s[22:23]
	s_mov_b32 m0, s41
	s_nop 0
	global_load_lds_dwordx4 v132, s[22:23]
	s_waitcnt vmcnt(8)
	s_waitcnt lgkmcnt(0)
	s_barrier
; #define PG8_STAGE(bufoff, gbase, voff) do { _Pragma("unroll") for (int _i = 0; _i < 2; ++_i) \
;         __builtin_amdgcn_global_load_lds((const unsigned*)((const char*)(gbase) + (voff)[_i]), (PG8_LAS unsigned*)(lds + (bufoff) + ldsw + _i * 8192), 16, 0, 0); } while (0)
; #define PG8_LDA(dst, b, h) do { _Pragma("unroll") for (int m = 0; m < 4; ++m) _Pragma("unroll") for (int k = 0; k < 2; ++k) dst[m][k] = *(const PG8_LAS bf16x8*)(lds + PG8_SA(b, h) + aoff + m * 2048 + k * 1024); } while (0)
; #define PG8_MMA(ai, bj, At, Bt) do { __builtin_amdgcn_s_setprio(1); _Pragma("unroll") for (int m = 0; m < 4; ++m) _Pragma("unroll") for (int n = 0; n < 2; ++n) _Pragma("unroll") for (int k = 0; k < 2; ++k) \
;         acc[ai][bj][m][n] = __builtin_amdgcn_mfma_f32_16x16x32_bf16(Bt[n][k], At[m][k], acc[ai][bj][m][n], 0, 0, 0); __builtin_amdgcn_s_setprio(0); } while (0)
; #define PG8_WAIT_V(n) asm volatile("s_waitcnt vmcnt(" #n ")" ::: "memory")
; #define PG8_WAIT_L(n) asm volatile("s_waitcnt lgkmcnt(" #n ")" ::: "memory")
; #define PG8_BAR __builtin_amdgcn_s_barrier()
; #define PG8_SCHED __builtin_amdgcn_sched_barrier(0)
; template <class Epi, class Sched, bool ALIGN_EPI = false, bool SP2 = false>
; __device__ __forceinline__ void gemm_phase(PG8_LAS unsigned char* lds, const Gemm g, const Sched& S, const Epi& E) {
;     ...
;             PG8_WAIT_V(8); PG8_WAIT_L(0); PG8_BAR; PG8_MMA(0, 0, At, B0); PG8_MMA(0, 1, At, B1); PG8_BAR; PG8_SCHED;
;             PG8_LDA(At, 1, 1); PG8_STAGE(PG8_SB(1, 0), b3, voffB); PG8_STAGE(PG8_SB(1, 1), b3 + hstep, voffB); PG8_STAGE(PG8_SA(1, 0), a3, voffA);
;             PG8_WAIT_V(8); PG8_WAIT_L(0); PG8_BAR; PG8_MMA(1, 0, At, B0); PG8_MMA(1, 1, At, B1); PG8_BAR; PG8_SCHED;
;     ...
;         if constexpr (ALIGN_EPI) { if (wr == 0) PG8_BAR; }
	v_mfma_f32_16x16x32_bf16 v[124:127], v[146:149], v[184:187], v[124:127]
	v_mfma_f32_16x16x32_bf16 v[120:123], v[160:163], v[184:187], v[120:123]
	v_mfma_f32_16x16x32_bf16 v[116:119], v[146:149], v[192:195], v[116:119]
	v_mfma_f32_16x16x32_bf16 v[112:115], v[160:163], v[192:195], v[112:115]
	v_mfma_f32_16x16x32_bf16 v[92:95], v[146:149], v[200:203], v[92:95]
	v_mfma_f32_16x16x32_bf16 v[88:91], v[160:163], v[200:203], v[88:91]
	v_mfma_f32_16x16x32_bf16 v[76:79], v[146:149], v[208:211], v[76:79]
	v_mfma_f32_16x16x32_bf16 v[72:75], v[160:163], v[208:211], v[72:75]
	v_mfma_f32_16x16x32_bf16 v[124:127], v[156:159], v[188:191], v[124:127]
	v_mfma_f32_16x16x32_bf16 v[120:123], v[164:167], v[188:191], v[120:123]
	v_mfma_f32_16x16x32_bf16 v[116:119], v[156:159], v[196:199], v[116:119]
	v_mfma_f32_16x16x32_bf16 v[112:115], v[164:167], v[196:199], v[112:115]
	v_mfma_f32_16x16x32_bf16 v[92:95], v[156:159], v[204:207], v[92:95]
	v_mfma_f32_16x16x32_bf16 v[88:91], v[164:167], v[204:207], v[88:91]
	v_mfma_f32_16x16x32_bf16 v[76:79], v[156:159], v[212:215], v[76:79]
	v_mfma_f32_16x16x32_bf16 v[72:75], v[164:167], v[212:215], v[72:75]
	v_mfma_f32_16x16x32_bf16 v[108:111], v[168:171], v[184:187], v[108:111]
	v_mfma_f32_16x16x32_bf16 v[104:107], v[176:179], v[184:187], v[104:107]
	v_mfma_f32_16x16x32_bf16 v[100:103], v[168:171], v[192:195], v[100:103]
	v_mfma_f32_16x16x32_bf16 v[96:99], v[176:179], v[192:195], v[96:99]
	v_mfma_f32_16x16x32_bf16 v[84:87], v[168:171], v[200:203], v[84:87]
	v_mfma_f32_16x16x32_bf16 v[80:83], v[176:179], v[200:203], v[80:83]
	v_mfma_f32_16x16x32_bf16 v[68:71], v[168:171], v[208:211], v[68:71]
	v_mfma_f32_16x16x32_bf16 v[64:67], v[176:179], v[208:211], v[64:67]
	v_mfma_f32_16x16x32_bf16 v[108:111], v[172:175], v[188:191], v[108:111]
	v_mfma_f32_16x16x32_bf16 v[104:107], v[180:183], v[188:191], v[104:107]
	v_mfma_f32_16x16x32_bf16 v[100:103], v[172:175], v[196:199], v[100:103]
	v_mfma_f32_16x16x32_bf16 v[96:99], v[180:183], v[196:199], v[96:99]
	v_mfma_f32_16x16x32_bf16 v[84:87], v[172:175], v[204:207], v[84:87]
	v_mfma_f32_16x16x32_bf16 v[80:83], v[180:183], v[204:207], v[80:83]
	v_mfma_f32_16x16x32_bf16 v[68:71], v[172:175], v[212:215], v[68:71]
	v_mfma_f32_16x16x32_bf16 v[64:67], v[180:183], v[212:215], v[64:67]
	s_barrier
	s_add_i32 s22, s57, s37
	v_lshl_add_u64 v[150:151], v[150:151], 0, s[8:9]
	s_mov_b32 m0, s22
	ds_read_b128 v[184:187], v155 offset:49152
	ds_read_b128 v[188:191], v155 offset:50176
	ds_read_b128 v[192:195], v155 offset:51200
	ds_read_b128 v[196:199], v155 offset:52224
	ds_read_b128 v[200:203], v155 offset:53248
	ds_read_b128 v[204:207], v155 offset:54272
	ds_read_b128 v[208:211], v155 offset:55296
	ds_read_b128 v[212:215], v155 offset:56320
	global_load_lds_dwordx4 v[150:151], off
	s_add_i32 m0, s22, 0x2000
	s_add_u32 s22, s26, 0xb0080
	v_lshl_add_u64 v[150:151], v[216:217], 0, s[8:9]
	s_addc_u32 s23, s27, 0
	s_add_i32 s26, s58, s37
	global_load_lds_dwordx4 v[150:151], off
	s_mov_b32 m0, s26
	s_nop 0
	global_load_lds_dwordx4 v130, s[22:23]
	s_add_i32 m0, s26, 0x2000
	s_nop 0
	global_load_lds_dwordx4 v134, s[22:23]
	v_lshl_add_u64 v[150:151], v[218:219], 0, s[8:9]
	s_mov_b32 m0, s43
	s_nop 0
	global_load_lds_dwordx4 v[150:151], off
	v_lshl_add_u64 v[150:151], v[220:221], 0, s[8:9]
	s_mov_b32 m0, s44
	s_nop 0
	global_load_lds_dwordx4 v[150:151], off
	s_waitcnt vmcnt(8)
	s_waitcnt lgkmcnt(0)
	s_barrier
	v_mfma_f32_16x16x32_bf16 v[60:63], v[146:149], v[184:187], v[60:63]
	v_mfma_f32_16x16x32_bf16 v[56:59], v[160:163], v[184:187], v[56:59]
	v_mfma_f32_16x16x32_bf16 v[44:47], v[146:149], v[192:195], v[44:47]
	v_mfma_f32_16x16x32_bf16 v[40:43], v[160:163], v[192:195], v[40:43]
	v_mfma_f32_16x16x32_bf16 v[28:31], v[146:149], v[200:203], v[28:31]
	v_mfma_f32_16x16x32_bf16 v[24:27], v[160:163], v[200:203], v[24:27]
	v_mfma_f32_16x16x32_bf16 v[12:15], v[146:149], v[208:211], v[12:15]
	v_mfma_f32_16x16x32_bf16 v[8:11], v[160:163], v[208:211], v[8:11]
	v_mfma_f32_16x16x32_bf16 v[60:63], v[156:159], v[188:191], v[60:63]
	v_mfma_f32_16x16x32_bf16 v[56:59], v[164:167], v[188:191], v[56:59]
	v_mfma_f32_16x16x32_bf16 v[44:47], v[156:159], v[196:199], v[44:47]
	v_mfma_f32_16x16x32_bf16 v[40:43], v[164:167], v[196:199], v[40:43]
	v_mfma_f32_16x16x32_bf16 v[28:31], v[156:159], v[204:207], v[28:31]
	v_mfma_f32_16x16x32_bf16 v[24:27], v[164:167], v[204:207], v[24:27]
	v_mfma_f32_16x16x32_bf16 v[12:15], v[156:159], v[212:215], v[12:15]
	v_mfma_f32_16x16x32_bf16 v[8:11], v[164:167], v[212:215], v[8:11]
	v_mfma_f32_16x16x32_bf16 v[52:55], v[168:171], v[184:187], v[52:55]
	v_mfma_f32_16x16x32_bf16 v[48:51], v[176:179], v[184:187], v[48:51]
	v_mfma_f32_16x16x32_bf16 v[36:39], v[168:171], v[192:195], v[36:39]
	v_mfma_f32_16x16x32_bf16 v[32:35], v[176:179], v[192:195], v[32:35]
	v_mfma_f32_16x16x32_bf16 v[20:23], v[168:171], v[200:203], v[20:23]
	v_mfma_f32_16x16x32_bf16 v[16:19], v[176:179], v[200:203], v[16:19]
	v_mfma_f32_16x16x32_bf16 v[4:7], v[168:171], v[208:211], v[4:7]
	v_mfma_f32_16x16x32_bf16 v[0:3], v[176:179], v[208:211], v[0:3]
	v_mfma_f32_16x16x32_bf16 v[52:55], v[172:175], v[188:191], v[52:55]
	v_mfma_f32_16x16x32_bf16 v[48:51], v[180:183], v[188:191], v[48:51]
	v_mfma_f32_16x16x32_bf16 v[36:39], v[172:175], v[196:199], v[36:39]
	v_mfma_f32_16x16x32_bf16 v[32:35], v[180:183], v[196:199], v[32:35]
	v_mfma_f32_16x16x32_bf16 v[20:23], v[172:175], v[204:207], v[20:23]
	v_mfma_f32_16x16x32_bf16 v[16:19], v[180:183], v[204:207], v[16:19]
	v_mfma_f32_16x16x32_bf16 v[4:7], v[172:175], v[212:215], v[4:7]
	v_mfma_f32_16x16x32_bf16 v[0:3], v[180:183], v[212:215], v[0:3]
	s_barrier
	s_add_i32 s56, s56, 2
	s_add_u32 s54, s54, 0x100
	s_addc_u32 s55, s55, 0
	s_cmp_gt_u32 s56, 41
	s_mov_b64 s[22:23], s[24:25]
	s_cbranch_scc0 .LBB0_1052
	s_setprio 0
	s_and_b64 vcc, exec, s[10:11]
	s_cbranch_vccz .LBB0_1055
	s_barrier
